# v66 + GEMM K-loops: post-barrier SALU runs moved up into the preceding MFMA cluster (issue in MFMA shadow)
# baseline (speedup 1.0000x reference)
; #define PG8_STAGE(bufoff, gbase, X) do { _Pragma("unroll") for (int _i = 0; _i < 2; ++_i) { \
;         const char* gp_ = (const char*)(gbase) + (_i ? rs##X : (size_t)0); const unsigned la_ = (unsigned)(size_t)(lds + (bufoff) + ldsw + _i * 8192); \
;         asm volatile("s_mov_b32 m0, %2\n\ts_nop 0\n\tglobal_load_lds_dwordx4 %0, %1" :: "v"(voff##X), "s"(gp_), "s"(la_) : "memory", "m0"); } } while (0)
; #define PG8_LDA(dst, b, h) do { _Pragma("unroll") for (int m = 0; m < 4; ++m) _Pragma("unroll") for (int k = 0; k < 2; ++k) dst[m][k] = *(const LAS bf16x8*)(lds + PG8_SA(b, h) + aoff + m * 2048 + k * 1024); } while (0)
; #define PG8_LDB(dst, b, h) do { _Pragma("unroll") for (int n = 0; n < 2; ++n) _Pragma("unroll") for (int k = 0; k < 2; ++k) dst[n][k] = *(const LAS bf16x8*)(lds + PG8_SB(b, h) + boff + n * 2048 + k * 1024); } while (0)
; #define PG8_WAIT_V(n) asm volatile("s_waitcnt vmcnt(" #n ")" ::: "memory")
; #define PG8_WAIT_L(n) asm volatile("s_waitcnt lgkmcnt(" #n ")" ::: "memory")
; #define PG8_BAR __builtin_amdgcn_s_barrier()
; #define PG8_SCHED __builtin_amdgcn_sched_barrier(0)
; template <class Epi>
; __device__ __forceinline__ void gemm_phase(LAS unsigned char* lds, const Gemm g_in, const StaticOrder& S, const Epi& E) {
;     ...
;             PG8_LDB(B0, 0, 0); PG8_LDB(B1, 0, 1); PG8_SCHED; PG8_LDA(At, 0, 0); PG8_STAGE(PG8_SA(1, 1), a1 + hsA, A);
;             PG8_WAIT_V(8); PG8_WAIT_L(0); PG8_BAR; PG8_MMA(0, 0, At, B0); PG8_MMA(0, 1, At, B1); PG8_BAR; PG8_SCHED;
;             PG8_LDA(At, 0, 1); PG8_STAGE(PG8_SB(0, 0), b2, B); PG8_STAGE(PG8_SB(0, 1), b2 + hsB, B); PG8_STAGE(PG8_SA(0, 0), a2, A);
;             PG8_WAIT_V(8); PG8_WAIT_L(0); PG8_BAR; PG8_MMA(1, 0, At, B0); PG8_MMA(1, 1, At, B1); PG8_BAR; PG8_SCHED;
.LBB0_156:
	v_add_u32_e32 v139, 0x10000, v137
	ds_read_b128 v[140:143], v139
	ds_read_b128 v[144:147], v139 offset:1024
	ds_read_b128 v[148:151], v139 offset:2048
	ds_read_b128 v[152:155], v139 offset:3072
	v_add_u32_e32 v139, 0x14000, v137
	ds_read_b128 v[156:159], v139
	ds_read_b128 v[172:175], v139 offset:1024
	ds_read_b128 v[182:185], v139 offset:2048
	ds_read_b128 v[186:189], v139 offset:3072
	s_add_i32 s63, s8, 2
	s_add_u32 s26, s4, 0xfff40080
	s_addc_u32 s9, s5, -1
	s_cmp_eq_u32 s55, s8
	s_cselect_b32 s8, s21, s26
	s_cselect_b32 s9, s19, s9
	s_cselect_b32 s28, s60, s61
	s_cselect_b32 s29, s59, s62
	s_add_u32 s26, s8, 0x80
	s_addc_u32 s27, s9, 0
	ds_read_b128 v[190:193], v138
	ds_read_b128 v[194:197], v138 offset:1024
	ds_read_b128 v[198:201], v138 offset:2048
	ds_read_b128 v[202:205], v138 offset:3072
	ds_read_b128 v[206:209], v138 offset:4096
	ds_read_b128 v[210:213], v138 offset:5120
	ds_read_b128 v[214:217], v138 offset:6144
	ds_read_b128 v[218:221], v138 offset:7168
	s_add_u32 s64, s4, 0xfffc0000
	s_addc_u32 s65, s5, -1
	s_mov_b32 m0, s56
	s_nop 0
	global_load_lds_dwordx4 v1, s[64:65]
	s_nop 0
	s_mov_b32 m0, s57
	s_nop 0
	global_load_lds_dwordx4 v1, s[4:5]
	s_waitcnt vmcnt(8)
	s_waitcnt lgkmcnt(0)
	s_barrier
	s_setprio 1
	s_waitcnt lgkmcnt(7)
	v_mfma_i32_16x16x64_i8 v[126:129], v[140:143], v[190:193], v[126:129]
	v_mfma_i32_16x16x64_i8 v[118:121], v[148:151], v[190:193], v[118:121]
	s_waitcnt lgkmcnt(5)
	v_mfma_i32_16x16x64_i8 v[110:113], v[140:143], v[198:201], v[110:113]
	v_mfma_i32_16x16x64_i8 v[102:105], v[148:151], v[198:201], v[102:105]
	s_waitcnt lgkmcnt(3)
	v_mfma_i32_16x16x64_i8 v[94:97], v[140:143], v[206:209], v[94:97]
	v_mfma_i32_16x16x64_i8 v[86:89], v[148:151], v[206:209], v[86:89]
	s_waitcnt lgkmcnt(1)
	v_mfma_i32_16x16x64_i8 v[78:81], v[140:143], v[214:217], v[78:81]
	v_mfma_i32_16x16x64_i8 v[70:73], v[148:151], v[214:217], v[70:73]
	v_mfma_i32_16x16x64_i8 v[126:129], v[144:147], v[194:197], v[126:129]
	v_mfma_i32_16x16x64_i8 v[118:121], v[152:155], v[194:197], v[118:121]
	v_mfma_i32_16x16x64_i8 v[110:113], v[144:147], v[202:205], v[110:113]
	v_mfma_i32_16x16x64_i8 v[102:105], v[152:155], v[202:205], v[102:105]
	v_mfma_i32_16x16x64_i8 v[94:97], v[144:147], v[210:213], v[94:97]
	v_mfma_i32_16x16x64_i8 v[86:89], v[152:155], v[210:213], v[86:89]
	s_waitcnt lgkmcnt(0)
	v_mfma_i32_16x16x64_i8 v[78:81], v[144:147], v[218:221], v[78:81]
	v_mfma_i32_16x16x64_i8 v[70:73], v[152:155], v[218:221], v[70:73]
	s_setprio 0
	s_setprio 1
	v_mfma_i32_16x16x64_i8 v[122:125], v[156:159], v[190:193], v[122:125]
	v_mfma_i32_16x16x64_i8 v[114:117], v[182:185], v[190:193], v[114:117]
	v_mfma_i32_16x16x64_i8 v[106:109], v[156:159], v[198:201], v[106:109]
	v_mfma_i32_16x16x64_i8 v[98:101], v[182:185], v[198:201], v[98:101]
	v_mfma_i32_16x16x64_i8 v[90:93], v[156:159], v[206:209], v[90:93]
	v_mfma_i32_16x16x64_i8 v[82:85], v[182:185], v[206:209], v[82:85]
	v_mfma_i32_16x16x64_i8 v[74:77], v[156:159], v[214:217], v[74:77]
	v_mfma_i32_16x16x64_i8 v[66:69], v[182:185], v[214:217], v[66:69]
	v_mfma_i32_16x16x64_i8 v[122:125], v[172:175], v[194:197], v[122:125]
	v_mfma_i32_16x16x64_i8 v[114:117], v[186:189], v[194:197], v[114:117]
	v_mfma_i32_16x16x64_i8 v[106:109], v[172:175], v[202:205], v[106:109]
	v_mfma_i32_16x16x64_i8 v[98:101], v[186:189], v[202:205], v[98:101]
	s_add_u32 s64, s28, 0x40000
	v_mfma_i32_16x16x64_i8 v[90:93], v[172:175], v[210:213], v[90:93]
	v_mfma_i32_16x16x64_i8 v[82:85], v[186:189], v[210:213], v[82:85]
	v_mfma_i32_16x16x64_i8 v[74:77], v[172:175], v[218:221], v[74:77]
	v_mfma_i32_16x16x64_i8 v[66:69], v[186:189], v[218:221], v[66:69]
	s_setprio 0
	s_barrier
	ds_read_b128 v[190:193], v138 offset:16384
	ds_read_b128 v[194:197], v138 offset:17408
	ds_read_b128 v[198:201], v138 offset:18432
	ds_read_b128 v[202:205], v138 offset:19456
	ds_read_b128 v[206:209], v138 offset:20480
	ds_read_b128 v[210:213], v138 offset:21504
	ds_read_b128 v[214:217], v138 offset:22528
	ds_read_b128 v[218:221], v138 offset:23552
	s_mov_b32 m0, s38
	s_nop 0
	global_load_lds_dwordx4 v134, s[28:29]
	s_addc_u32 s65, s29, 0
	s_mov_b32 m0, s39
	s_nop 0
	global_load_lds_dwordx4 v134, s[64:65]
	s_add_u32 s64, s28, 0x80000
	s_addc_u32 s65, s29, 0
	s_mov_b32 m0, s40
	s_nop 0
	global_load_lds_dwordx4 v134, s[64:65]
	s_add_u32 s64, s28, 0xc0000
	s_addc_u32 s65, s29, 0
	s_mov_b32 m0, s41
	s_nop 0
	global_load_lds_dwordx4 v134, s[64:65]
	s_add_u32 s64, s8, 0x40000
	s_mov_b32 m0, s37
	s_nop 0
	global_load_lds_dwordx4 v1, s[8:9]
	s_addc_u32 s65, s9, 0
	s_mov_b32 m0, s42
	s_nop 0
	global_load_lds_dwordx4 v1, s[64:65]
	s_waitcnt vmcnt(8)
	s_waitcnt lgkmcnt(0)
	s_barrier
; #define PG8_STAGE(bufoff, gbase, X) do { _Pragma("unroll") for (int _i = 0; _i < 2; ++_i) { \
;         const char* gp_ = (const char*)(gbase) + (_i ? rs##X : (size_t)0); const unsigned la_ = (unsigned)(size_t)(lds + (bufoff) + ldsw + _i * 8192); \
;         asm volatile("s_mov_b32 m0, %2\n\ts_nop 0\n\tglobal_load_lds_dwordx4 %0, %1" :: "v"(voff##X), "s"(gp_), "s"(la_) : "memory", "m0"); } } while (0)
; #define PG8_LDA(dst, b, h) do { _Pragma("unroll") for (int m = 0; m < 4; ++m) _Pragma("unroll") for (int k = 0; k < 2; ++k) dst[m][k] = *(const LAS bf16x8*)(lds + PG8_SA(b, h) + aoff + m * 2048 + k * 1024); } while (0)
; #define PG8_LDB(dst, b, h) do { _Pragma("unroll") for (int n = 0; n < 2; ++n) _Pragma("unroll") for (int k = 0; k < 2; ++k) dst[n][k] = *(const LAS bf16x8*)(lds + PG8_SB(b, h) + boff + n * 2048 + k * 1024); } while (0)
; #define PG8_WAIT_V(n) asm volatile("s_waitcnt vmcnt(" #n ")" ::: "memory")
; #define PG8_WAIT_L(n) asm volatile("s_waitcnt lgkmcnt(" #n ")" ::: "memory")
; #define PG8_BAR __builtin_amdgcn_s_barrier()
; #define PG8_SCHED __builtin_amdgcn_sched_barrier(0)
; template <class Epi>
; __device__ __forceinline__ void gemm_phase(LAS unsigned char* lds, const Gemm g_in, const StaticOrder& S, const Epi& E) {
;     ...
;             PG8_WAIT_V(8); PG8_WAIT_L(0); PG8_BAR; PG8_MMA(1, 0, At, B0); PG8_MMA(1, 1, At, B1); PG8_BAR; PG8_SCHED;
;             PG8_LDB(B0, 1, 0); PG8_LDB(B1, 1, 1); PG8_SCHED; PG8_LDA(At, 1, 0); PG8_STAGE(PG8_SA(0, 1), a2 + hsA, A);
;             PG8_WAIT_V(8); PG8_WAIT_L(0); PG8_BAR; PG8_MMA(0, 0, At, B0); PG8_MMA(0, 1, At, B1); PG8_BAR; PG8_SCHED;
	s_setprio 1
	s_waitcnt lgkmcnt(7)
	v_mfma_i32_16x16x64_i8 v[62:65], v[140:143], v[190:193], v[62:65]
	v_mfma_i32_16x16x64_i8 v[54:57], v[148:151], v[190:193], v[54:57]
	s_waitcnt lgkmcnt(5)
	v_mfma_i32_16x16x64_i8 v[46:49], v[140:143], v[198:201], v[46:49]
	v_mfma_i32_16x16x64_i8 v[38:41], v[148:151], v[198:201], v[38:41]
	s_waitcnt lgkmcnt(3)
	v_mfma_i32_16x16x64_i8 v[30:33], v[140:143], v[206:209], v[30:33]
	v_mfma_i32_16x16x64_i8 v[22:25], v[148:151], v[206:209], v[22:25]
	s_waitcnt lgkmcnt(1)
	v_mfma_i32_16x16x64_i8 v[14:17], v[140:143], v[214:217], v[14:17]
	v_mfma_i32_16x16x64_i8 v[6:9], v[148:151], v[214:217], v[6:9]
	v_mfma_i32_16x16x64_i8 v[62:65], v[144:147], v[194:197], v[62:65]
	v_mfma_i32_16x16x64_i8 v[54:57], v[152:155], v[194:197], v[54:57]
	v_mfma_i32_16x16x64_i8 v[46:49], v[144:147], v[202:205], v[46:49]
	v_mfma_i32_16x16x64_i8 v[38:41], v[152:155], v[202:205], v[38:41]
	v_mfma_i32_16x16x64_i8 v[30:33], v[144:147], v[210:213], v[30:33]
	v_mfma_i32_16x16x64_i8 v[22:25], v[152:155], v[210:213], v[22:25]
	s_waitcnt lgkmcnt(0)
	v_mfma_i32_16x16x64_i8 v[14:17], v[144:147], v[218:221], v[14:17]
	v_mfma_i32_16x16x64_i8 v[6:9], v[152:155], v[218:221], v[6:9]
	s_setprio 0
	s_setprio 1
	v_mfma_i32_16x16x64_i8 v[58:61], v[156:159], v[190:193], v[58:61]
	v_mfma_i32_16x16x64_i8 v[50:53], v[182:185], v[190:193], v[50:53]
	v_mfma_i32_16x16x64_i8 v[42:45], v[156:159], v[198:201], v[42:45]
	v_mfma_i32_16x16x64_i8 v[34:37], v[182:185], v[198:201], v[34:37]
	v_mfma_i32_16x16x64_i8 v[26:29], v[156:159], v[206:209], v[26:29]
	v_mfma_i32_16x16x64_i8 v[18:21], v[182:185], v[206:209], v[18:21]
	v_mfma_i32_16x16x64_i8 v[10:13], v[156:159], v[214:217], v[10:13]
	v_mfma_i32_16x16x64_i8 v[2:5], v[182:185], v[214:217], v[2:5]
	v_mfma_i32_16x16x64_i8 v[58:61], v[172:175], v[194:197], v[58:61]
	v_mfma_i32_16x16x64_i8 v[50:53], v[186:189], v[194:197], v[50:53]
	v_mfma_i32_16x16x64_i8 v[42:45], v[172:175], v[202:205], v[42:45]
	v_mfma_i32_16x16x64_i8 v[34:37], v[186:189], v[202:205], v[34:37]
	v_mfma_i32_16x16x64_i8 v[26:29], v[172:175], v[210:213], v[26:29]
	v_mfma_i32_16x16x64_i8 v[18:21], v[186:189], v[210:213], v[18:21]
	v_mfma_i32_16x16x64_i8 v[10:13], v[172:175], v[218:221], v[10:13]
	v_mfma_i32_16x16x64_i8 v[2:5], v[186:189], v[218:221], v[2:5]
	s_setprio 0
	s_barrier
	v_add_u32_e32 v139, 0x18000, v137
	ds_read_b128 v[140:143], v139
	ds_read_b128 v[144:147], v139 offset:1024
	ds_read_b128 v[148:151], v139 offset:2048
	ds_read_b128 v[152:155], v139 offset:3072
	v_add_u32_e32 v139, 0x1c000, v137
	ds_read_b128 v[156:159], v139
	ds_read_b128 v[172:175], v139 offset:1024
	ds_read_b128 v[182:185], v139 offset:2048
	ds_read_b128 v[186:189], v139 offset:3072
	ds_read_b128 v[190:193], v138 offset:32768
	ds_read_b128 v[194:197], v138 offset:33792
	ds_read_b128 v[198:201], v138 offset:34816
	ds_read_b128 v[202:205], v138 offset:35840
	ds_read_b128 v[206:209], v138 offset:36864
	ds_read_b128 v[210:213], v138 offset:37888
	ds_read_b128 v[214:217], v138 offset:38912
	ds_read_b128 v[218:221], v138 offset:39936
	s_add_u32 s64, s8, 0x80000
	s_addc_u32 s65, s9, 0
	s_mov_b32 m0, s43
	s_nop 0
	global_load_lds_dwordx4 v1, s[64:65]
	s_add_u32 s64, s8, 0xc0000
	s_addc_u32 s65, s9, 0
	s_mov_b32 m0, s44
	s_nop 0
	global_load_lds_dwordx4 v1, s[64:65]
	s_waitcnt vmcnt(8)
	s_waitcnt lgkmcnt(0)
	s_barrier
	s_setprio 1
	s_waitcnt lgkmcnt(7)
	v_mfma_i32_16x16x64_i8 v[126:129], v[140:143], v[190:193], v[126:129]
	v_mfma_i32_16x16x64_i8 v[118:121], v[148:151], v[190:193], v[118:121]
	s_waitcnt lgkmcnt(5)
	v_mfma_i32_16x16x64_i8 v[110:113], v[140:143], v[198:201], v[110:113]
	v_mfma_i32_16x16x64_i8 v[102:105], v[148:151], v[198:201], v[102:105]
	s_waitcnt lgkmcnt(3)
	v_mfma_i32_16x16x64_i8 v[94:97], v[140:143], v[206:209], v[94:97]
	v_mfma_i32_16x16x64_i8 v[86:89], v[148:151], v[206:209], v[86:89]
	s_waitcnt lgkmcnt(1)
	v_mfma_i32_16x16x64_i8 v[78:81], v[140:143], v[214:217], v[78:81]
	v_mfma_i32_16x16x64_i8 v[70:73], v[148:151], v[214:217], v[70:73]
	v_mfma_i32_16x16x64_i8 v[126:129], v[144:147], v[194:197], v[126:129]
	v_mfma_i32_16x16x64_i8 v[118:121], v[152:155], v[194:197], v[118:121]
	v_mfma_i32_16x16x64_i8 v[110:113], v[144:147], v[202:205], v[110:113]
	v_mfma_i32_16x16x64_i8 v[102:105], v[152:155], v[202:205], v[102:105]
	v_mfma_i32_16x16x64_i8 v[94:97], v[144:147], v[210:213], v[94:97]
	v_mfma_i32_16x16x64_i8 v[86:89], v[152:155], v[210:213], v[86:89]
	s_waitcnt lgkmcnt(0)
	v_mfma_i32_16x16x64_i8 v[78:81], v[144:147], v[218:221], v[78:81]
	v_mfma_i32_16x16x64_i8 v[70:73], v[152:155], v[218:221], v[70:73]
	s_setprio 0
	s_setprio 1
	v_mfma_i32_16x16x64_i8 v[122:125], v[156:159], v[190:193], v[122:125]
	v_mfma_i32_16x16x64_i8 v[114:117], v[182:185], v[190:193], v[114:117]
	v_mfma_i32_16x16x64_i8 v[106:109], v[156:159], v[198:201], v[106:109]
	v_mfma_i32_16x16x64_i8 v[98:101], v[182:185], v[198:201], v[98:101]
	v_mfma_i32_16x16x64_i8 v[90:93], v[156:159], v[206:209], v[90:93]
	v_mfma_i32_16x16x64_i8 v[82:85], v[182:185], v[206:209], v[82:85]
	v_mfma_i32_16x16x64_i8 v[74:77], v[156:159], v[214:217], v[74:77]
	v_mfma_i32_16x16x64_i8 v[66:69], v[182:185], v[214:217], v[66:69]
	v_mfma_i32_16x16x64_i8 v[122:125], v[172:175], v[194:197], v[122:125]
	v_mfma_i32_16x16x64_i8 v[114:117], v[186:189], v[194:197], v[114:117]
	v_mfma_i32_16x16x64_i8 v[106:109], v[172:175], v[202:205], v[106:109]
	v_mfma_i32_16x16x64_i8 v[98:101], v[186:189], v[202:205], v[98:101]
	s_add_u32 s64, s28, 0x80
	s_addc_u32 s65, s29, 0
	v_mfma_i32_16x16x64_i8 v[90:93], v[172:175], v[210:213], v[90:93]
	v_mfma_i32_16x16x64_i8 v[82:85], v[186:189], v[210:213], v[82:85]
	v_mfma_i32_16x16x64_i8 v[74:77], v[172:175], v[218:221], v[74:77]
	v_mfma_i32_16x16x64_i8 v[66:69], v[186:189], v[218:221], v[66:69]
	s_setprio 0
	s_barrier
; #define PG8_STAGE(bufoff, gbase, X) do { _Pragma("unroll") for (int _i = 0; _i < 2; ++_i) { \
;         const char* gp_ = (const char*)(gbase) + (_i ? rs##X : (size_t)0); const unsigned la_ = (unsigned)(size_t)(lds + (bufoff) + ldsw + _i * 8192); \
;         asm volatile("s_mov_b32 m0, %2\n\ts_nop 0\n\tglobal_load_lds_dwordx4 %0, %1" :: "v"(voff##X), "s"(gp_), "s"(la_) : "memory", "m0"); } } while (0)
; #define PG8_LDA(dst, b, h) do { _Pragma("unroll") for (int m = 0; m < 4; ++m) _Pragma("unroll") for (int k = 0; k < 2; ++k) dst[m][k] = *(const LAS bf16x8*)(lds + PG8_SA(b, h) + aoff + m * 2048 + k * 1024); } while (0)
; #define PG8_WAIT_V(n) asm volatile("s_waitcnt vmcnt(" #n ")" ::: "memory")
; #define PG8_WAIT_L(n) asm volatile("s_waitcnt lgkmcnt(" #n ")" ::: "memory")
; #define PG8_BAR __builtin_amdgcn_s_barrier()
; #define PG8_SCHED __builtin_amdgcn_sched_barrier(0)
; template <class Epi>
; __device__ __forceinline__ void gemm_phase(LAS unsigned char* lds, const Gemm g_in, const StaticOrder& S, const Epi& E) {
;     ...
;             PG8_LDA(At, 1, 1); PG8_STAGE(PG8_SB(1, 0), b3, B); PG8_STAGE(PG8_SB(1, 1), b3 + hsB, B); PG8_STAGE(PG8_SA(1, 0), a3, A);
;             PG8_WAIT_V(8); PG8_WAIT_L(0); PG8_BAR; PG8_MMA(1, 0, At, B0); PG8_MMA(1, 1, At, B1); PG8_BAR; PG8_SCHED;
;         }
	ds_read_b128 v[190:193], v138 offset:49152
	ds_read_b128 v[194:197], v138 offset:50176
	ds_read_b128 v[198:201], v138 offset:51200
	ds_read_b128 v[202:205], v138 offset:52224
	ds_read_b128 v[206:209], v138 offset:53248
	ds_read_b128 v[210:213], v138 offset:54272
	ds_read_b128 v[214:217], v138 offset:55296
	ds_read_b128 v[218:221], v138 offset:56320
	s_mov_b32 m0, s47
	s_nop 0
	global_load_lds_dwordx4 v134, s[64:65]
	s_add_u32 s64, s28, 0x40080
	s_addc_u32 s65, s29, 0
	s_mov_b32 m0, s50
	s_nop 0
	global_load_lds_dwordx4 v134, s[64:65]
	s_add_u32 s64, s28, 0x80080
	s_addc_u32 s65, s29, 0
	s_mov_b32 m0, s53
	s_nop 0
	global_load_lds_dwordx4 v134, s[64:65]
	s_add_u32 s28, s28, 0xc0080
	s_addc_u32 s29, s29, 0
	s_mov_b32 m0, s54
	s_nop 0
	global_load_lds_dwordx4 v134, s[28:29]
	s_add_u32 s8, s8, 0x40080
	s_mov_b32 m0, s51
	s_nop 0
	global_load_lds_dwordx4 v1, s[26:27]
	s_addc_u32 s9, s9, 0
	s_mov_b32 m0, s52
	s_nop 0
	global_load_lds_dwordx4 v1, s[8:9]
	s_waitcnt vmcnt(8)
	s_waitcnt lgkmcnt(0)
	s_barrier
	s_setprio 1
	s_waitcnt lgkmcnt(7)
	v_mfma_i32_16x16x64_i8 v[62:65], v[140:143], v[190:193], v[62:65]
	v_mfma_i32_16x16x64_i8 v[54:57], v[148:151], v[190:193], v[54:57]
	s_waitcnt lgkmcnt(5)
	v_mfma_i32_16x16x64_i8 v[46:49], v[140:143], v[198:201], v[46:49]
	v_mfma_i32_16x16x64_i8 v[38:41], v[148:151], v[198:201], v[38:41]
	s_waitcnt lgkmcnt(3)
	v_mfma_i32_16x16x64_i8 v[30:33], v[140:143], v[206:209], v[30:33]
	v_mfma_i32_16x16x64_i8 v[22:25], v[148:151], v[206:209], v[22:25]
	s_waitcnt lgkmcnt(1)
	v_mfma_i32_16x16x64_i8 v[14:17], v[140:143], v[214:217], v[14:17]
	v_mfma_i32_16x16x64_i8 v[6:9], v[148:151], v[214:217], v[6:9]
	v_mfma_i32_16x16x64_i8 v[62:65], v[144:147], v[194:197], v[62:65]
	v_mfma_i32_16x16x64_i8 v[54:57], v[152:155], v[194:197], v[54:57]
	v_mfma_i32_16x16x64_i8 v[46:49], v[144:147], v[202:205], v[46:49]
	v_mfma_i32_16x16x64_i8 v[38:41], v[152:155], v[202:205], v[38:41]
	v_mfma_i32_16x16x64_i8 v[30:33], v[144:147], v[210:213], v[30:33]
	v_mfma_i32_16x16x64_i8 v[22:25], v[152:155], v[210:213], v[22:25]
	s_waitcnt lgkmcnt(0)
	v_mfma_i32_16x16x64_i8 v[14:17], v[144:147], v[218:221], v[14:17]
	v_mfma_i32_16x16x64_i8 v[6:9], v[152:155], v[218:221], v[6:9]
	s_setprio 0
	s_setprio 1
	v_mfma_i32_16x16x64_i8 v[58:61], v[156:159], v[190:193], v[58:61]
	v_mfma_i32_16x16x64_i8 v[50:53], v[182:185], v[190:193], v[50:53]
	v_mfma_i32_16x16x64_i8 v[42:45], v[156:159], v[198:201], v[42:45]
	v_mfma_i32_16x16x64_i8 v[34:37], v[182:185], v[198:201], v[34:37]
	v_mfma_i32_16x16x64_i8 v[26:29], v[156:159], v[206:209], v[26:29]
	v_mfma_i32_16x16x64_i8 v[18:21], v[182:185], v[206:209], v[18:21]
	v_mfma_i32_16x16x64_i8 v[10:13], v[156:159], v[214:217], v[10:13]
	v_mfma_i32_16x16x64_i8 v[2:5], v[182:185], v[214:217], v[2:5]
	v_mfma_i32_16x16x64_i8 v[58:61], v[172:175], v[194:197], v[58:61]
	v_mfma_i32_16x16x64_i8 v[50:53], v[186:189], v[194:197], v[50:53]
	v_mfma_i32_16x16x64_i8 v[42:45], v[172:175], v[202:205], v[42:45]
	v_mfma_i32_16x16x64_i8 v[34:37], v[186:189], v[202:205], v[34:37]
	s_add_u32 s61, s61, 0x100
	s_addc_u32 s62, s62, 0
	s_add_u32 s4, s4, 0x100
	s_addc_u32 s5, s5, 0
	s_cmp_ge_i32 s63, s34
	s_mov_b32 s8, s63
	v_mfma_i32_16x16x64_i8 v[26:29], v[172:175], v[210:213], v[26:29]
	v_mfma_i32_16x16x64_i8 v[18:21], v[186:189], v[210:213], v[18:21]
	v_mfma_i32_16x16x64_i8 v[10:13], v[172:175], v[218:221], v[10:13]
	v_mfma_i32_16x16x64_i8 v[2:5], v[186:189], v[218:221], v[2:5]
	s_setprio 0
	s_barrier
	s_cbranch_scc0 .LBB0_156
	s_and_b64 vcc, exec, s[14:15]
	s_cbranch_vccz .LBB0_159

; #define PG8_STAGE(bufoff, gbase, X) do { _Pragma("unroll") for (int _i = 0; _i < 2; ++_i) { \
;         const char* gp_ = (const char*)(gbase) + (_i ? rs##X : (size_t)0); const unsigned la_ = (unsigned)(size_t)(lds + (bufoff) + ldsw + _i * 8192); \
;         asm volatile("s_mov_b32 m0, %2\n\ts_nop 0\n\tglobal_load_lds_dwordx4 %0, %1" :: "v"(voff##X), "s"(gp_), "s"(la_) : "memory", "m0"); } } while (0)
; #define PG8_LDA(dst, b, h) do { _Pragma("unroll") for (int m = 0; m < 4; ++m) _Pragma("unroll") for (int k = 0; k < 2; ++k) dst[m][k] = *(const LAS bf16x8*)(lds + PG8_SA(b, h) + aoff + m * 2048 + k * 1024); } while (0)
; #define PG8_LDB(dst, b, h) do { _Pragma("unroll") for (int n = 0; n < 2; ++n) _Pragma("unroll") for (int k = 0; k < 2; ++k) dst[n][k] = *(const LAS bf16x8*)(lds + PG8_SB(b, h) + boff + n * 2048 + k * 1024); } while (0)
; #define PG8_WAIT_V(n) asm volatile("s_waitcnt vmcnt(" #n ")" ::: "memory")
; #define PG8_WAIT_L(n) asm volatile("s_waitcnt lgkmcnt(" #n ")" ::: "memory")
; #define PG8_BAR __builtin_amdgcn_s_barrier()
; #define PG8_SCHED __builtin_amdgcn_sched_barrier(0)
; template <class Epi>
; __device__ __forceinline__ void gemm_phase(LAS unsigned char* lds, const Gemm g_in, const StaticOrder& S, const Epi& E) {
;     ...
;         for (int t = 0; t < nt; t += 2) {
;             const bool last = (t == nt - 2);
;             const char* a1 = cA + (size_t)(t + 1) * kstep;
;             const char* a2 = last ? nA : cA + (size_t)(t + 2) * kstep; const char* b2 = last ? nB : cB + (size_t)(t + 2) * kstep;
;             const char* a3 = a2 + kstep; const char* b3 = b2 + kstep;
;             PG8_LDB(B0, 0, 0); PG8_LDB(B1, 0, 1); PG8_SCHED; PG8_LDA(At, 0, 0); PG8_STAGE(PG8_SA(1, 1), a1 + hsA, A);
;             PG8_WAIT_V(8); PG8_WAIT_L(0); PG8_BAR; PG8_MMA(0, 0, At, B0); PG8_MMA(0, 1, At, B1); PG8_BAR; PG8_SCHED;
;             PG8_LDA(At, 0, 1); PG8_STAGE(PG8_SB(0, 0), b2, B); PG8_STAGE(PG8_SB(0, 1), b2 + hsB, B); PG8_STAGE(PG8_SA(0, 0), a2, A);
;             PG8_WAIT_V(8); PG8_WAIT_L(0); PG8_BAR; PG8_MMA(1, 0, At, B0); PG8_MMA(1, 1, At, B1); PG8_BAR; PG8_SCHED;
.LBB0_388:
	ds_read_b128 v[142:145], v137
	ds_read_b128 v[146:149], v137 offset:1024
	ds_read_b128 v[150:153], v137 offset:2048
	ds_read_b128 v[154:157], v137 offset:3072
	ds_read_b128 v[158:161], v138
	ds_read_b128 v[170:173], v138 offset:1024
	ds_read_b128 v[174:177], v138 offset:2048
	ds_read_b128 v[184:187], v138 offset:3072
	s_add_i32 s62, s22, 2
	s_add_u32 s24, s20, 0xffe80080
	s_addc_u32 s23, s21, -1
	s_cmp_eq_u32 s54, s22
	s_cselect_b32 s22, s15, s24
	s_cselect_b32 s23, s13, s23
	s_cselect_b32 s26, s59, s60
	s_cselect_b32 s27, s58, s61
	s_add_u32 s24, s22, 0x80
	s_addc_u32 s25, s23, 0
	ds_read_b128 v[188:191], v139
	ds_read_b128 v[192:195], v139 offset:1024
	ds_read_b128 v[196:199], v139 offset:2048
	ds_read_b128 v[204:207], v139 offset:3072
	ds_read_b128 v[208:211], v139 offset:4096
	ds_read_b128 v[212:215], v139 offset:5120
	ds_read_b128 v[216:219], v139 offset:6144
	ds_read_b128 v[220:223], v139 offset:7168
	s_add_u32 s64, s20, 0xfff80000
	s_addc_u32 s65, s21, -1
	s_mov_b32 m0, s55
	s_nop 0
	global_load_lds_dwordx4 v1, s[64:65]
	s_nop 0
	s_mov_b32 m0, s56
	s_nop 0
	global_load_lds_dwordx4 v1, s[20:21]
	s_waitcnt vmcnt(8)
	s_waitcnt lgkmcnt(0)
	s_barrier
	s_setprio 1
	s_waitcnt lgkmcnt(7)
	v_mfma_f32_16x16x32_bf16 v[126:129], v[142:145], v[188:191], v[126:129]
	v_mfma_f32_16x16x32_bf16 v[122:125], v[150:153], v[188:191], v[122:125]
	s_waitcnt lgkmcnt(5)
	v_mfma_f32_16x16x32_bf16 v[110:113], v[142:145], v[196:199], v[110:113]
	v_mfma_f32_16x16x32_bf16 v[106:109], v[150:153], v[196:199], v[106:109]
	s_waitcnt lgkmcnt(3)
	v_mfma_f32_16x16x32_bf16 v[94:97], v[142:145], v[208:211], v[94:97]
	v_mfma_f32_16x16x32_bf16 v[90:93], v[150:153], v[208:211], v[90:93]
	s_waitcnt lgkmcnt(1)
	v_mfma_f32_16x16x32_bf16 v[78:81], v[142:145], v[216:219], v[78:81]
	v_mfma_f32_16x16x32_bf16 v[74:77], v[150:153], v[216:219], v[74:77]
	v_mfma_f32_16x16x32_bf16 v[126:129], v[146:149], v[192:195], v[126:129]
	v_mfma_f32_16x16x32_bf16 v[122:125], v[154:157], v[192:195], v[122:125]
	v_mfma_f32_16x16x32_bf16 v[110:113], v[146:149], v[204:207], v[110:113]
	v_mfma_f32_16x16x32_bf16 v[106:109], v[154:157], v[204:207], v[106:109]
	v_mfma_f32_16x16x32_bf16 v[94:97], v[146:149], v[212:215], v[94:97]
	v_mfma_f32_16x16x32_bf16 v[90:93], v[154:157], v[212:215], v[90:93]
	s_waitcnt lgkmcnt(0)
	v_mfma_f32_16x16x32_bf16 v[78:81], v[146:149], v[220:223], v[78:81]
	v_mfma_f32_16x16x32_bf16 v[74:77], v[154:157], v[220:223], v[74:77]
	s_setprio 0
	s_setprio 1
	v_mfma_f32_16x16x32_bf16 v[118:121], v[158:161], v[188:191], v[118:121]
	v_mfma_f32_16x16x32_bf16 v[114:117], v[174:177], v[188:191], v[114:117]
	v_mfma_f32_16x16x32_bf16 v[102:105], v[158:161], v[196:199], v[102:105]
	v_mfma_f32_16x16x32_bf16 v[98:101], v[174:177], v[196:199], v[98:101]
	v_mfma_f32_16x16x32_bf16 v[86:89], v[158:161], v[208:211], v[86:89]
	v_mfma_f32_16x16x32_bf16 v[82:85], v[174:177], v[208:211], v[82:85]
	v_mfma_f32_16x16x32_bf16 v[70:73], v[158:161], v[216:219], v[70:73]
	v_mfma_f32_16x16x32_bf16 v[66:69], v[174:177], v[216:219], v[66:69]
	v_mfma_f32_16x16x32_bf16 v[118:121], v[170:173], v[192:195], v[118:121]
	v_mfma_f32_16x16x32_bf16 v[114:117], v[184:187], v[192:195], v[114:117]
	v_mfma_f32_16x16x32_bf16 v[102:105], v[170:173], v[204:207], v[102:105]
	v_mfma_f32_16x16x32_bf16 v[98:101], v[184:187], v[204:207], v[98:101]
	s_add_u32 s64, s26, 0x80000
	v_mfma_f32_16x16x32_bf16 v[86:89], v[170:173], v[212:215], v[86:89]
	v_mfma_f32_16x16x32_bf16 v[82:85], v[184:187], v[212:215], v[82:85]
	v_mfma_f32_16x16x32_bf16 v[70:73], v[170:173], v[220:223], v[70:73]
	v_mfma_f32_16x16x32_bf16 v[66:69], v[184:187], v[220:223], v[66:69]
	s_setprio 0
	s_barrier
	ds_read_b128 v[188:191], v139 offset:16384
	ds_read_b128 v[192:195], v139 offset:17408
	ds_read_b128 v[196:199], v139 offset:18432
	ds_read_b128 v[204:207], v139 offset:19456
	ds_read_b128 v[208:211], v139 offset:20480
	ds_read_b128 v[212:215], v139 offset:21504
	ds_read_b128 v[216:219], v139 offset:22528
	ds_read_b128 v[220:223], v139 offset:23552
	s_mov_b32 m0, s37
	s_nop 0
	global_load_lds_dwordx4 v134, s[26:27]
	s_addc_u32 s65, s27, 0
	s_mov_b32 m0, s38
	s_nop 0
	global_load_lds_dwordx4 v134, s[64:65]
	s_add_u32 s64, s26, 0x100000
	s_addc_u32 s65, s27, 0
	s_mov_b32 m0, s39
	s_nop 0
	global_load_lds_dwordx4 v134, s[64:65]
	s_add_u32 s64, s26, 0x180000
	s_addc_u32 s65, s27, 0
	s_mov_b32 m0, s40
	s_nop 0
	global_load_lds_dwordx4 v134, s[64:65]
	s_add_u32 s64, s22, 0x80000
	s_mov_b32 m0, s36
	s_nop 0
	global_load_lds_dwordx4 v1, s[22:23]
	s_addc_u32 s65, s23, 0
	s_mov_b32 m0, s41
	s_nop 0
	global_load_lds_dwordx4 v1, s[64:65]
	s_waitcnt vmcnt(8)
	s_waitcnt lgkmcnt(0)
	s_barrier
; #define PG8_STAGE(bufoff, gbase, X) do { _Pragma("unroll") for (int _i = 0; _i < 2; ++_i) { \
;         const char* gp_ = (const char*)(gbase) + (_i ? rs##X : (size_t)0); const unsigned la_ = (unsigned)(size_t)(lds + (bufoff) + ldsw + _i * 8192); \
;         asm volatile("s_mov_b32 m0, %2\n\ts_nop 0\n\tglobal_load_lds_dwordx4 %0, %1" :: "v"(voff##X), "s"(gp_), "s"(la_) : "memory", "m0"); } } while (0)
; #define PG8_LDA(dst, b, h) do { _Pragma("unroll") for (int m = 0; m < 4; ++m) _Pragma("unroll") for (int k = 0; k < 2; ++k) dst[m][k] = *(const LAS bf16x8*)(lds + PG8_SA(b, h) + aoff + m * 2048 + k * 1024); } while (0)
; #define PG8_LDB(dst, b, h) do { _Pragma("unroll") for (int n = 0; n < 2; ++n) _Pragma("unroll") for (int k = 0; k < 2; ++k) dst[n][k] = *(const LAS bf16x8*)(lds + PG8_SB(b, h) + boff + n * 2048 + k * 1024); } while (0)
; #define PG8_WAIT_V(n) asm volatile("s_waitcnt vmcnt(" #n ")" ::: "memory")
; #define PG8_WAIT_L(n) asm volatile("s_waitcnt lgkmcnt(" #n ")" ::: "memory")
; #define PG8_BAR __builtin_amdgcn_s_barrier()
; #define PG8_SCHED __builtin_amdgcn_sched_barrier(0)
; template <class Epi>
; __device__ __forceinline__ void gemm_phase(LAS unsigned char* lds, const Gemm g_in, const StaticOrder& S, const Epi& E) {
;     ...
;             PG8_WAIT_V(8); PG8_WAIT_L(0); PG8_BAR; PG8_MMA(1, 0, At, B0); PG8_MMA(1, 1, At, B1); PG8_BAR; PG8_SCHED;
;             PG8_LDB(B0, 1, 0); PG8_LDB(B1, 1, 1); PG8_SCHED; PG8_LDA(At, 1, 0); PG8_STAGE(PG8_SA(0, 1), a2 + hsA, A);
;             PG8_WAIT_V(8); PG8_WAIT_L(0); PG8_BAR; PG8_MMA(0, 0, At, B0); PG8_MMA(0, 1, At, B1); PG8_BAR; PG8_SCHED;
	s_setprio 1
	s_waitcnt lgkmcnt(7)
	v_mfma_f32_16x16x32_bf16 v[62:65], v[142:145], v[188:191], v[62:65]
	v_mfma_f32_16x16x32_bf16 v[58:61], v[150:153], v[188:191], v[58:61]
	s_waitcnt lgkmcnt(5)
	v_mfma_f32_16x16x32_bf16 v[46:49], v[142:145], v[196:199], v[46:49]
	v_mfma_f32_16x16x32_bf16 v[42:45], v[150:153], v[196:199], v[42:45]
	s_waitcnt lgkmcnt(3)
	v_mfma_f32_16x16x32_bf16 v[30:33], v[142:145], v[208:211], v[30:33]
	v_mfma_f32_16x16x32_bf16 v[26:29], v[150:153], v[208:211], v[26:29]
	s_waitcnt lgkmcnt(1)
	v_mfma_f32_16x16x32_bf16 v[14:17], v[142:145], v[216:219], v[14:17]
	v_mfma_f32_16x16x32_bf16 v[10:13], v[150:153], v[216:219], v[10:13]
	v_mfma_f32_16x16x32_bf16 v[62:65], v[146:149], v[192:195], v[62:65]
	v_mfma_f32_16x16x32_bf16 v[58:61], v[154:157], v[192:195], v[58:61]
	v_mfma_f32_16x16x32_bf16 v[46:49], v[146:149], v[204:207], v[46:49]
	v_mfma_f32_16x16x32_bf16 v[42:45], v[154:157], v[204:207], v[42:45]
	v_mfma_f32_16x16x32_bf16 v[30:33], v[146:149], v[212:215], v[30:33]
	v_mfma_f32_16x16x32_bf16 v[26:29], v[154:157], v[212:215], v[26:29]
	s_waitcnt lgkmcnt(0)
	v_mfma_f32_16x16x32_bf16 v[14:17], v[146:149], v[220:223], v[14:17]
	v_mfma_f32_16x16x32_bf16 v[10:13], v[154:157], v[220:223], v[10:13]
	s_setprio 0
	s_setprio 1
	v_mfma_f32_16x16x32_bf16 v[54:57], v[158:161], v[188:191], v[54:57]
	v_mfma_f32_16x16x32_bf16 v[50:53], v[174:177], v[188:191], v[50:53]
	v_mfma_f32_16x16x32_bf16 v[38:41], v[158:161], v[196:199], v[38:41]
	v_mfma_f32_16x16x32_bf16 v[34:37], v[174:177], v[196:199], v[34:37]
	v_mfma_f32_16x16x32_bf16 v[22:25], v[158:161], v[208:211], v[22:25]
	v_mfma_f32_16x16x32_bf16 v[18:21], v[174:177], v[208:211], v[18:21]
	v_mfma_f32_16x16x32_bf16 v[6:9], v[158:161], v[216:219], v[6:9]
	v_mfma_f32_16x16x32_bf16 v[2:5], v[174:177], v[216:219], v[2:5]
	v_mfma_f32_16x16x32_bf16 v[54:57], v[170:173], v[192:195], v[54:57]
	v_mfma_f32_16x16x32_bf16 v[50:53], v[184:187], v[192:195], v[50:53]
	v_mfma_f32_16x16x32_bf16 v[38:41], v[170:173], v[204:207], v[38:41]
	v_mfma_f32_16x16x32_bf16 v[34:37], v[184:187], v[204:207], v[34:37]
	v_mfma_f32_16x16x32_bf16 v[22:25], v[170:173], v[212:215], v[22:25]
	v_mfma_f32_16x16x32_bf16 v[18:21], v[184:187], v[212:215], v[18:21]
	v_mfma_f32_16x16x32_bf16 v[6:9], v[170:173], v[220:223], v[6:9]
	v_mfma_f32_16x16x32_bf16 v[2:5], v[184:187], v[220:223], v[2:5]
	s_setprio 0
	s_barrier
	ds_read_b128 v[142:145], v140
	ds_read_b128 v[146:149], v140 offset:1024
	ds_read_b128 v[150:153], v140 offset:2048
	ds_read_b128 v[154:157], v140 offset:3072
	ds_read_b128 v[158:161], v141
	ds_read_b128 v[170:173], v141 offset:1024
	ds_read_b128 v[174:177], v141 offset:2048
	ds_read_b128 v[184:187], v141 offset:3072
	ds_read_b128 v[188:191], v139 offset:32768
	ds_read_b128 v[192:195], v139 offset:33792
	ds_read_b128 v[196:199], v139 offset:34816
	ds_read_b128 v[204:207], v139 offset:35840
	ds_read_b128 v[208:211], v139 offset:36864
	ds_read_b128 v[212:215], v139 offset:37888
	ds_read_b128 v[216:219], v139 offset:38912
	ds_read_b128 v[220:223], v139 offset:39936
	s_add_u32 s64, s22, 0x100000
	s_addc_u32 s65, s23, 0
	s_mov_b32 m0, s42
	s_nop 0
	global_load_lds_dwordx4 v1, s[64:65]
	s_add_u32 s64, s22, 0x180000
	s_addc_u32 s65, s23, 0
	s_mov_b32 m0, s43
	s_nop 0
	global_load_lds_dwordx4 v1, s[64:65]
	s_waitcnt vmcnt(8)
	s_waitcnt lgkmcnt(0)
	s_barrier
	s_setprio 1
	s_waitcnt lgkmcnt(7)
	v_mfma_f32_16x16x32_bf16 v[126:129], v[142:145], v[188:191], v[126:129]
	v_mfma_f32_16x16x32_bf16 v[122:125], v[150:153], v[188:191], v[122:125]
	s_waitcnt lgkmcnt(5)
	v_mfma_f32_16x16x32_bf16 v[110:113], v[142:145], v[196:199], v[110:113]
	v_mfma_f32_16x16x32_bf16 v[106:109], v[150:153], v[196:199], v[106:109]
	s_waitcnt lgkmcnt(3)
	v_mfma_f32_16x16x32_bf16 v[94:97], v[142:145], v[208:211], v[94:97]
	v_mfma_f32_16x16x32_bf16 v[90:93], v[150:153], v[208:211], v[90:93]
	s_waitcnt lgkmcnt(1)
	v_mfma_f32_16x16x32_bf16 v[78:81], v[142:145], v[216:219], v[78:81]
	v_mfma_f32_16x16x32_bf16 v[74:77], v[150:153], v[216:219], v[74:77]
	v_mfma_f32_16x16x32_bf16 v[126:129], v[146:149], v[192:195], v[126:129]
	v_mfma_f32_16x16x32_bf16 v[122:125], v[154:157], v[192:195], v[122:125]
	v_mfma_f32_16x16x32_bf16 v[110:113], v[146:149], v[204:207], v[110:113]
	v_mfma_f32_16x16x32_bf16 v[106:109], v[154:157], v[204:207], v[106:109]
	v_mfma_f32_16x16x32_bf16 v[94:97], v[146:149], v[212:215], v[94:97]
	v_mfma_f32_16x16x32_bf16 v[90:93], v[154:157], v[212:215], v[90:93]
	s_waitcnt lgkmcnt(0)
	v_mfma_f32_16x16x32_bf16 v[78:81], v[146:149], v[220:223], v[78:81]
	v_mfma_f32_16x16x32_bf16 v[74:77], v[154:157], v[220:223], v[74:77]
	s_setprio 0
	s_setprio 1
	v_mfma_f32_16x16x32_bf16 v[118:121], v[158:161], v[188:191], v[118:121]
	v_mfma_f32_16x16x32_bf16 v[114:117], v[174:177], v[188:191], v[114:117]
	v_mfma_f32_16x16x32_bf16 v[102:105], v[158:161], v[196:199], v[102:105]
	v_mfma_f32_16x16x32_bf16 v[98:101], v[174:177], v[196:199], v[98:101]
	v_mfma_f32_16x16x32_bf16 v[86:89], v[158:161], v[208:211], v[86:89]
	v_mfma_f32_16x16x32_bf16 v[82:85], v[174:177], v[208:211], v[82:85]
	v_mfma_f32_16x16x32_bf16 v[70:73], v[158:161], v[216:219], v[70:73]
	v_mfma_f32_16x16x32_bf16 v[66:69], v[174:177], v[216:219], v[66:69]
	v_mfma_f32_16x16x32_bf16 v[118:121], v[170:173], v[192:195], v[118:121]
	v_mfma_f32_16x16x32_bf16 v[114:117], v[184:187], v[192:195], v[114:117]
	v_mfma_f32_16x16x32_bf16 v[102:105], v[170:173], v[204:207], v[102:105]
	v_mfma_f32_16x16x32_bf16 v[98:101], v[184:187], v[204:207], v[98:101]
	s_add_u32 s64, s26, 0x80
	s_addc_u32 s65, s27, 0
	v_mfma_f32_16x16x32_bf16 v[86:89], v[170:173], v[212:215], v[86:89]
	v_mfma_f32_16x16x32_bf16 v[82:85], v[184:187], v[212:215], v[82:85]
	v_mfma_f32_16x16x32_bf16 v[70:73], v[170:173], v[220:223], v[70:73]
	v_mfma_f32_16x16x32_bf16 v[66:69], v[184:187], v[220:223], v[66:69]
	s_setprio 0
	s_barrier
; #define PG8_STAGE(bufoff, gbase, X) do { _Pragma("unroll") for (int _i = 0; _i < 2; ++_i) { \
;         const char* gp_ = (const char*)(gbase) + (_i ? rs##X : (size_t)0); const unsigned la_ = (unsigned)(size_t)(lds + (bufoff) + ldsw + _i * 8192); \
;         asm volatile("s_mov_b32 m0, %2\n\ts_nop 0\n\tglobal_load_lds_dwordx4 %0, %1" :: "v"(voff##X), "s"(gp_), "s"(la_) : "memory", "m0"); } } while (0)
; #define PG8_LDA(dst, b, h) do { _Pragma("unroll") for (int m = 0; m < 4; ++m) _Pragma("unroll") for (int k = 0; k < 2; ++k) dst[m][k] = *(const LAS bf16x8*)(lds + PG8_SA(b, h) + aoff + m * 2048 + k * 1024); } while (0)
; #define PG8_WAIT_V(n) asm volatile("s_waitcnt vmcnt(" #n ")" ::: "memory")
; #define PG8_WAIT_L(n) asm volatile("s_waitcnt lgkmcnt(" #n ")" ::: "memory")
; #define PG8_BAR __builtin_amdgcn_s_barrier()
; #define PG8_SCHED __builtin_amdgcn_sched_barrier(0)
; template <class Epi>
; __device__ __forceinline__ void gemm_phase(LAS unsigned char* lds, const Gemm g_in, const StaticOrder& S, const Epi& E) {
;     ...
;             PG8_LDA(At, 1, 1); PG8_STAGE(PG8_SB(1, 0), b3, B); PG8_STAGE(PG8_SB(1, 1), b3 + hsB, B); PG8_STAGE(PG8_SA(1, 0), a3, A);
;             PG8_WAIT_V(8); PG8_WAIT_L(0); PG8_BAR; PG8_MMA(1, 0, At, B0); PG8_MMA(1, 1, At, B1); PG8_BAR; PG8_SCHED;
;         }
	ds_read_b128 v[188:191], v139 offset:49152
	ds_read_b128 v[192:195], v139 offset:50176
	ds_read_b128 v[196:199], v139 offset:51200
	ds_read_b128 v[204:207], v139 offset:52224
	ds_read_b128 v[208:211], v139 offset:53248
	ds_read_b128 v[212:215], v139 offset:54272
	ds_read_b128 v[216:219], v139 offset:55296
	ds_read_b128 v[220:223], v139 offset:56320
	s_mov_b32 m0, s46
	s_nop 0
	global_load_lds_dwordx4 v134, s[64:65]
	s_add_u32 s64, s26, 0x80080
	s_addc_u32 s65, s27, 0
	s_mov_b32 m0, s47
	s_nop 0
	global_load_lds_dwordx4 v134, s[64:65]
	s_add_u32 s64, s26, 0x100080
	s_addc_u32 s65, s27, 0
	s_mov_b32 m0, s52
	s_nop 0
	global_load_lds_dwordx4 v134, s[64:65]
	s_add_u32 s26, s26, 0x180080
	s_addc_u32 s27, s27, 0
	s_mov_b32 m0, s53
	s_nop 0
	global_load_lds_dwordx4 v134, s[26:27]
	s_add_u32 s22, s22, 0x80080
	s_mov_b32 m0, s50
	s_nop 0
	global_load_lds_dwordx4 v1, s[24:25]
	s_addc_u32 s23, s23, 0
	s_mov_b32 m0, s51
	s_nop 0
	global_load_lds_dwordx4 v1, s[22:23]
	s_waitcnt vmcnt(8)
	s_waitcnt lgkmcnt(0)
	s_barrier
	s_setprio 1
	s_waitcnt lgkmcnt(7)
	v_mfma_f32_16x16x32_bf16 v[62:65], v[142:145], v[188:191], v[62:65]
	v_mfma_f32_16x16x32_bf16 v[58:61], v[150:153], v[188:191], v[58:61]
	s_waitcnt lgkmcnt(5)
	v_mfma_f32_16x16x32_bf16 v[46:49], v[142:145], v[196:199], v[46:49]
	v_mfma_f32_16x16x32_bf16 v[42:45], v[150:153], v[196:199], v[42:45]
	s_waitcnt lgkmcnt(3)
	v_mfma_f32_16x16x32_bf16 v[30:33], v[142:145], v[208:211], v[30:33]
	v_mfma_f32_16x16x32_bf16 v[26:29], v[150:153], v[208:211], v[26:29]
	s_waitcnt lgkmcnt(1)
	v_mfma_f32_16x16x32_bf16 v[14:17], v[142:145], v[216:219], v[14:17]
	v_mfma_f32_16x16x32_bf16 v[10:13], v[150:153], v[216:219], v[10:13]
	v_mfma_f32_16x16x32_bf16 v[62:65], v[146:149], v[192:195], v[62:65]
	v_mfma_f32_16x16x32_bf16 v[58:61], v[154:157], v[192:195], v[58:61]
	v_mfma_f32_16x16x32_bf16 v[46:49], v[146:149], v[204:207], v[46:49]
	v_mfma_f32_16x16x32_bf16 v[42:45], v[154:157], v[204:207], v[42:45]
	v_mfma_f32_16x16x32_bf16 v[30:33], v[146:149], v[212:215], v[30:33]
	v_mfma_f32_16x16x32_bf16 v[26:29], v[154:157], v[212:215], v[26:29]
	s_waitcnt lgkmcnt(0)
	v_mfma_f32_16x16x32_bf16 v[14:17], v[146:149], v[220:223], v[14:17]
	v_mfma_f32_16x16x32_bf16 v[10:13], v[154:157], v[220:223], v[10:13]
	s_setprio 0
	s_setprio 1
	v_mfma_f32_16x16x32_bf16 v[54:57], v[158:161], v[188:191], v[54:57]
	v_mfma_f32_16x16x32_bf16 v[50:53], v[174:177], v[188:191], v[50:53]
	v_mfma_f32_16x16x32_bf16 v[38:41], v[158:161], v[196:199], v[38:41]
	v_mfma_f32_16x16x32_bf16 v[34:37], v[174:177], v[196:199], v[34:37]
	v_mfma_f32_16x16x32_bf16 v[22:25], v[158:161], v[208:211], v[22:25]
	v_mfma_f32_16x16x32_bf16 v[18:21], v[174:177], v[208:211], v[18:21]
	v_mfma_f32_16x16x32_bf16 v[6:9], v[158:161], v[216:219], v[6:9]
	v_mfma_f32_16x16x32_bf16 v[2:5], v[174:177], v[216:219], v[2:5]
	v_mfma_f32_16x16x32_bf16 v[54:57], v[170:173], v[192:195], v[54:57]
	v_mfma_f32_16x16x32_bf16 v[50:53], v[184:187], v[192:195], v[50:53]
	v_mfma_f32_16x16x32_bf16 v[38:41], v[170:173], v[204:207], v[38:41]
	v_mfma_f32_16x16x32_bf16 v[34:37], v[184:187], v[204:207], v[34:37]
	s_add_u32 s60, s60, 0x100
	s_addc_u32 s61, s61, 0
	s_add_u32 s20, s20, 0x100
	s_addc_u32 s21, s21, 0
	s_cmp_ge_i32 s62, s31
	s_mov_b32 s22, s62
	v_mfma_f32_16x16x32_bf16 v[22:25], v[170:173], v[212:215], v[22:25]
	v_mfma_f32_16x16x32_bf16 v[18:21], v[184:187], v[212:215], v[18:21]
	v_mfma_f32_16x16x32_bf16 v[6:9], v[170:173], v[220:223], v[6:9]
	v_mfma_f32_16x16x32_bf16 v[2:5], v[184:187], v[220:223], v[2:5]
	s_setprio 0
	s_barrier
	s_cbranch_scc0 .LBB0_388
	s_and_b64 vcc, exec, s[6:7]
	s_cbranch_vccz .LBB0_391

; #define PG8_STAGE(bufoff, gbase, X) do { _Pragma("unroll") for (int _i = 0; _i < 2; ++_i) { \
;         const char* gp_ = (const char*)(gbase) + (_i ? rs##X : (size_t)0); const unsigned la_ = (unsigned)(size_t)(lds + (bufoff) + ldsw + _i * 8192); \
;         asm volatile("s_mov_b32 m0, %2\n\ts_nop 0\n\tglobal_load_lds_dwordx4 %0, %1" :: "v"(voff##X), "s"(gp_), "s"(la_) : "memory", "m0"); } } while (0)
; #define PG8_LDA(dst, b, h) do { _Pragma("unroll") for (int m = 0; m < 4; ++m) _Pragma("unroll") for (int k = 0; k < 2; ++k) dst[m][k] = *(const LAS bf16x8*)(lds + PG8_SA(b, h) + aoff + m * 2048 + k * 1024); } while (0)
; #define PG8_LDB(dst, b, h) do { _Pragma("unroll") for (int n = 0; n < 2; ++n) _Pragma("unroll") for (int k = 0; k < 2; ++k) dst[n][k] = *(const LAS bf16x8*)(lds + PG8_SB(b, h) + boff + n * 2048 + k * 1024); } while (0)
; #define PG8_WAIT_V(n) asm volatile("s_waitcnt vmcnt(" #n ")" ::: "memory")
; #define PG8_WAIT_L(n) asm volatile("s_waitcnt lgkmcnt(" #n ")" ::: "memory")
; #define PG8_BAR __builtin_amdgcn_s_barrier()
; #define PG8_SCHED __builtin_amdgcn_sched_barrier(0)
; template <class Epi>
; __device__ __forceinline__ void gemm_phase(LAS unsigned char* lds, const Gemm g_in, const StaticOrder& S, const Epi& E) {
;     ...
;         for (int t = 0; t < nt; t += 2) {
;             const bool last = (t == nt - 2);
;             const char* a1 = cA + (size_t)(t + 1) * kstep;
;             const char* a2 = last ? nA : cA + (size_t)(t + 2) * kstep; const char* b2 = last ? nB : cB + (size_t)(t + 2) * kstep;
;             const char* a3 = a2 + kstep; const char* b3 = b2 + kstep;
;             PG8_LDB(B0, 0, 0); PG8_LDB(B1, 0, 1); PG8_SCHED; PG8_LDA(At, 0, 0); PG8_STAGE(PG8_SA(1, 1), a1 + hsA, A);
;             PG8_WAIT_V(8); PG8_WAIT_L(0); PG8_BAR; PG8_MMA(0, 0, At, B0); PG8_MMA(0, 1, At, B1); PG8_BAR; PG8_SCHED;
;             PG8_LDA(At, 0, 1); PG8_STAGE(PG8_SB(0, 0), b2, B); PG8_STAGE(PG8_SB(0, 1), b2 + hsB, B); PG8_STAGE(PG8_SA(0, 0), a2, A);
;             PG8_WAIT_V(8); PG8_WAIT_L(0); PG8_BAR; PG8_MMA(1, 0, At, B0); PG8_MMA(1, 1, At, B1); PG8_BAR; PG8_SCHED;
.LBB0_406:
	v_add_u32_e32 v143, 0x10000, v141
	ds_read_b128 v[134:137], v143
	ds_read_b128 v[144:147], v143 offset:1024
	ds_read_b128 v[148:151], v143 offset:2048
	ds_read_b128 v[152:155], v143 offset:3072
	v_add_u32_e32 v143, 0x14000, v141
	ds_read_b128 v[156:159], v143
	ds_read_b128 v[170:173], v143 offset:1024
	ds_read_b128 v[174:177], v143 offset:2048
	ds_read_b128 v[184:187], v143 offset:3072
	s_add_i32 s70, s30, 2
	s_add_u32 s34, s28, 0xfff40080
	s_addc_u32 s31, s29, -1
	s_cmp_eq_u32 s62, s30
	s_cselect_b32 s30, s21, s34
	s_cselect_b32 s31, s19, s31
	s_cselect_b32 s36, s67, s68
	s_cselect_b32 s37, s66, s69
	s_add_u32 s34, s30, 0x80
	s_addc_u32 s35, s31, 0
	ds_read_b128 v[188:191], v142
	ds_read_b128 v[192:195], v142 offset:1024
	ds_read_b128 v[196:199], v142 offset:2048
	ds_read_b128 v[204:207], v142 offset:3072
	ds_read_b128 v[208:211], v142 offset:4096
	ds_read_b128 v[212:215], v142 offset:5120
	ds_read_b128 v[216:219], v142 offset:6144
	ds_read_b128 v[220:223], v142 offset:7168
	s_add_u32 s72, s28, 0xfffc0000
	s_addc_u32 s73, s29, -1
	s_mov_b32 m0, s63
	s_nop 0
	global_load_lds_dwordx4 v1, s[72:73]
	s_nop 0
	s_mov_b32 m0, s64
	s_nop 0
	global_load_lds_dwordx4 v1, s[28:29]
	s_waitcnt vmcnt(8)
	s_waitcnt lgkmcnt(0)
	s_barrier
	s_setprio 1
	s_waitcnt lgkmcnt(7)
	v_mfma_i32_16x16x64_i8 v[126:129], v[134:137], v[188:191], v[126:129]
	v_mfma_i32_16x16x64_i8 v[122:125], v[148:151], v[188:191], v[122:125]
	s_waitcnt lgkmcnt(5)
	v_mfma_i32_16x16x64_i8 v[118:121], v[134:137], v[196:199], v[118:121]
	v_mfma_i32_16x16x64_i8 v[110:113], v[148:151], v[196:199], v[110:113]
	s_waitcnt lgkmcnt(3)
	v_mfma_i32_16x16x64_i8 v[102:105], v[134:137], v[208:211], v[102:105]
	v_mfma_i32_16x16x64_i8 v[94:97], v[148:151], v[208:211], v[94:97]
	s_waitcnt lgkmcnt(1)
	v_mfma_i32_16x16x64_i8 v[86:89], v[134:137], v[216:219], v[86:89]
	v_mfma_i32_16x16x64_i8 v[78:81], v[148:151], v[216:219], v[78:81]
	v_mfma_i32_16x16x64_i8 v[126:129], v[144:147], v[192:195], v[126:129]
	v_mfma_i32_16x16x64_i8 v[122:125], v[152:155], v[192:195], v[122:125]
	v_mfma_i32_16x16x64_i8 v[118:121], v[144:147], v[204:207], v[118:121]
	v_mfma_i32_16x16x64_i8 v[110:113], v[152:155], v[204:207], v[110:113]
	v_mfma_i32_16x16x64_i8 v[102:105], v[144:147], v[212:215], v[102:105]
	v_mfma_i32_16x16x64_i8 v[94:97], v[152:155], v[212:215], v[94:97]
	s_waitcnt lgkmcnt(0)
	v_mfma_i32_16x16x64_i8 v[86:89], v[144:147], v[220:223], v[86:89]
	v_mfma_i32_16x16x64_i8 v[78:81], v[152:155], v[220:223], v[78:81]
	s_setprio 0
	s_setprio 1
	v_mfma_i32_16x16x64_i8 v[114:117], v[156:159], v[188:191], v[114:117]
	v_mfma_i32_16x16x64_i8 v[106:109], v[174:177], v[188:191], v[106:109]
	v_mfma_i32_16x16x64_i8 v[98:101], v[156:159], v[196:199], v[98:101]
	v_mfma_i32_16x16x64_i8 v[90:93], v[174:177], v[196:199], v[90:93]
	v_mfma_i32_16x16x64_i8 v[82:85], v[156:159], v[208:211], v[82:85]
	v_mfma_i32_16x16x64_i8 v[74:77], v[174:177], v[208:211], v[74:77]
	v_mfma_i32_16x16x64_i8 v[70:73], v[156:159], v[216:219], v[70:73]
	v_mfma_i32_16x16x64_i8 v[66:69], v[174:177], v[216:219], v[66:69]
	v_mfma_i32_16x16x64_i8 v[114:117], v[170:173], v[192:195], v[114:117]
	v_mfma_i32_16x16x64_i8 v[106:109], v[184:187], v[192:195], v[106:109]
	v_mfma_i32_16x16x64_i8 v[98:101], v[170:173], v[204:207], v[98:101]
	v_mfma_i32_16x16x64_i8 v[90:93], v[184:187], v[204:207], v[90:93]
	s_add_u32 s72, s36, 0x40000
	v_mfma_i32_16x16x64_i8 v[82:85], v[170:173], v[212:215], v[82:85]
	v_mfma_i32_16x16x64_i8 v[74:77], v[184:187], v[212:215], v[74:77]
	v_mfma_i32_16x16x64_i8 v[70:73], v[170:173], v[220:223], v[70:73]
	v_mfma_i32_16x16x64_i8 v[66:69], v[184:187], v[220:223], v[66:69]
	s_setprio 0
	s_barrier
	ds_read_b128 v[188:191], v142 offset:16384
	ds_read_b128 v[192:195], v142 offset:17408
	ds_read_b128 v[196:199], v142 offset:18432
	ds_read_b128 v[204:207], v142 offset:19456
	ds_read_b128 v[208:211], v142 offset:20480
	ds_read_b128 v[212:215], v142 offset:21504
	ds_read_b128 v[216:219], v142 offset:22528
	ds_read_b128 v[220:223], v142 offset:23552
	s_mov_b32 m0, s44
	s_nop 0
	global_load_lds_dwordx4 v138, s[36:37]
	s_addc_u32 s73, s37, 0
	s_mov_b32 m0, s45
	s_nop 0
	global_load_lds_dwordx4 v138, s[72:73]
	s_add_u32 s72, s36, 0x80000
	s_addc_u32 s73, s37, 0
	s_mov_b32 m0, s46
	s_nop 0
	global_load_lds_dwordx4 v138, s[72:73]
	s_add_u32 s72, s36, 0xc0000
	s_addc_u32 s73, s37, 0
	s_mov_b32 m0, s47
	s_nop 0
	global_load_lds_dwordx4 v138, s[72:73]
	s_add_u32 s72, s30, 0x40000
	s_mov_b32 m0, s23
	s_nop 0
	global_load_lds_dwordx4 v1, s[30:31]
	s_addc_u32 s73, s31, 0
	s_mov_b32 m0, s50
	s_nop 0
	global_load_lds_dwordx4 v1, s[72:73]
	s_waitcnt vmcnt(8)
	s_waitcnt lgkmcnt(0)
	s_barrier
; #define PG8_STAGE(bufoff, gbase, X) do { _Pragma("unroll") for (int _i = 0; _i < 2; ++_i) { \
;         const char* gp_ = (const char*)(gbase) + (_i ? rs##X : (size_t)0); const unsigned la_ = (unsigned)(size_t)(lds + (bufoff) + ldsw + _i * 8192); \
;         asm volatile("s_mov_b32 m0, %2\n\ts_nop 0\n\tglobal_load_lds_dwordx4 %0, %1" :: "v"(voff##X), "s"(gp_), "s"(la_) : "memory", "m0"); } } while (0)
; #define PG8_LDA(dst, b, h) do { _Pragma("unroll") for (int m = 0; m < 4; ++m) _Pragma("unroll") for (int k = 0; k < 2; ++k) dst[m][k] = *(const LAS bf16x8*)(lds + PG8_SA(b, h) + aoff + m * 2048 + k * 1024); } while (0)
; #define PG8_LDB(dst, b, h) do { _Pragma("unroll") for (int n = 0; n < 2; ++n) _Pragma("unroll") for (int k = 0; k < 2; ++k) dst[n][k] = *(const LAS bf16x8*)(lds + PG8_SB(b, h) + boff + n * 2048 + k * 1024); } while (0)
; #define PG8_WAIT_V(n) asm volatile("s_waitcnt vmcnt(" #n ")" ::: "memory")
; #define PG8_WAIT_L(n) asm volatile("s_waitcnt lgkmcnt(" #n ")" ::: "memory")
; #define PG8_BAR __builtin_amdgcn_s_barrier()
; #define PG8_SCHED __builtin_amdgcn_sched_barrier(0)
; template <class Epi>
; __device__ __forceinline__ void gemm_phase(LAS unsigned char* lds, const Gemm g_in, const StaticOrder& S, const Epi& E) {
;     ...
;             PG8_WAIT_V(8); PG8_WAIT_L(0); PG8_BAR; PG8_MMA(1, 0, At, B0); PG8_MMA(1, 1, At, B1); PG8_BAR; PG8_SCHED;
;             PG8_LDB(B0, 1, 0); PG8_LDB(B1, 1, 1); PG8_SCHED; PG8_LDA(At, 1, 0); PG8_STAGE(PG8_SA(0, 1), a2 + hsA, A);
;             PG8_WAIT_V(8); PG8_WAIT_L(0); PG8_BAR; PG8_MMA(0, 0, At, B0); PG8_MMA(0, 1, At, B1); PG8_BAR; PG8_SCHED;
	s_setprio 1
	s_waitcnt lgkmcnt(7)
	v_mfma_i32_16x16x64_i8 v[62:65], v[134:137], v[188:191], v[62:65]
	v_mfma_i32_16x16x64_i8 v[58:61], v[148:151], v[188:191], v[58:61]
	s_waitcnt lgkmcnt(5)
	v_mfma_i32_16x16x64_i8 v[54:57], v[134:137], v[196:199], v[54:57]
	v_mfma_i32_16x16x64_i8 v[46:49], v[148:151], v[196:199], v[46:49]
	s_waitcnt lgkmcnt(3)
	v_mfma_i32_16x16x64_i8 v[38:41], v[134:137], v[208:211], v[38:41]
	v_mfma_i32_16x16x64_i8 v[30:33], v[148:151], v[208:211], v[30:33]
	s_waitcnt lgkmcnt(1)
	v_mfma_i32_16x16x64_i8 v[22:25], v[134:137], v[216:219], v[22:25]
	v_mfma_i32_16x16x64_i8 v[14:17], v[148:151], v[216:219], v[14:17]
	v_mfma_i32_16x16x64_i8 v[62:65], v[144:147], v[192:195], v[62:65]
	v_mfma_i32_16x16x64_i8 v[58:61], v[152:155], v[192:195], v[58:61]
	v_mfma_i32_16x16x64_i8 v[54:57], v[144:147], v[204:207], v[54:57]
	v_mfma_i32_16x16x64_i8 v[46:49], v[152:155], v[204:207], v[46:49]
	v_mfma_i32_16x16x64_i8 v[38:41], v[144:147], v[212:215], v[38:41]
	v_mfma_i32_16x16x64_i8 v[30:33], v[152:155], v[212:215], v[30:33]
	s_waitcnt lgkmcnt(0)
	v_mfma_i32_16x16x64_i8 v[22:25], v[144:147], v[220:223], v[22:25]
	v_mfma_i32_16x16x64_i8 v[14:17], v[152:155], v[220:223], v[14:17]
	s_setprio 0
	s_setprio 1
	v_mfma_i32_16x16x64_i8 v[50:53], v[156:159], v[188:191], v[50:53]
	v_mfma_i32_16x16x64_i8 v[42:45], v[174:177], v[188:191], v[42:45]
	v_mfma_i32_16x16x64_i8 v[34:37], v[156:159], v[196:199], v[34:37]
	v_mfma_i32_16x16x64_i8 v[26:29], v[174:177], v[196:199], v[26:29]
	v_mfma_i32_16x16x64_i8 v[18:21], v[156:159], v[208:211], v[18:21]
	v_mfma_i32_16x16x64_i8 v[10:13], v[174:177], v[208:211], v[10:13]
	v_mfma_i32_16x16x64_i8 v[6:9], v[156:159], v[216:219], v[6:9]
	v_mfma_i32_16x16x64_i8 v[2:5], v[174:177], v[216:219], v[2:5]
	v_mfma_i32_16x16x64_i8 v[50:53], v[170:173], v[192:195], v[50:53]
	v_mfma_i32_16x16x64_i8 v[42:45], v[184:187], v[192:195], v[42:45]
	v_mfma_i32_16x16x64_i8 v[34:37], v[170:173], v[204:207], v[34:37]
	v_mfma_i32_16x16x64_i8 v[26:29], v[184:187], v[204:207], v[26:29]
	v_mfma_i32_16x16x64_i8 v[18:21], v[170:173], v[212:215], v[18:21]
	v_mfma_i32_16x16x64_i8 v[10:13], v[184:187], v[212:215], v[10:13]
	v_mfma_i32_16x16x64_i8 v[6:9], v[170:173], v[220:223], v[6:9]
	v_mfma_i32_16x16x64_i8 v[2:5], v[184:187], v[220:223], v[2:5]
	s_setprio 0
	s_barrier
	v_add_u32_e32 v143, 0x18000, v141
	ds_read_b128 v[134:137], v143
	ds_read_b128 v[144:147], v143 offset:1024
	ds_read_b128 v[148:151], v143 offset:2048
	ds_read_b128 v[152:155], v143 offset:3072
	v_add_u32_e32 v143, 0x1c000, v141
	ds_read_b128 v[156:159], v143
	ds_read_b128 v[170:173], v143 offset:1024
	ds_read_b128 v[174:177], v143 offset:2048
	ds_read_b128 v[184:187], v143 offset:3072
	ds_read_b128 v[188:191], v142 offset:32768
	ds_read_b128 v[192:195], v142 offset:33792
	ds_read_b128 v[196:199], v142 offset:34816
	ds_read_b128 v[204:207], v142 offset:35840
	ds_read_b128 v[208:211], v142 offset:36864
	ds_read_b128 v[212:215], v142 offset:37888
	ds_read_b128 v[216:219], v142 offset:38912
	ds_read_b128 v[220:223], v142 offset:39936
	s_add_u32 s72, s30, 0x80000
	s_addc_u32 s73, s31, 0
	s_mov_b32 m0, s51
	s_nop 0
	global_load_lds_dwordx4 v1, s[72:73]
	s_add_u32 s72, s30, 0xc0000
	s_addc_u32 s73, s31, 0
	s_mov_b32 m0, s52
	s_nop 0
	global_load_lds_dwordx4 v1, s[72:73]
	s_waitcnt vmcnt(8)
	s_waitcnt lgkmcnt(0)
	s_barrier
	s_setprio 1
	s_waitcnt lgkmcnt(7)
	v_mfma_i32_16x16x64_i8 v[126:129], v[134:137], v[188:191], v[126:129]
	v_mfma_i32_16x16x64_i8 v[122:125], v[148:151], v[188:191], v[122:125]
	s_waitcnt lgkmcnt(5)
	v_mfma_i32_16x16x64_i8 v[118:121], v[134:137], v[196:199], v[118:121]
	v_mfma_i32_16x16x64_i8 v[110:113], v[148:151], v[196:199], v[110:113]
	s_waitcnt lgkmcnt(3)
	v_mfma_i32_16x16x64_i8 v[102:105], v[134:137], v[208:211], v[102:105]
	v_mfma_i32_16x16x64_i8 v[94:97], v[148:151], v[208:211], v[94:97]
	s_waitcnt lgkmcnt(1)
	v_mfma_i32_16x16x64_i8 v[86:89], v[134:137], v[216:219], v[86:89]
	v_mfma_i32_16x16x64_i8 v[78:81], v[148:151], v[216:219], v[78:81]
	v_mfma_i32_16x16x64_i8 v[126:129], v[144:147], v[192:195], v[126:129]
	v_mfma_i32_16x16x64_i8 v[122:125], v[152:155], v[192:195], v[122:125]
	v_mfma_i32_16x16x64_i8 v[118:121], v[144:147], v[204:207], v[118:121]
	v_mfma_i32_16x16x64_i8 v[110:113], v[152:155], v[204:207], v[110:113]
	v_mfma_i32_16x16x64_i8 v[102:105], v[144:147], v[212:215], v[102:105]
	v_mfma_i32_16x16x64_i8 v[94:97], v[152:155], v[212:215], v[94:97]
	s_waitcnt lgkmcnt(0)
	v_mfma_i32_16x16x64_i8 v[86:89], v[144:147], v[220:223], v[86:89]
	v_mfma_i32_16x16x64_i8 v[78:81], v[152:155], v[220:223], v[78:81]
	s_setprio 0
	s_setprio 1
	v_mfma_i32_16x16x64_i8 v[114:117], v[156:159], v[188:191], v[114:117]
	v_mfma_i32_16x16x64_i8 v[106:109], v[174:177], v[188:191], v[106:109]
	v_mfma_i32_16x16x64_i8 v[98:101], v[156:159], v[196:199], v[98:101]
	v_mfma_i32_16x16x64_i8 v[90:93], v[174:177], v[196:199], v[90:93]
	v_mfma_i32_16x16x64_i8 v[82:85], v[156:159], v[208:211], v[82:85]
	v_mfma_i32_16x16x64_i8 v[74:77], v[174:177], v[208:211], v[74:77]
	v_mfma_i32_16x16x64_i8 v[70:73], v[156:159], v[216:219], v[70:73]
	v_mfma_i32_16x16x64_i8 v[66:69], v[174:177], v[216:219], v[66:69]
	v_mfma_i32_16x16x64_i8 v[114:117], v[170:173], v[192:195], v[114:117]
	v_mfma_i32_16x16x64_i8 v[106:109], v[184:187], v[192:195], v[106:109]
	v_mfma_i32_16x16x64_i8 v[98:101], v[170:173], v[204:207], v[98:101]
	v_mfma_i32_16x16x64_i8 v[90:93], v[184:187], v[204:207], v[90:93]
	s_add_u32 s72, s36, 0x80
	s_addc_u32 s73, s37, 0
	v_mfma_i32_16x16x64_i8 v[82:85], v[170:173], v[212:215], v[82:85]
	v_mfma_i32_16x16x64_i8 v[74:77], v[184:187], v[212:215], v[74:77]
	v_mfma_i32_16x16x64_i8 v[70:73], v[170:173], v[220:223], v[70:73]
	v_mfma_i32_16x16x64_i8 v[66:69], v[184:187], v[220:223], v[66:69]
	s_setprio 0
	s_barrier
; #define PG8_STAGE(bufoff, gbase, X) do { _Pragma("unroll") for (int _i = 0; _i < 2; ++_i) { \
;         const char* gp_ = (const char*)(gbase) + (_i ? rs##X : (size_t)0); const unsigned la_ = (unsigned)(size_t)(lds + (bufoff) + ldsw + _i * 8192); \
;         asm volatile("s_mov_b32 m0, %2\n\ts_nop 0\n\tglobal_load_lds_dwordx4 %0, %1" :: "v"(voff##X), "s"(gp_), "s"(la_) : "memory", "m0"); } } while (0)
; #define PG8_LDA(dst, b, h) do { _Pragma("unroll") for (int m = 0; m < 4; ++m) _Pragma("unroll") for (int k = 0; k < 2; ++k) dst[m][k] = *(const LAS bf16x8*)(lds + PG8_SA(b, h) + aoff + m * 2048 + k * 1024); } while (0)
; #define PG8_WAIT_V(n) asm volatile("s_waitcnt vmcnt(" #n ")" ::: "memory")
; #define PG8_WAIT_L(n) asm volatile("s_waitcnt lgkmcnt(" #n ")" ::: "memory")
; #define PG8_BAR __builtin_amdgcn_s_barrier()
; #define PG8_SCHED __builtin_amdgcn_sched_barrier(0)
; template <class Epi>
; __device__ __forceinline__ void gemm_phase(LAS unsigned char* lds, const Gemm g_in, const StaticOrder& S, const Epi& E) {
;     ...
;             PG8_LDA(At, 1, 1); PG8_STAGE(PG8_SB(1, 0), b3, B); PG8_STAGE(PG8_SB(1, 1), b3 + hsB, B); PG8_STAGE(PG8_SA(1, 0), a3, A);
;             PG8_WAIT_V(8); PG8_WAIT_L(0); PG8_BAR; PG8_MMA(1, 0, At, B0); PG8_MMA(1, 1, At, B1); PG8_BAR; PG8_SCHED;
;         }
;     __device__ __forceinline__ void operator()(const f32x4 (&acc)[2][2][4][2], const Unit& u, int wr, int wc, int fr, int fq) const {
;     ...
;                 for (int bj = 0; bj < 2; ++bj) { f32x4 v0 = acc[ai][bj][m][0], v1 = acc[ai][bj][m][1];
;                     if (I8_) { v0 = __builtin_convertvector(__builtin_bit_cast(i32x4, v0), f32x4) * I8_DEQ; v1 = __builtin_convertvector(__builtin_bit_cast(i32x4, v1), f32x4) * I8_DEQ; }
	ds_read_b128 v[188:191], v142 offset:49152
	ds_read_b128 v[192:195], v142 offset:50176
	ds_read_b128 v[196:199], v142 offset:51200
	ds_read_b128 v[204:207], v142 offset:52224
	ds_read_b128 v[208:211], v142 offset:53248
	ds_read_b128 v[212:215], v142 offset:54272
	ds_read_b128 v[216:219], v142 offset:55296
	ds_read_b128 v[220:223], v142 offset:56320
	s_mov_b32 m0, s56
	s_nop 0
	global_load_lds_dwordx4 v138, s[72:73]
	s_add_u32 s72, s36, 0x40080
	s_addc_u32 s73, s37, 0
	s_mov_b32 m0, s57
	s_nop 0
	global_load_lds_dwordx4 v138, s[72:73]
	s_add_u32 s72, s36, 0x80080
	s_addc_u32 s73, s37, 0
	s_mov_b32 m0, s60
	s_nop 0
	global_load_lds_dwordx4 v138, s[72:73]
	s_add_u32 s36, s36, 0xc0080
	s_addc_u32 s37, s37, 0
	s_mov_b32 m0, s61
	s_nop 0
	global_load_lds_dwordx4 v138, s[36:37]
	s_add_u32 s30, s30, 0x40080
	s_mov_b32 m0, s58
	s_nop 0
	global_load_lds_dwordx4 v1, s[34:35]
	s_addc_u32 s31, s31, 0
	s_mov_b32 m0, s59
	s_nop 0
	global_load_lds_dwordx4 v1, s[30:31]
	s_waitcnt vmcnt(8)
	s_waitcnt lgkmcnt(0)
	s_barrier
	s_setprio 1
	s_waitcnt lgkmcnt(7)
	v_mfma_i32_16x16x64_i8 v[62:65], v[134:137], v[188:191], v[62:65]
	v_mfma_i32_16x16x64_i8 v[58:61], v[148:151], v[188:191], v[58:61]
	s_waitcnt lgkmcnt(5)
	v_mfma_i32_16x16x64_i8 v[54:57], v[134:137], v[196:199], v[54:57]
	v_mfma_i32_16x16x64_i8 v[46:49], v[148:151], v[196:199], v[46:49]
	s_waitcnt lgkmcnt(3)
	v_mfma_i32_16x16x64_i8 v[38:41], v[134:137], v[208:211], v[38:41]
	v_mfma_i32_16x16x64_i8 v[30:33], v[148:151], v[208:211], v[30:33]
	s_waitcnt lgkmcnt(1)
	v_mfma_i32_16x16x64_i8 v[22:25], v[134:137], v[216:219], v[22:25]
	v_mfma_i32_16x16x64_i8 v[14:17], v[148:151], v[216:219], v[14:17]
	v_mfma_i32_16x16x64_i8 v[62:65], v[144:147], v[192:195], v[62:65]
	v_mfma_i32_16x16x64_i8 v[58:61], v[152:155], v[192:195], v[58:61]
	v_mfma_i32_16x16x64_i8 v[54:57], v[144:147], v[204:207], v[54:57]
	v_mfma_i32_16x16x64_i8 v[46:49], v[152:155], v[204:207], v[46:49]
	v_mfma_i32_16x16x64_i8 v[38:41], v[144:147], v[212:215], v[38:41]
	v_mfma_i32_16x16x64_i8 v[30:33], v[152:155], v[212:215], v[30:33]
	s_waitcnt lgkmcnt(0)
	v_mfma_i32_16x16x64_i8 v[22:25], v[144:147], v[220:223], v[22:25]
	v_mfma_i32_16x16x64_i8 v[14:17], v[152:155], v[220:223], v[14:17]
	s_setprio 0
	s_setprio 1
	v_mfma_i32_16x16x64_i8 v[50:53], v[156:159], v[188:191], v[50:53]
	v_mfma_i32_16x16x64_i8 v[42:45], v[174:177], v[188:191], v[42:45]
	v_mfma_i32_16x16x64_i8 v[34:37], v[156:159], v[196:199], v[34:37]
	v_mfma_i32_16x16x64_i8 v[26:29], v[174:177], v[196:199], v[26:29]
	v_mfma_i32_16x16x64_i8 v[18:21], v[156:159], v[208:211], v[18:21]
	v_mfma_i32_16x16x64_i8 v[10:13], v[174:177], v[208:211], v[10:13]
	v_mfma_i32_16x16x64_i8 v[6:9], v[156:159], v[216:219], v[6:9]
	v_mfma_i32_16x16x64_i8 v[2:5], v[174:177], v[216:219], v[2:5]
	v_mfma_i32_16x16x64_i8 v[50:53], v[170:173], v[192:195], v[50:53]
	v_mfma_i32_16x16x64_i8 v[42:45], v[184:187], v[192:195], v[42:45]
	v_mfma_i32_16x16x64_i8 v[34:37], v[170:173], v[204:207], v[34:37]
	v_mfma_i32_16x16x64_i8 v[26:29], v[184:187], v[204:207], v[26:29]
	s_add_u32 s68, s68, 0x100
	s_addc_u32 s69, s69, 0
	s_add_u32 s28, s28, 0x100
	s_addc_u32 s29, s29, 0
	s_cmp_ge_i32 s70, s41
	s_mov_b32 s30, s70
	v_mfma_i32_16x16x64_i8 v[18:21], v[170:173], v[212:215], v[18:21]
	v_mfma_i32_16x16x64_i8 v[10:13], v[184:187], v[212:215], v[10:13]
	v_mfma_i32_16x16x64_i8 v[6:9], v[170:173], v[220:223], v[6:9]
	v_mfma_i32_16x16x64_i8 v[2:5], v[184:187], v[220:223], v[2:5]
	s_setprio 0
	s_barrier
	s_cbranch_scc0 .LBB0_406
	v_cvt_f32_i32_e32 v129, v129
	v_cvt_f32_i32_e32 v128, v128
	v_cvt_f32_i32_e32 v135, v123
	v_cvt_f32_i32_e32 v134, v122
	v_cvt_f32_i32_e32 v109, v109
	v_pk_mul_f32 v[122:123], v[128:129], s[8:9] op_sel_hi:[1,0]
	v_cvt_f32_i32_e32 v108, v108
	v_pk_mul_f32 v[128:129], v[134:135], s[8:9] op_sel_hi:[1,0]
	v_cvt_f32_i32_e32 v135, v115
	v_cvt_f32_i32_e32 v134, v114
	v_cvt_f32_i32_e32 v115, v117
	v_cvt_f32_i32_e32 v114, v116
	v_cvt_f32_i32_e32 v113, v113
	v_pk_mul_f32 v[116:117], v[134:135], s[8:9] op_sel_hi:[1,0]
	v_pk_mul_f32 v[134:135], v[108:109], s[8:9] op_sel_hi:[1,0]
	v_cvt_f32_i32_e32 v109, v119
	v_cvt_f32_i32_e32 v108, v118
	v_cvt_f32_i32_e32 v119, v111
	v_cvt_f32_i32_e32 v112, v112
	v_cvt_f32_i32_e32 v118, v110
	v_cvt_f32_i32_e32 v93, v93
	v_cvt_f32_i32_e32 v92, v92
	v_pk_mul_f32 v[110:111], v[112:113], s[8:9] op_sel_hi:[1,0]
	v_pk_mul_f32 v[112:113], v[118:119], s[8:9] op_sel_hi:[1,0]
	v_cvt_f32_i32_e32 v119, v99
	v_cvt_f32_i32_e32 v118, v98
	v_cvt_f32_i32_e32 v99, v101
	v_cvt_f32_i32_e32 v98, v100
	v_cvt_f32_i32_e32 v97, v97
	v_pk_mul_f32 v[100:101], v[118:119], s[8:9] op_sel_hi:[1,0]
	v_pk_mul_f32 v[118:119], v[92:93], s[8:9] op_sel_hi:[1,0]
	v_cvt_f32_i32_e32 v93, v103
	v_cvt_f32_i32_e32 v92, v102
	v_cvt_f32_i32_e32 v103, v95
	v_cvt_f32_i32_e32 v96, v96
	v_cvt_f32_i32_e32 v102, v94
	v_cvt_f32_i32_e32 v77, v77
	v_cvt_f32_i32_e32 v76, v76
	v_pk_mul_f32 v[94:95], v[96:97], s[8:9] op_sel_hi:[1,0]
	v_pk_mul_f32 v[96:97], v[102:103], s[8:9] op_sel_hi:[1,0]
	v_cvt_f32_i32_e32 v103, v83
	v_cvt_f32_i32_e32 v102, v82
	v_cvt_f32_i32_e32 v83, v85
	v_cvt_f32_i32_e32 v82, v84
	v_cvt_f32_i32_e32 v81, v81
	v_pk_mul_f32 v[84:85], v[102:103], s[8:9] op_sel_hi:[1,0]
	v_pk_mul_f32 v[102:103], v[76:77], s[8:9] op_sel_hi:[1,0]
	v_cvt_f32_i32_e32 v77, v87
	v_cvt_f32_i32_e32 v76, v86
	v_cvt_f32_i32_e32 v87, v79
	v_cvt_f32_i32_e32 v80, v80
	v_cvt_f32_i32_e32 v86, v78
	v_cvt_f32_i32_e32 v73, v73
	v_cvt_f32_i32_e32 v72, v72
;     __device__ __forceinline__ void operator()(const f32x4 (&acc)[2][2][4][2], const Unit& u, int wr, int wc, int fr, int fq) const {
;     ...
;                 for (int bj = 0; bj < 2; ++bj) { f32x4 v0 = acc[ai][bj][m][0], v1 = acc[ai][bj][m][1];
;                     if (I8_) { v0 = __builtin_convertvector(__builtin_bit_cast(i32x4, v0), f32x4) * I8_DEQ; v1 = __builtin_convertvector(__builtin_bit_cast(i32x4, v1), f32x4) * I8_DEQ; }
	v_pk_mul_f32 v[78:79], v[80:81], s[8:9] op_sel_hi:[1,0]
	v_pk_mul_f32 v[80:81], v[86:87], s[8:9] op_sel_hi:[1,0]
	v_cvt_f32_i32_e32 v87, v67
	v_cvt_f32_i32_e32 v86, v66
	v_pk_mul_f32 v[66:67], v[72:73], s[8:9] op_sel_hi:[1,0]
	v_cvt_f32_i32_e32 v65, v65
	v_cvt_f32_i32_e32 v64, v64
	v_pk_mul_f32 v[72:73], v[86:87], s[8:9] op_sel_hi:[1,0]
	v_cvt_f32_i32_e32 v87, v59
	v_cvt_f32_i32_e32 v86, v58
	v_pk_mul_f32 v[58:59], v[64:65], s[8:9] op_sel_hi:[1,0]
	v_cvt_f32_i32_e32 v45, v45
	v_cvt_f32_i32_e32 v44, v44
	v_pk_mul_f32 v[64:65], v[86:87], s[8:9] op_sel_hi:[1,0]
	v_cvt_f32_i32_e32 v87, v51
	v_cvt_f32_i32_e32 v86, v50
	v_cvt_f32_i32_e32 v51, v53
	v_cvt_f32_i32_e32 v50, v52
	v_cvt_f32_i32_e32 v49, v49
	v_pk_mul_f32 v[52:53], v[86:87], s[8:9] op_sel_hi:[1,0]
	v_pk_mul_f32 v[86:87], v[44:45], s[8:9] op_sel_hi:[1,0]
	v_cvt_f32_i32_e32 v45, v55
	v_cvt_f32_i32_e32 v44, v54
	v_cvt_f32_i32_e32 v55, v47
	v_cvt_f32_i32_e32 v48, v48
	v_cvt_f32_i32_e32 v54, v46
	v_cvt_f32_i32_e32 v29, v29
	v_cvt_f32_i32_e32 v28, v28
	v_pk_mul_f32 v[46:47], v[48:49], s[8:9] op_sel_hi:[1,0]
	v_pk_mul_f32 v[48:49], v[54:55], s[8:9] op_sel_hi:[1,0]
	v_cvt_f32_i32_e32 v55, v35
	v_cvt_f32_i32_e32 v54, v34
	v_cvt_f32_i32_e32 v127, v127
	v_cvt_f32_i32_e32 v126, v126
	v_cvt_f32_i32_e32 v137, v125
	v_cvt_f32_i32_e32 v136, v124
	v_cvt_f32_i32_e32 v107, v107
	v_cvt_f32_i32_e32 v106, v106
	v_cvt_f32_i32_e32 v91, v91
	v_cvt_f32_i32_e32 v90, v90
	v_cvt_f32_i32_e32 v75, v75
	v_cvt_f32_i32_e32 v74, v74
	v_cvt_f32_i32_e32 v35, v37
	v_cvt_f32_i32_e32 v34, v36
	v_pk_mul_f32 v[36:37], v[54:55], s[8:9] op_sel_hi:[1,0]
	v_pk_mul_f32 v[54:55], v[28:29], s[8:9] op_sel_hi:[1,0]
	v_cvt_f32_i32_e32 v29, v39
	v_cvt_f32_i32_e32 v28, v38
	v_cvt_f32_i32_e32 v39, v31
	v_cvt_f32_i32_e32 v33, v33
	v_cvt_f32_i32_e32 v32, v32
	v_cvt_f32_i32_e32 v38, v30
	v_pk_mul_f32 v[124:125], v[126:127], s[8:9] op_sel_hi:[1,0]
	v_pk_mul_f32 v[126:127], v[136:137], s[8:9] op_sel_hi:[1,0]
	v_pk_mul_f32 v[136:137], v[106:107], s[8:9] op_sel_hi:[1,0]
	v_cvt_f32_i32_e32 v107, v121
	v_cvt_f32_i32_e32 v106, v120
	v_pk_mul_f32 v[120:121], v[90:91], s[8:9] op_sel_hi:[1,0]
	v_cvt_f32_i32_e32 v91, v105
	v_cvt_f32_i32_e32 v90, v104
	v_pk_mul_f32 v[104:105], v[74:75], s[8:9] op_sel_hi:[1,0]
	v_cvt_f32_i32_e32 v75, v89
	v_cvt_f32_i32_e32 v74, v88
	v_cvt_f32_i32_e32 v71, v71
	v_cvt_f32_i32_e32 v70, v70
	v_cvt_f32_i32_e32 v89, v69
	v_cvt_f32_i32_e32 v88, v68
	v_pk_mul_f32 v[30:31], v[32:33], s[8:9] op_sel_hi:[1,0]
	v_pk_mul_f32 v[32:33], v[38:39], s[8:9] op_sel_hi:[1,0]
	v_cvt_f32_i32_e32 v39, v19
	v_cvt_f32_i32_e32 v38, v18
	v_cvt_f32_i32_e32 v13, v13
	v_cvt_f32_i32_e32 v12, v12
	v_pk_mul_f32 v[68:69], v[70:71], s[8:9] op_sel_hi:[1,0]
	v_pk_mul_f32 v[70:71], v[88:89], s[8:9] op_sel_hi:[1,0]
	v_cvt_f32_i32_e32 v63, v63
	v_cvt_f32_i32_e32 v62, v62
	v_cvt_f32_i32_e32 v89, v61
	v_cvt_f32_i32_e32 v88, v60
	v_cvt_f32_i32_e32 v43, v43
	v_cvt_f32_i32_e32 v42, v42
	v_cvt_f32_i32_e32 v27, v27
	v_cvt_f32_i32_e32 v26, v26
	v_cvt_f32_i32_e32 v19, v21
	v_cvt_f32_i32_e32 v18, v20
	v_cvt_f32_i32_e32 v11, v11
	v_cvt_f32_i32_e32 v10, v10
	v_pk_mul_f32 v[20:21], v[38:39], s[8:9] op_sel_hi:[1,0]
	v_pk_mul_f32 v[38:39], v[12:13], s[8:9] op_sel_hi:[1,0]
	v_cvt_f32_i32_e32 v13, v23
	v_cvt_f32_i32_e32 v12, v22
	v_cvt_f32_i32_e32 v23, v15
	v_cvt_f32_i32_e32 v17, v17
	v_cvt_f32_i32_e32 v16, v16
	v_cvt_f32_i32_e32 v22, v14
	v_pk_mul_f32 v[60:61], v[62:63], s[8:9] op_sel_hi:[1,0]
	v_pk_mul_f32 v[62:63], v[88:89], s[8:9] op_sel_hi:[1,0]
	v_pk_mul_f32 v[88:89], v[42:43], s[8:9] op_sel_hi:[1,0]
	v_cvt_f32_i32_e32 v43, v57
	v_cvt_f32_i32_e32 v42, v56
	v_pk_mul_f32 v[56:57], v[26:27], s[8:9] op_sel_hi:[1,0]
	v_cvt_f32_i32_e32 v27, v41
	v_cvt_f32_i32_e32 v26, v40
	v_pk_mul_f32 v[40:41], v[10:11], s[8:9] op_sel_hi:[1,0]
	v_cvt_f32_i32_e32 v11, v25
	v_cvt_f32_i32_e32 v10, v24
	v_pk_mul_f32 v[14:15], v[16:17], s[8:9] op_sel_hi:[1,0]
	v_pk_mul_f32 v[16:17], v[22:23], s[8:9] op_sel_hi:[1,0]
	v_cvt_f32_i32_e32 v7, v7
	v_cvt_f32_i32_e32 v6, v6
	v_cvt_f32_i32_e32 v9, v9
	v_cvt_f32_i32_e32 v8, v8
	v_cvt_f32_i32_e32 v23, v3
	v_cvt_f32_i32_e32 v25, v5
	v_cvt_f32_i32_e32 v24, v4
	v_cvt_f32_i32_e32 v22, v2
	v_pk_mul_f32 v[114:115], v[114:115], s[8:9] op_sel_hi:[1,0]
	v_pk_mul_f32 v[106:107], v[106:107], s[8:9] op_sel_hi:[1,0]
	v_pk_mul_f32 v[108:109], v[108:109], s[8:9] op_sel_hi:[1,0]
	v_pk_mul_f32 v[98:99], v[98:99], s[8:9] op_sel_hi:[1,0]
	v_pk_mul_f32 v[90:91], v[90:91], s[8:9] op_sel_hi:[1,0]
	v_pk_mul_f32 v[92:93], v[92:93], s[8:9] op_sel_hi:[1,0]
	v_pk_mul_f32 v[82:83], v[82:83], s[8:9] op_sel_hi:[1,0]
	v_pk_mul_f32 v[74:75], v[74:75], s[8:9] op_sel_hi:[1,0]
	v_pk_mul_f32 v[76:77], v[76:77], s[8:9] op_sel_hi:[1,0]
	v_pk_mul_f32 v[50:51], v[50:51], s[8:9] op_sel_hi:[1,0]
	v_pk_mul_f32 v[42:43], v[42:43], s[8:9] op_sel_hi:[1,0]
	v_pk_mul_f32 v[44:45], v[44:45], s[8:9] op_sel_hi:[1,0]
	v_pk_mul_f32 v[34:35], v[34:35], s[8:9] op_sel_hi:[1,0]
	v_pk_mul_f32 v[26:27], v[26:27], s[8:9] op_sel_hi:[1,0]
	v_pk_mul_f32 v[28:29], v[28:29], s[8:9] op_sel_hi:[1,0]
	v_pk_mul_f32 v[18:19], v[18:19], s[8:9] op_sel_hi:[1,0]
	v_pk_mul_f32 v[10:11], v[10:11], s[8:9] op_sel_hi:[1,0]
	v_pk_mul_f32 v[12:13], v[12:13], s[8:9] op_sel_hi:[1,0]
	v_pk_mul_f32 v[2:3], v[8:9], s[8:9] op_sel_hi:[1,0]
	v_pk_mul_f32 v[4:5], v[6:7], s[8:9] op_sel_hi:[1,0]
	v_pk_mul_f32 v[6:7], v[24:25], s[8:9] op_sel_hi:[1,0]
	v_pk_mul_f32 v[8:9], v[22:23], s[8:9] op_sel_hi:[1,0]
	s_and_b64 vcc, exec, s[4:5]
	s_cbranch_vccz .LBB0_409

; #define PG8_STAGE(bufoff, gbase, X) do { _Pragma("unroll") for (int _i = 0; _i < 2; ++_i) { \
;         const char* gp_ = (const char*)(gbase) + (_i ? rs##X : (size_t)0); const unsigned la_ = (unsigned)(size_t)(lds + (bufoff) + ldsw + _i * 8192); \
;         asm volatile("s_mov_b32 m0, %2\n\ts_nop 0\n\tglobal_load_lds_dwordx4 %0, %1" :: "v"(voff##X), "s"(gp_), "s"(la_) : "memory", "m0"); } } while (0)
; #define PG8_LDA(dst, b, h) do { _Pragma("unroll") for (int m = 0; m < 4; ++m) _Pragma("unroll") for (int k = 0; k < 2; ++k) dst[m][k] = *(const LAS bf16x8*)(lds + PG8_SA(b, h) + aoff + m * 2048 + k * 1024); } while (0)
; #define PG8_LDB(dst, b, h) do { _Pragma("unroll") for (int n = 0; n < 2; ++n) _Pragma("unroll") for (int k = 0; k < 2; ++k) dst[n][k] = *(const LAS bf16x8*)(lds + PG8_SB(b, h) + boff + n * 2048 + k * 1024); } while (0)
; #define PG8_WAIT_V(n) asm volatile("s_waitcnt vmcnt(" #n ")" ::: "memory")
; #define PG8_WAIT_L(n) asm volatile("s_waitcnt lgkmcnt(" #n ")" ::: "memory")
; #define PG8_BAR __builtin_amdgcn_s_barrier()
; #define PG8_SCHED __builtin_amdgcn_sched_barrier(0)
; template <class Epi>
; __device__ __forceinline__ void gemm_phase(LAS unsigned char* lds, const Gemm g_in, const StaticOrder& S, const Epi& E) {
;     ...
;         for (int t = 0; t < nt; t += 2) {
;             const bool last = (t == nt - 2);
;             const char* a1 = cA + (size_t)(t + 1) * kstep;
;             const char* a2 = last ? nA : cA + (size_t)(t + 2) * kstep; const char* b2 = last ? nB : cB + (size_t)(t + 2) * kstep;
;             const char* a3 = a2 + kstep; const char* b3 = b2 + kstep;
;             PG8_LDB(B0, 0, 0); PG8_LDB(B1, 0, 1); PG8_SCHED; PG8_LDA(At, 0, 0); PG8_STAGE(PG8_SA(1, 1), a1 + hsA, A);
;             PG8_WAIT_V(8); PG8_WAIT_L(0); PG8_BAR; PG8_MMA(0, 0, At, B0); PG8_MMA(0, 1, At, B1); PG8_BAR; PG8_SCHED;
;             PG8_LDA(At, 0, 1); PG8_STAGE(PG8_SB(0, 0), b2, B); PG8_STAGE(PG8_SB(0, 1), b2 + hsB, B); PG8_STAGE(PG8_SA(0, 0), a2, A);
;             PG8_WAIT_V(8); PG8_WAIT_L(0); PG8_BAR; PG8_MMA(1, 0, At, B0); PG8_MMA(1, 1, At, B1); PG8_BAR; PG8_SCHED;
.LBB0_751:
	ds_read_b128 v[130:133], v157
	ds_read_b128 v[134:137], v157 offset:1024
	ds_read_b128 v[142:145], v157 offset:2048
	ds_read_b128 v[146:149], v157 offset:3072
	ds_read_b128 v[168:171], v158
	ds_read_b128 v[172:175], v158 offset:1024
	ds_read_b128 v[184:187], v158 offset:2048
	ds_read_b128 v[188:191], v158 offset:3072
	s_add_i32 s62, s24, 2
	s_add_u32 s26, s22, 0xfffa0080
	s_addc_u32 s25, s23, -1
	s_cmp_eq_u32 s55, s24
	s_cselect_b32 s24, s11, s26
	s_cselect_b32 s25, s1, s25
	s_cselect_b32 s28, s59, s60
	s_cselect_b32 s29, s58, s61
	s_add_u32 s26, s24, 0x80
	s_addc_u32 s27, s25, 0
	ds_read_b128 v[192:195], v159
	ds_read_b128 v[196:199], v159 offset:1024
	ds_read_b128 v[204:207], v159 offset:2048
	ds_read_b128 v[208:211], v159 offset:3072
	ds_read_b128 v[212:215], v159 offset:4096
	ds_read_b128 v[216:219], v159 offset:5120
	ds_read_b128 v[220:223], v159 offset:6144
	ds_read_b128 v[224:227], v159 offset:7168
	s_add_u32 s64, s22, 0xfffe0000
	s_addc_u32 s65, s23, -1
	s_mov_b32 m0, s56
	s_nop 0
	global_load_lds_dwordx4 v1, s[64:65]
	s_nop 0
	s_mov_b32 m0, s57
	s_nop 0
	global_load_lds_dwordx4 v1, s[22:23]
	s_waitcnt vmcnt(8)
	s_waitcnt lgkmcnt(0)
	s_barrier
	s_setprio 1
	s_waitcnt lgkmcnt(7)
	v_mfma_f32_16x16x32_bf16 v[126:129], v[130:133], v[192:195], v[126:129]
	v_mfma_f32_16x16x32_bf16 v[122:125], v[142:145], v[192:195], v[122:125]
	s_waitcnt lgkmcnt(5)
	v_mfma_f32_16x16x32_bf16 v[118:121], v[130:133], v[204:207], v[118:121]
	v_mfma_f32_16x16x32_bf16 v[114:117], v[142:145], v[204:207], v[114:117]
	s_waitcnt lgkmcnt(3)
	v_mfma_f32_16x16x32_bf16 v[110:113], v[130:133], v[212:215], v[110:113]
	v_mfma_f32_16x16x32_bf16 v[106:109], v[142:145], v[212:215], v[106:109]
	s_waitcnt lgkmcnt(1)
	v_mfma_f32_16x16x32_bf16 v[102:105], v[130:133], v[220:223], v[102:105]
	v_mfma_f32_16x16x32_bf16 v[94:97], v[142:145], v[220:223], v[94:97]
	v_mfma_f32_16x16x32_bf16 v[126:129], v[134:137], v[196:199], v[126:129]
	v_mfma_f32_16x16x32_bf16 v[122:125], v[146:149], v[196:199], v[122:125]
	v_mfma_f32_16x16x32_bf16 v[118:121], v[134:137], v[208:211], v[118:121]
	v_mfma_f32_16x16x32_bf16 v[114:117], v[146:149], v[208:211], v[114:117]
	v_mfma_f32_16x16x32_bf16 v[110:113], v[134:137], v[216:219], v[110:113]
	v_mfma_f32_16x16x32_bf16 v[106:109], v[146:149], v[216:219], v[106:109]
	s_waitcnt lgkmcnt(0)
	v_mfma_f32_16x16x32_bf16 v[102:105], v[134:137], v[224:227], v[102:105]
	v_mfma_f32_16x16x32_bf16 v[94:97], v[146:149], v[224:227], v[94:97]
	s_setprio 0
	s_setprio 1
	v_mfma_f32_16x16x32_bf16 v[62:65], v[168:171], v[192:195], v[62:65]
	v_mfma_f32_16x16x32_bf16 v[58:61], v[184:187], v[192:195], v[58:61]
	v_mfma_f32_16x16x32_bf16 v[54:57], v[168:171], v[204:207], v[54:57]
	v_mfma_f32_16x16x32_bf16 v[50:53], v[184:187], v[204:207], v[50:53]
	v_mfma_f32_16x16x32_bf16 v[46:49], v[168:171], v[212:215], v[46:49]
	v_mfma_f32_16x16x32_bf16 v[42:45], v[184:187], v[212:215], v[42:45]
	v_mfma_f32_16x16x32_bf16 v[38:41], v[168:171], v[220:223], v[38:41]
	v_mfma_f32_16x16x32_bf16 v[34:37], v[184:187], v[220:223], v[34:37]
	v_mfma_f32_16x16x32_bf16 v[62:65], v[172:175], v[196:199], v[62:65]
	v_mfma_f32_16x16x32_bf16 v[58:61], v[188:191], v[196:199], v[58:61]
	v_mfma_f32_16x16x32_bf16 v[54:57], v[172:175], v[208:211], v[54:57]
	v_mfma_f32_16x16x32_bf16 v[50:53], v[188:191], v[208:211], v[50:53]
	s_add_u32 s64, s28, 0x8000
	v_mfma_f32_16x16x32_bf16 v[46:49], v[172:175], v[216:219], v[46:49]
	v_mfma_f32_16x16x32_bf16 v[42:45], v[188:191], v[216:219], v[42:45]
	v_mfma_f32_16x16x32_bf16 v[38:41], v[172:175], v[224:227], v[38:41]
	v_mfma_f32_16x16x32_bf16 v[34:37], v[188:191], v[224:227], v[34:37]
	s_setprio 0
	s_barrier
	ds_read_b128 v[192:195], v159 offset:16384
	ds_read_b128 v[196:199], v159 offset:17408
	ds_read_b128 v[204:207], v159 offset:18432
	ds_read_b128 v[208:211], v159 offset:19456
	ds_read_b128 v[212:215], v159 offset:20480
	ds_read_b128 v[216:219], v159 offset:21504
	ds_read_b128 v[220:223], v159 offset:22528
	ds_read_b128 v[224:227], v159 offset:23552
	s_mov_b32 m0, s42
	s_nop 0
	global_load_lds_dwordx4 v154, s[28:29]
	s_addc_u32 s65, s29, 0
	s_mov_b32 m0, s43
	s_nop 0
	global_load_lds_dwordx4 v154, s[64:65]
	s_add_u32 s64, s28, 0x10000
	s_addc_u32 s65, s29, 0
	s_mov_b32 m0, s44
	s_nop 0
	global_load_lds_dwordx4 v154, s[64:65]
	s_add_u32 s64, s28, 0x18000
	s_addc_u32 s65, s29, 0
	s_mov_b32 m0, s45
	s_nop 0
	global_load_lds_dwordx4 v154, s[64:65]
	s_add_u32 s64, s24, 0x20000
	s_mov_b32 m0, s41
	s_nop 0
	global_load_lds_dwordx4 v1, s[24:25]
	s_addc_u32 s65, s25, 0
	s_mov_b32 m0, s46
	s_nop 0
	global_load_lds_dwordx4 v1, s[64:65]
	s_waitcnt vmcnt(8)
	s_waitcnt lgkmcnt(0)
	s_barrier
; #define PG8_STAGE(bufoff, gbase, X) do { _Pragma("unroll") for (int _i = 0; _i < 2; ++_i) { \
;         const char* gp_ = (const char*)(gbase) + (_i ? rs##X : (size_t)0); const unsigned la_ = (unsigned)(size_t)(lds + (bufoff) + ldsw + _i * 8192); \
;         asm volatile("s_mov_b32 m0, %2\n\ts_nop 0\n\tglobal_load_lds_dwordx4 %0, %1" :: "v"(voff##X), "s"(gp_), "s"(la_) : "memory", "m0"); } } while (0)
; #define PG8_LDA(dst, b, h) do { _Pragma("unroll") for (int m = 0; m < 4; ++m) _Pragma("unroll") for (int k = 0; k < 2; ++k) dst[m][k] = *(const LAS bf16x8*)(lds + PG8_SA(b, h) + aoff + m * 2048 + k * 1024); } while (0)
; #define PG8_LDB(dst, b, h) do { _Pragma("unroll") for (int n = 0; n < 2; ++n) _Pragma("unroll") for (int k = 0; k < 2; ++k) dst[n][k] = *(const LAS bf16x8*)(lds + PG8_SB(b, h) + boff + n * 2048 + k * 1024); } while (0)
; #define PG8_WAIT_V(n) asm volatile("s_waitcnt vmcnt(" #n ")" ::: "memory")
; #define PG8_WAIT_L(n) asm volatile("s_waitcnt lgkmcnt(" #n ")" ::: "memory")
; #define PG8_BAR __builtin_amdgcn_s_barrier()
; #define PG8_SCHED __builtin_amdgcn_sched_barrier(0)
; template <class Epi>
; __device__ __forceinline__ void gemm_phase(LAS unsigned char* lds, const Gemm g_in, const StaticOrder& S, const Epi& E) {
;     ...
;             PG8_WAIT_V(8); PG8_WAIT_L(0); PG8_BAR; PG8_MMA(1, 0, At, B0); PG8_MMA(1, 1, At, B1); PG8_BAR; PG8_SCHED;
;             PG8_LDB(B0, 1, 0); PG8_LDB(B1, 1, 1); PG8_SCHED; PG8_LDA(At, 1, 0); PG8_STAGE(PG8_SA(0, 1), a2 + hsA, A);
;             PG8_WAIT_V(8); PG8_WAIT_L(0); PG8_BAR; PG8_MMA(0, 0, At, B0); PG8_MMA(0, 1, At, B1); PG8_BAR; PG8_SCHED;
	s_setprio 1
	s_waitcnt lgkmcnt(7)
	v_mfma_f32_16x16x32_bf16 v[98:101], v[130:133], v[192:195], v[98:101]
	v_mfma_f32_16x16x32_bf16 v[90:93], v[142:145], v[192:195], v[90:93]
	s_waitcnt lgkmcnt(5)
	v_mfma_f32_16x16x32_bf16 v[86:89], v[130:133], v[204:207], v[86:89]
	v_mfma_f32_16x16x32_bf16 v[82:85], v[142:145], v[204:207], v[82:85]
	s_waitcnt lgkmcnt(3)
	v_mfma_f32_16x16x32_bf16 v[78:81], v[130:133], v[212:215], v[78:81]
	v_mfma_f32_16x16x32_bf16 v[74:77], v[142:145], v[212:215], v[74:77]
	s_waitcnt lgkmcnt(1)
	v_mfma_f32_16x16x32_bf16 v[70:73], v[130:133], v[220:223], v[70:73]
	v_mfma_f32_16x16x32_bf16 v[66:69], v[142:145], v[220:223], v[66:69]
	v_mfma_f32_16x16x32_bf16 v[98:101], v[134:137], v[196:199], v[98:101]
	v_mfma_f32_16x16x32_bf16 v[90:93], v[146:149], v[196:199], v[90:93]
	v_mfma_f32_16x16x32_bf16 v[86:89], v[134:137], v[208:211], v[86:89]
	v_mfma_f32_16x16x32_bf16 v[82:85], v[146:149], v[208:211], v[82:85]
	v_mfma_f32_16x16x32_bf16 v[78:81], v[134:137], v[216:219], v[78:81]
	v_mfma_f32_16x16x32_bf16 v[74:77], v[146:149], v[216:219], v[74:77]
	s_waitcnt lgkmcnt(0)
	v_mfma_f32_16x16x32_bf16 v[70:73], v[134:137], v[224:227], v[70:73]
	v_mfma_f32_16x16x32_bf16 v[66:69], v[146:149], v[224:227], v[66:69]
	s_setprio 0
	s_setprio 1
	v_mfma_f32_16x16x32_bf16 v[30:33], v[168:171], v[192:195], v[30:33]
	v_mfma_f32_16x16x32_bf16 v[26:29], v[184:187], v[192:195], v[26:29]
	v_mfma_f32_16x16x32_bf16 v[22:25], v[168:171], v[204:207], v[22:25]
	v_mfma_f32_16x16x32_bf16 v[18:21], v[184:187], v[204:207], v[18:21]
	v_mfma_f32_16x16x32_bf16 v[14:17], v[168:171], v[212:215], v[14:17]
	v_mfma_f32_16x16x32_bf16 v[10:13], v[184:187], v[212:215], v[10:13]
	v_mfma_f32_16x16x32_bf16 v[6:9], v[168:171], v[220:223], v[6:9]
	v_mfma_f32_16x16x32_bf16 v[2:5], v[184:187], v[220:223], v[2:5]
	v_mfma_f32_16x16x32_bf16 v[30:33], v[172:175], v[196:199], v[30:33]
	v_mfma_f32_16x16x32_bf16 v[26:29], v[188:191], v[196:199], v[26:29]
	v_mfma_f32_16x16x32_bf16 v[22:25], v[172:175], v[208:211], v[22:25]
	v_mfma_f32_16x16x32_bf16 v[18:21], v[188:191], v[208:211], v[18:21]
	v_mfma_f32_16x16x32_bf16 v[14:17], v[172:175], v[216:219], v[14:17]
	v_mfma_f32_16x16x32_bf16 v[10:13], v[188:191], v[216:219], v[10:13]
	v_mfma_f32_16x16x32_bf16 v[6:9], v[172:175], v[224:227], v[6:9]
	v_mfma_f32_16x16x32_bf16 v[2:5], v[188:191], v[224:227], v[2:5]
	s_setprio 0
	s_barrier
	ds_read_b128 v[130:133], v160
	ds_read_b128 v[134:137], v160 offset:1024
	ds_read_b128 v[142:145], v160 offset:2048
	ds_read_b128 v[146:149], v160 offset:3072
	ds_read_b128 v[168:171], v161
	ds_read_b128 v[172:175], v161 offset:1024
	ds_read_b128 v[184:187], v161 offset:2048
	ds_read_b128 v[188:191], v161 offset:3072
	ds_read_b128 v[192:195], v159 offset:32768
	ds_read_b128 v[196:199], v159 offset:33792
	ds_read_b128 v[204:207], v159 offset:34816
	ds_read_b128 v[208:211], v159 offset:35840
	ds_read_b128 v[212:215], v159 offset:36864
	ds_read_b128 v[216:219], v159 offset:37888
	ds_read_b128 v[220:223], v159 offset:38912
	ds_read_b128 v[224:227], v159 offset:39936
	s_add_u32 s64, s24, 0x40000
	s_addc_u32 s65, s25, 0
	s_mov_b32 m0, s47
	s_nop 0
	global_load_lds_dwordx4 v1, s[64:65]
	s_add_u32 s64, s24, 0x60000
	s_addc_u32 s65, s25, 0
	s_mov_b32 m0, s48
	s_nop 0
	global_load_lds_dwordx4 v1, s[64:65]
	s_waitcnt vmcnt(8)
	s_waitcnt lgkmcnt(0)
	s_barrier
	s_setprio 1
	s_waitcnt lgkmcnt(7)
	v_mfma_f32_16x16x32_bf16 v[126:129], v[130:133], v[192:195], v[126:129]
	v_mfma_f32_16x16x32_bf16 v[122:125], v[142:145], v[192:195], v[122:125]
	s_waitcnt lgkmcnt(5)
	v_mfma_f32_16x16x32_bf16 v[118:121], v[130:133], v[204:207], v[118:121]
	v_mfma_f32_16x16x32_bf16 v[114:117], v[142:145], v[204:207], v[114:117]
	s_waitcnt lgkmcnt(3)
	v_mfma_f32_16x16x32_bf16 v[110:113], v[130:133], v[212:215], v[110:113]
	v_mfma_f32_16x16x32_bf16 v[106:109], v[142:145], v[212:215], v[106:109]
	s_waitcnt lgkmcnt(1)
	v_mfma_f32_16x16x32_bf16 v[102:105], v[130:133], v[220:223], v[102:105]
	v_mfma_f32_16x16x32_bf16 v[94:97], v[142:145], v[220:223], v[94:97]
	v_mfma_f32_16x16x32_bf16 v[126:129], v[134:137], v[196:199], v[126:129]
	v_mfma_f32_16x16x32_bf16 v[122:125], v[146:149], v[196:199], v[122:125]
	v_mfma_f32_16x16x32_bf16 v[118:121], v[134:137], v[208:211], v[118:121]
	v_mfma_f32_16x16x32_bf16 v[114:117], v[146:149], v[208:211], v[114:117]
	v_mfma_f32_16x16x32_bf16 v[110:113], v[134:137], v[216:219], v[110:113]
	v_mfma_f32_16x16x32_bf16 v[106:109], v[146:149], v[216:219], v[106:109]
	s_waitcnt lgkmcnt(0)
	v_mfma_f32_16x16x32_bf16 v[102:105], v[134:137], v[224:227], v[102:105]
	v_mfma_f32_16x16x32_bf16 v[94:97], v[146:149], v[224:227], v[94:97]
	s_setprio 0
	s_setprio 1
	v_mfma_f32_16x16x32_bf16 v[62:65], v[168:171], v[192:195], v[62:65]
	v_mfma_f32_16x16x32_bf16 v[58:61], v[184:187], v[192:195], v[58:61]
	v_mfma_f32_16x16x32_bf16 v[54:57], v[168:171], v[204:207], v[54:57]
	v_mfma_f32_16x16x32_bf16 v[50:53], v[184:187], v[204:207], v[50:53]
	v_mfma_f32_16x16x32_bf16 v[46:49], v[168:171], v[212:215], v[46:49]
	v_mfma_f32_16x16x32_bf16 v[42:45], v[184:187], v[212:215], v[42:45]
	v_mfma_f32_16x16x32_bf16 v[38:41], v[168:171], v[220:223], v[38:41]
	v_mfma_f32_16x16x32_bf16 v[34:37], v[184:187], v[220:223], v[34:37]
	v_mfma_f32_16x16x32_bf16 v[62:65], v[172:175], v[196:199], v[62:65]
	v_mfma_f32_16x16x32_bf16 v[58:61], v[188:191], v[196:199], v[58:61]
	v_mfma_f32_16x16x32_bf16 v[54:57], v[172:175], v[208:211], v[54:57]
	v_mfma_f32_16x16x32_bf16 v[50:53], v[188:191], v[208:211], v[50:53]
	s_add_u32 s64, s28, 0x80
	s_addc_u32 s65, s29, 0
	v_mfma_f32_16x16x32_bf16 v[46:49], v[172:175], v[216:219], v[46:49]
	v_mfma_f32_16x16x32_bf16 v[42:45], v[188:191], v[216:219], v[42:45]
	v_mfma_f32_16x16x32_bf16 v[38:41], v[172:175], v[224:227], v[38:41]
	v_mfma_f32_16x16x32_bf16 v[34:37], v[188:191], v[224:227], v[34:37]
	s_setprio 0
	s_barrier
; #define PG8_STAGE(bufoff, gbase, X) do { _Pragma("unroll") for (int _i = 0; _i < 2; ++_i) { \
;         const char* gp_ = (const char*)(gbase) + (_i ? rs##X : (size_t)0); const unsigned la_ = (unsigned)(size_t)(lds + (bufoff) + ldsw + _i * 8192); \
;         asm volatile("s_mov_b32 m0, %2\n\ts_nop 0\n\tglobal_load_lds_dwordx4 %0, %1" :: "v"(voff##X), "s"(gp_), "s"(la_) : "memory", "m0"); } } while (0)
; #define PG8_LDA(dst, b, h) do { _Pragma("unroll") for (int m = 0; m < 4; ++m) _Pragma("unroll") for (int k = 0; k < 2; ++k) dst[m][k] = *(const LAS bf16x8*)(lds + PG8_SA(b, h) + aoff + m * 2048 + k * 1024); } while (0)
; #define PG8_WAIT_V(n) asm volatile("s_waitcnt vmcnt(" #n ")" ::: "memory")
; #define PG8_WAIT_L(n) asm volatile("s_waitcnt lgkmcnt(" #n ")" ::: "memory")
; #define PG8_BAR __builtin_amdgcn_s_barrier()
; #define PG8_SCHED __builtin_amdgcn_sched_barrier(0)
; template <class Epi>
; __device__ __forceinline__ void gemm_phase(LAS unsigned char* lds, const Gemm g_in, const StaticOrder& S, const Epi& E) {
;     ...
;             PG8_LDA(At, 1, 1); PG8_STAGE(PG8_SB(1, 0), b3, B); PG8_STAGE(PG8_SB(1, 1), b3 + hsB, B); PG8_STAGE(PG8_SA(1, 0), a3, A);
;             PG8_WAIT_V(8); PG8_WAIT_L(0); PG8_BAR; PG8_MMA(1, 0, At, B0); PG8_MMA(1, 1, At, B1); PG8_BAR; PG8_SCHED;
;         }
	ds_read_b128 v[192:195], v159 offset:49152
	ds_read_b128 v[196:199], v159 offset:50176
	ds_read_b128 v[204:207], v159 offset:51200
	ds_read_b128 v[208:211], v159 offset:52224
	ds_read_b128 v[212:215], v159 offset:53248
	ds_read_b128 v[216:219], v159 offset:54272
	ds_read_b128 v[220:223], v159 offset:55296
	ds_read_b128 v[224:227], v159 offset:56320
	s_mov_b32 m0, s49
	s_nop 0
	global_load_lds_dwordx4 v154, s[64:65]
	s_add_u32 s64, s28, 0x8080
	s_addc_u32 s65, s29, 0
	s_mov_b32 m0, s50
	s_nop 0
	global_load_lds_dwordx4 v154, s[64:65]
	s_add_u32 s64, s28, 0x10080
	s_addc_u32 s65, s29, 0
	s_mov_b32 m0, s53
	s_nop 0
	global_load_lds_dwordx4 v154, s[64:65]
	s_add_u32 s28, s28, 0x18080
	s_addc_u32 s29, s29, 0
	s_mov_b32 m0, s54
	s_nop 0
	global_load_lds_dwordx4 v154, s[28:29]
	s_add_u32 s24, s24, 0x20080
	s_mov_b32 m0, s51
	s_nop 0
	global_load_lds_dwordx4 v1, s[26:27]
	s_addc_u32 s25, s25, 0
	s_mov_b32 m0, s52
	s_nop 0
	global_load_lds_dwordx4 v1, s[24:25]
	s_waitcnt vmcnt(8)
	s_waitcnt lgkmcnt(0)
	s_barrier
	s_setprio 1
	s_waitcnt lgkmcnt(7)
	v_mfma_f32_16x16x32_bf16 v[98:101], v[130:133], v[192:195], v[98:101]
	v_mfma_f32_16x16x32_bf16 v[90:93], v[142:145], v[192:195], v[90:93]
	s_waitcnt lgkmcnt(5)
	v_mfma_f32_16x16x32_bf16 v[86:89], v[130:133], v[204:207], v[86:89]
	v_mfma_f32_16x16x32_bf16 v[82:85], v[142:145], v[204:207], v[82:85]
	s_waitcnt lgkmcnt(3)
	v_mfma_f32_16x16x32_bf16 v[78:81], v[130:133], v[212:215], v[78:81]
	v_mfma_f32_16x16x32_bf16 v[74:77], v[142:145], v[212:215], v[74:77]
	s_waitcnt lgkmcnt(1)
	v_mfma_f32_16x16x32_bf16 v[70:73], v[130:133], v[220:223], v[70:73]
	v_mfma_f32_16x16x32_bf16 v[66:69], v[142:145], v[220:223], v[66:69]
	v_mfma_f32_16x16x32_bf16 v[98:101], v[134:137], v[196:199], v[98:101]
	v_mfma_f32_16x16x32_bf16 v[90:93], v[146:149], v[196:199], v[90:93]
	v_mfma_f32_16x16x32_bf16 v[86:89], v[134:137], v[208:211], v[86:89]
	v_mfma_f32_16x16x32_bf16 v[82:85], v[146:149], v[208:211], v[82:85]
	v_mfma_f32_16x16x32_bf16 v[78:81], v[134:137], v[216:219], v[78:81]
	v_mfma_f32_16x16x32_bf16 v[74:77], v[146:149], v[216:219], v[74:77]
	s_waitcnt lgkmcnt(0)
	v_mfma_f32_16x16x32_bf16 v[70:73], v[134:137], v[224:227], v[70:73]
	v_mfma_f32_16x16x32_bf16 v[66:69], v[146:149], v[224:227], v[66:69]
	s_setprio 0
	s_setprio 1
	v_mfma_f32_16x16x32_bf16 v[30:33], v[168:171], v[192:195], v[30:33]
	v_mfma_f32_16x16x32_bf16 v[26:29], v[184:187], v[192:195], v[26:29]
	v_mfma_f32_16x16x32_bf16 v[22:25], v[168:171], v[204:207], v[22:25]
	v_mfma_f32_16x16x32_bf16 v[18:21], v[184:187], v[204:207], v[18:21]
	v_mfma_f32_16x16x32_bf16 v[14:17], v[168:171], v[212:215], v[14:17]
	v_mfma_f32_16x16x32_bf16 v[10:13], v[184:187], v[212:215], v[10:13]
	v_mfma_f32_16x16x32_bf16 v[6:9], v[168:171], v[220:223], v[6:9]
	v_mfma_f32_16x16x32_bf16 v[2:5], v[184:187], v[220:223], v[2:5]
	v_mfma_f32_16x16x32_bf16 v[30:33], v[172:175], v[196:199], v[30:33]
	v_mfma_f32_16x16x32_bf16 v[26:29], v[188:191], v[196:199], v[26:29]
	v_mfma_f32_16x16x32_bf16 v[22:25], v[172:175], v[208:211], v[22:25]
	v_mfma_f32_16x16x32_bf16 v[18:21], v[188:191], v[208:211], v[18:21]
	s_add_u32 s60, s60, 0x100
	s_addc_u32 s61, s61, 0
	s_add_u32 s22, s22, 0x100
	s_addc_u32 s23, s23, 0
	s_cmp_ge_i32 s62, s37
	s_mov_b32 s24, s62
	v_mfma_f32_16x16x32_bf16 v[14:17], v[172:175], v[216:219], v[14:17]
	v_mfma_f32_16x16x32_bf16 v[10:13], v[188:191], v[216:219], v[10:13]
	v_mfma_f32_16x16x32_bf16 v[6:9], v[172:175], v[224:227], v[6:9]
	v_mfma_f32_16x16x32_bf16 v[2:5], v[188:191], v[224:227], v[2:5]
	s_setprio 0
	s_barrier
	s_cbranch_scc0 .LBB0_751
	s_and_b64 vcc, exec, s[14:15]
	s_cbranch_vccz .LBB0_754

; #define PG8_STAGE(bufoff, gbase, X) do { _Pragma("unroll") for (int _i = 0; _i < 2; ++_i) { \
;         const char* gp_ = (const char*)(gbase) + (_i ? rs##X : (size_t)0); const unsigned la_ = (unsigned)(size_t)(lds + (bufoff) + ldsw + _i * 8192); \
;         asm volatile("s_mov_b32 m0, %2\n\ts_nop 0\n\tglobal_load_lds_dwordx4 %0, %1" :: "v"(voff##X), "s"(gp_), "s"(la_) : "memory", "m0"); } } while (0)
; #define PG8_LDA(dst, b, h) do { _Pragma("unroll") for (int m = 0; m < 4; ++m) _Pragma("unroll") for (int k = 0; k < 2; ++k) dst[m][k] = *(const LAS bf16x8*)(lds + PG8_SA(b, h) + aoff + m * 2048 + k * 1024); } while (0)
; #define PG8_LDB(dst, b, h) do { _Pragma("unroll") for (int n = 0; n < 2; ++n) _Pragma("unroll") for (int k = 0; k < 2; ++k) dst[n][k] = *(const LAS bf16x8*)(lds + PG8_SB(b, h) + boff + n * 2048 + k * 1024); } while (0)
; #define PG8_WAIT_V(n) asm volatile("s_waitcnt vmcnt(" #n ")" ::: "memory")
; #define PG8_WAIT_L(n) asm volatile("s_waitcnt lgkmcnt(" #n ")" ::: "memory")
; #define PG8_BAR __builtin_amdgcn_s_barrier()
; #define PG8_SCHED __builtin_amdgcn_sched_barrier(0)
; template <class Epi>
; __device__ __forceinline__ void gemm_phase(LAS unsigned char* lds, const Gemm g_in, const StaticOrder& S, const Epi& E) {
;     ...
;         for (int t = 0; t < nt; t += 2) {
;             const bool last = (t == nt - 2);
;             const char* a1 = cA + (size_t)(t + 1) * kstep;
;             const char* a2 = last ? nA : cA + (size_t)(t + 2) * kstep; const char* b2 = last ? nB : cB + (size_t)(t + 2) * kstep;
;             const char* a3 = a2 + kstep; const char* b3 = b2 + kstep;
;             PG8_LDB(B0, 0, 0); PG8_LDB(B1, 0, 1); PG8_SCHED; PG8_LDA(At, 0, 0); PG8_STAGE(PG8_SA(1, 1), a1 + hsA, A);
;             PG8_WAIT_V(8); PG8_WAIT_L(0); PG8_BAR; PG8_MMA(0, 0, At, B0); PG8_MMA(0, 1, At, B1); PG8_BAR; PG8_SCHED;
;             PG8_LDA(At, 0, 1); PG8_STAGE(PG8_SB(0, 0), b2, B); PG8_STAGE(PG8_SB(0, 1), b2 + hsB, B); PG8_STAGE(PG8_SA(0, 0), a2, A);
;             PG8_WAIT_V(8); PG8_WAIT_L(0); PG8_BAR; PG8_MMA(1, 0, At, B0); PG8_MMA(1, 1, At, B1); PG8_BAR; PG8_SCHED;
.LBB0_769:
	ds_read_b128 v[130:133], v147
	ds_read_b128 v[134:137], v147 offset:1024
	ds_read_b128 v[154:157], v147 offset:2048
	ds_read_b128 v[158:161], v147 offset:3072
	ds_read_b128 v[168:171], v148
	ds_read_b128 v[172:175], v148 offset:1024
	ds_read_b128 v[184:187], v148 offset:2048
	ds_read_b128 v[188:191], v148 offset:3072
	s_add_i32 s64, s10, 2
	s_add_u32 s28, s6, 0xfffa0080
	s_addc_u32 s11, s7, -1
	s_cmp_eq_u32 s57, s10
	s_cselect_b32 s10, s23, s28
	s_cselect_b32 s11, s21, s11
	s_cselect_b32 s30, s61, s62
	s_cselect_b32 s31, s60, s63
	s_add_u32 s28, s10, 0x80
	s_addc_u32 s29, s11, 0
	ds_read_b128 v[192:195], v149
	ds_read_b128 v[196:199], v149 offset:1024
	ds_read_b128 v[204:207], v149 offset:2048
	ds_read_b128 v[208:211], v149 offset:3072
	ds_read_b128 v[212:215], v149 offset:4096
	ds_read_b128 v[216:219], v149 offset:5120
	ds_read_b128 v[220:223], v149 offset:6144
	ds_read_b128 v[224:227], v149 offset:7168
	s_add_u32 s66, s6, 0xfffe0000
	s_addc_u32 s67, s7, -1
	s_mov_b32 m0, s58
	s_nop 0
	global_load_lds_dwordx4 v1, s[66:67]
	s_nop 0
	s_mov_b32 m0, s59
	s_nop 0
	global_load_lds_dwordx4 v1, s[6:7]
	s_waitcnt vmcnt(8)
	s_waitcnt lgkmcnt(0)
	s_barrier
	s_setprio 1
	s_waitcnt lgkmcnt(7)
	v_mfma_f32_16x16x32_bf16 v[126:129], v[130:133], v[192:195], v[126:129]
	v_mfma_f32_16x16x32_bf16 v[122:125], v[154:157], v[192:195], v[122:125]
	s_waitcnt lgkmcnt(5)
	v_mfma_f32_16x16x32_bf16 v[118:121], v[130:133], v[204:207], v[118:121]
	v_mfma_f32_16x16x32_bf16 v[114:117], v[154:157], v[204:207], v[114:117]
	s_waitcnt lgkmcnt(3)
	v_mfma_f32_16x16x32_bf16 v[110:113], v[130:133], v[212:215], v[110:113]
	v_mfma_f32_16x16x32_bf16 v[106:109], v[154:157], v[212:215], v[106:109]
	s_waitcnt lgkmcnt(1)
	v_mfma_f32_16x16x32_bf16 v[102:105], v[130:133], v[220:223], v[102:105]
	v_mfma_f32_16x16x32_bf16 v[98:101], v[154:157], v[220:223], v[98:101]
	v_mfma_f32_16x16x32_bf16 v[126:129], v[134:137], v[196:199], v[126:129]
	v_mfma_f32_16x16x32_bf16 v[122:125], v[158:161], v[196:199], v[122:125]
	v_mfma_f32_16x16x32_bf16 v[118:121], v[134:137], v[208:211], v[118:121]
	v_mfma_f32_16x16x32_bf16 v[114:117], v[158:161], v[208:211], v[114:117]
	v_mfma_f32_16x16x32_bf16 v[110:113], v[134:137], v[216:219], v[110:113]
	v_mfma_f32_16x16x32_bf16 v[106:109], v[158:161], v[216:219], v[106:109]
	s_waitcnt lgkmcnt(0)
	v_mfma_f32_16x16x32_bf16 v[102:105], v[134:137], v[224:227], v[102:105]
	v_mfma_f32_16x16x32_bf16 v[98:101], v[158:161], v[224:227], v[98:101]
	s_setprio 0
	s_setprio 1
	v_mfma_f32_16x16x32_bf16 v[62:65], v[168:171], v[192:195], v[62:65]
	v_mfma_f32_16x16x32_bf16 v[58:61], v[184:187], v[192:195], v[58:61]
	v_mfma_f32_16x16x32_bf16 v[54:57], v[168:171], v[204:207], v[54:57]
	v_mfma_f32_16x16x32_bf16 v[50:53], v[184:187], v[204:207], v[50:53]
	v_mfma_f32_16x16x32_bf16 v[46:49], v[168:171], v[212:215], v[46:49]
	v_mfma_f32_16x16x32_bf16 v[42:45], v[184:187], v[212:215], v[42:45]
	v_mfma_f32_16x16x32_bf16 v[38:41], v[168:171], v[220:223], v[38:41]
	v_mfma_f32_16x16x32_bf16 v[34:37], v[184:187], v[220:223], v[34:37]
	v_mfma_f32_16x16x32_bf16 v[62:65], v[172:175], v[196:199], v[62:65]
	v_mfma_f32_16x16x32_bf16 v[58:61], v[188:191], v[196:199], v[58:61]
	v_mfma_f32_16x16x32_bf16 v[54:57], v[172:175], v[208:211], v[54:57]
	v_mfma_f32_16x16x32_bf16 v[50:53], v[188:191], v[208:211], v[50:53]
	s_add_u32 s66, s30, 0x8000
	v_mfma_f32_16x16x32_bf16 v[46:49], v[172:175], v[216:219], v[46:49]
	v_mfma_f32_16x16x32_bf16 v[42:45], v[188:191], v[216:219], v[42:45]
	v_mfma_f32_16x16x32_bf16 v[38:41], v[172:175], v[224:227], v[38:41]
	v_mfma_f32_16x16x32_bf16 v[34:37], v[188:191], v[224:227], v[34:37]
	s_setprio 0
	s_barrier
	ds_read_b128 v[192:195], v149 offset:16384
	ds_read_b128 v[196:199], v149 offset:17408
	ds_read_b128 v[204:207], v149 offset:18432
	ds_read_b128 v[208:211], v149 offset:19456
	ds_read_b128 v[212:215], v149 offset:20480
	ds_read_b128 v[216:219], v149 offset:21504
	ds_read_b128 v[220:223], v149 offset:22528
	ds_read_b128 v[224:227], v149 offset:23552
	s_mov_b32 m0, s44
	s_nop 0
	global_load_lds_dwordx4 v144, s[30:31]
	s_addc_u32 s67, s31, 0
	s_mov_b32 m0, s45
	s_nop 0
	global_load_lds_dwordx4 v144, s[66:67]
	s_add_u32 s66, s30, 0x10000
	s_addc_u32 s67, s31, 0
	s_mov_b32 m0, s46
	s_nop 0
	global_load_lds_dwordx4 v144, s[66:67]
	s_add_u32 s66, s30, 0x18000
	s_addc_u32 s67, s31, 0
	s_mov_b32 m0, s47
	s_nop 0
	global_load_lds_dwordx4 v144, s[66:67]
	s_add_u32 s66, s10, 0x20000
	s_mov_b32 m0, s43
	s_nop 0
	global_load_lds_dwordx4 v1, s[10:11]
	s_addc_u32 s67, s11, 0
	s_mov_b32 m0, s48
	s_nop 0
	global_load_lds_dwordx4 v1, s[66:67]
	s_waitcnt vmcnt(8)
	s_waitcnt lgkmcnt(0)
	s_barrier
; #define PG8_STAGE(bufoff, gbase, X) do { _Pragma("unroll") for (int _i = 0; _i < 2; ++_i) { \
;         const char* gp_ = (const char*)(gbase) + (_i ? rs##X : (size_t)0); const unsigned la_ = (unsigned)(size_t)(lds + (bufoff) + ldsw + _i * 8192); \
;         asm volatile("s_mov_b32 m0, %2\n\ts_nop 0\n\tglobal_load_lds_dwordx4 %0, %1" :: "v"(voff##X), "s"(gp_), "s"(la_) : "memory", "m0"); } } while (0)
; #define PG8_LDA(dst, b, h) do { _Pragma("unroll") for (int m = 0; m < 4; ++m) _Pragma("unroll") for (int k = 0; k < 2; ++k) dst[m][k] = *(const LAS bf16x8*)(lds + PG8_SA(b, h) + aoff + m * 2048 + k * 1024); } while (0)
; #define PG8_LDB(dst, b, h) do { _Pragma("unroll") for (int n = 0; n < 2; ++n) _Pragma("unroll") for (int k = 0; k < 2; ++k) dst[n][k] = *(const LAS bf16x8*)(lds + PG8_SB(b, h) + boff + n * 2048 + k * 1024); } while (0)
; #define PG8_WAIT_V(n) asm volatile("s_waitcnt vmcnt(" #n ")" ::: "memory")
; #define PG8_WAIT_L(n) asm volatile("s_waitcnt lgkmcnt(" #n ")" ::: "memory")
; #define PG8_BAR __builtin_amdgcn_s_barrier()
; #define PG8_SCHED __builtin_amdgcn_sched_barrier(0)
; template <class Epi>
; __device__ __forceinline__ void gemm_phase(LAS unsigned char* lds, const Gemm g_in, const StaticOrder& S, const Epi& E) {
;     ...
;             PG8_WAIT_V(8); PG8_WAIT_L(0); PG8_BAR; PG8_MMA(1, 0, At, B0); PG8_MMA(1, 1, At, B1); PG8_BAR; PG8_SCHED;
;             PG8_LDB(B0, 1, 0); PG8_LDB(B1, 1, 1); PG8_SCHED; PG8_LDA(At, 1, 0); PG8_STAGE(PG8_SA(0, 1), a2 + hsA, A);
;             PG8_WAIT_V(8); PG8_WAIT_L(0); PG8_BAR; PG8_MMA(0, 0, At, B0); PG8_MMA(0, 1, At, B1); PG8_BAR; PG8_SCHED;
	s_setprio 1
	s_waitcnt lgkmcnt(7)
	v_mfma_f32_16x16x32_bf16 v[94:97], v[130:133], v[192:195], v[94:97]
	v_mfma_f32_16x16x32_bf16 v[90:93], v[154:157], v[192:195], v[90:93]
	s_waitcnt lgkmcnt(5)
	v_mfma_f32_16x16x32_bf16 v[86:89], v[130:133], v[204:207], v[86:89]
	v_mfma_f32_16x16x32_bf16 v[82:85], v[154:157], v[204:207], v[82:85]
	s_waitcnt lgkmcnt(3)
	v_mfma_f32_16x16x32_bf16 v[78:81], v[130:133], v[212:215], v[78:81]
	v_mfma_f32_16x16x32_bf16 v[74:77], v[154:157], v[212:215], v[74:77]
	s_waitcnt lgkmcnt(1)
	v_mfma_f32_16x16x32_bf16 v[70:73], v[130:133], v[220:223], v[70:73]
	v_mfma_f32_16x16x32_bf16 v[66:69], v[154:157], v[220:223], v[66:69]
	v_mfma_f32_16x16x32_bf16 v[94:97], v[134:137], v[196:199], v[94:97]
	v_mfma_f32_16x16x32_bf16 v[90:93], v[158:161], v[196:199], v[90:93]
	v_mfma_f32_16x16x32_bf16 v[86:89], v[134:137], v[208:211], v[86:89]
	v_mfma_f32_16x16x32_bf16 v[82:85], v[158:161], v[208:211], v[82:85]
	v_mfma_f32_16x16x32_bf16 v[78:81], v[134:137], v[216:219], v[78:81]
	v_mfma_f32_16x16x32_bf16 v[74:77], v[158:161], v[216:219], v[74:77]
	s_waitcnt lgkmcnt(0)
	v_mfma_f32_16x16x32_bf16 v[70:73], v[134:137], v[224:227], v[70:73]
	v_mfma_f32_16x16x32_bf16 v[66:69], v[158:161], v[224:227], v[66:69]
	s_setprio 0
	s_setprio 1
	v_mfma_f32_16x16x32_bf16 v[30:33], v[168:171], v[192:195], v[30:33]
	v_mfma_f32_16x16x32_bf16 v[26:29], v[184:187], v[192:195], v[26:29]
	v_mfma_f32_16x16x32_bf16 v[22:25], v[168:171], v[204:207], v[22:25]
	v_mfma_f32_16x16x32_bf16 v[18:21], v[184:187], v[204:207], v[18:21]
	v_mfma_f32_16x16x32_bf16 v[14:17], v[168:171], v[212:215], v[14:17]
	v_mfma_f32_16x16x32_bf16 v[10:13], v[184:187], v[212:215], v[10:13]
	v_mfma_f32_16x16x32_bf16 v[6:9], v[168:171], v[220:223], v[6:9]
	v_mfma_f32_16x16x32_bf16 v[2:5], v[184:187], v[220:223], v[2:5]
	v_mfma_f32_16x16x32_bf16 v[30:33], v[172:175], v[196:199], v[30:33]
	v_mfma_f32_16x16x32_bf16 v[26:29], v[188:191], v[196:199], v[26:29]
	v_mfma_f32_16x16x32_bf16 v[22:25], v[172:175], v[208:211], v[22:25]
	v_mfma_f32_16x16x32_bf16 v[18:21], v[188:191], v[208:211], v[18:21]
	v_mfma_f32_16x16x32_bf16 v[14:17], v[172:175], v[216:219], v[14:17]
	v_mfma_f32_16x16x32_bf16 v[10:13], v[188:191], v[216:219], v[10:13]
	v_mfma_f32_16x16x32_bf16 v[6:9], v[172:175], v[224:227], v[6:9]
	v_mfma_f32_16x16x32_bf16 v[2:5], v[188:191], v[224:227], v[2:5]
	s_setprio 0
	s_barrier
	ds_read_b128 v[130:133], v150
	ds_read_b128 v[134:137], v150 offset:1024
	ds_read_b128 v[154:157], v150 offset:2048
	ds_read_b128 v[158:161], v150 offset:3072
	ds_read_b128 v[168:171], v151
	ds_read_b128 v[172:175], v151 offset:1024
	ds_read_b128 v[184:187], v151 offset:2048
	ds_read_b128 v[188:191], v151 offset:3072
	ds_read_b128 v[192:195], v149 offset:32768
	ds_read_b128 v[196:199], v149 offset:33792
	ds_read_b128 v[204:207], v149 offset:34816
	ds_read_b128 v[208:211], v149 offset:35840
	ds_read_b128 v[212:215], v149 offset:36864
	ds_read_b128 v[216:219], v149 offset:37888
	ds_read_b128 v[220:223], v149 offset:38912
	ds_read_b128 v[224:227], v149 offset:39936
	s_add_u32 s66, s10, 0x40000
	s_addc_u32 s67, s11, 0
	s_mov_b32 m0, s49
	s_nop 0
	global_load_lds_dwordx4 v1, s[66:67]
	s_add_u32 s66, s10, 0x60000
	s_addc_u32 s67, s11, 0
	s_mov_b32 m0, s50
	s_nop 0
	global_load_lds_dwordx4 v1, s[66:67]
	s_waitcnt vmcnt(8)
	s_waitcnt lgkmcnt(0)
	s_barrier
	s_setprio 1
	s_waitcnt lgkmcnt(7)
	v_mfma_f32_16x16x32_bf16 v[126:129], v[130:133], v[192:195], v[126:129]
	v_mfma_f32_16x16x32_bf16 v[122:125], v[154:157], v[192:195], v[122:125]
	s_waitcnt lgkmcnt(5)
	v_mfma_f32_16x16x32_bf16 v[118:121], v[130:133], v[204:207], v[118:121]
	v_mfma_f32_16x16x32_bf16 v[114:117], v[154:157], v[204:207], v[114:117]
	s_waitcnt lgkmcnt(3)
	v_mfma_f32_16x16x32_bf16 v[110:113], v[130:133], v[212:215], v[110:113]
	v_mfma_f32_16x16x32_bf16 v[106:109], v[154:157], v[212:215], v[106:109]
	s_waitcnt lgkmcnt(1)
	v_mfma_f32_16x16x32_bf16 v[102:105], v[130:133], v[220:223], v[102:105]
	v_mfma_f32_16x16x32_bf16 v[98:101], v[154:157], v[220:223], v[98:101]
	v_mfma_f32_16x16x32_bf16 v[126:129], v[134:137], v[196:199], v[126:129]
	v_mfma_f32_16x16x32_bf16 v[122:125], v[158:161], v[196:199], v[122:125]
	v_mfma_f32_16x16x32_bf16 v[118:121], v[134:137], v[208:211], v[118:121]
	v_mfma_f32_16x16x32_bf16 v[114:117], v[158:161], v[208:211], v[114:117]
	v_mfma_f32_16x16x32_bf16 v[110:113], v[134:137], v[216:219], v[110:113]
	v_mfma_f32_16x16x32_bf16 v[106:109], v[158:161], v[216:219], v[106:109]
	s_waitcnt lgkmcnt(0)
	v_mfma_f32_16x16x32_bf16 v[102:105], v[134:137], v[224:227], v[102:105]
	v_mfma_f32_16x16x32_bf16 v[98:101], v[158:161], v[224:227], v[98:101]
	s_setprio 0
	s_setprio 1
	v_mfma_f32_16x16x32_bf16 v[62:65], v[168:171], v[192:195], v[62:65]
	v_mfma_f32_16x16x32_bf16 v[58:61], v[184:187], v[192:195], v[58:61]
	v_mfma_f32_16x16x32_bf16 v[54:57], v[168:171], v[204:207], v[54:57]
	v_mfma_f32_16x16x32_bf16 v[50:53], v[184:187], v[204:207], v[50:53]
	v_mfma_f32_16x16x32_bf16 v[46:49], v[168:171], v[212:215], v[46:49]
	v_mfma_f32_16x16x32_bf16 v[42:45], v[184:187], v[212:215], v[42:45]
	v_mfma_f32_16x16x32_bf16 v[38:41], v[168:171], v[220:223], v[38:41]
	v_mfma_f32_16x16x32_bf16 v[34:37], v[184:187], v[220:223], v[34:37]
	v_mfma_f32_16x16x32_bf16 v[62:65], v[172:175], v[196:199], v[62:65]
	v_mfma_f32_16x16x32_bf16 v[58:61], v[188:191], v[196:199], v[58:61]
	v_mfma_f32_16x16x32_bf16 v[54:57], v[172:175], v[208:211], v[54:57]
	v_mfma_f32_16x16x32_bf16 v[50:53], v[188:191], v[208:211], v[50:53]
	s_add_u32 s66, s30, 0x80
	s_addc_u32 s67, s31, 0
	v_mfma_f32_16x16x32_bf16 v[46:49], v[172:175], v[216:219], v[46:49]
	v_mfma_f32_16x16x32_bf16 v[42:45], v[188:191], v[216:219], v[42:45]
	v_mfma_f32_16x16x32_bf16 v[38:41], v[172:175], v[224:227], v[38:41]
	v_mfma_f32_16x16x32_bf16 v[34:37], v[188:191], v[224:227], v[34:37]
	s_setprio 0
	s_barrier
; #define PG8_STAGE(bufoff, gbase, X) do { _Pragma("unroll") for (int _i = 0; _i < 2; ++_i) { \
;         const char* gp_ = (const char*)(gbase) + (_i ? rs##X : (size_t)0); const unsigned la_ = (unsigned)(size_t)(lds + (bufoff) + ldsw + _i * 8192); \
;         asm volatile("s_mov_b32 m0, %2\n\ts_nop 0\n\tglobal_load_lds_dwordx4 %0, %1" :: "v"(voff##X), "s"(gp_), "s"(la_) : "memory", "m0"); } } while (0)
; #define PG8_LDA(dst, b, h) do { _Pragma("unroll") for (int m = 0; m < 4; ++m) _Pragma("unroll") for (int k = 0; k < 2; ++k) dst[m][k] = *(const LAS bf16x8*)(lds + PG8_SA(b, h) + aoff + m * 2048 + k * 1024); } while (0)
; #define PG8_WAIT_V(n) asm volatile("s_waitcnt vmcnt(" #n ")" ::: "memory")
; #define PG8_WAIT_L(n) asm volatile("s_waitcnt lgkmcnt(" #n ")" ::: "memory")
; #define PG8_BAR __builtin_amdgcn_s_barrier()
; #define PG8_SCHED __builtin_amdgcn_sched_barrier(0)
; template <class Epi>
; __device__ __forceinline__ void gemm_phase(LAS unsigned char* lds, const Gemm g_in, const StaticOrder& S, const Epi& E) {
;     ...
;             PG8_LDA(At, 1, 1); PG8_STAGE(PG8_SB(1, 0), b3, B); PG8_STAGE(PG8_SB(1, 1), b3 + hsB, B); PG8_STAGE(PG8_SA(1, 0), a3, A);
;             PG8_WAIT_V(8); PG8_WAIT_L(0); PG8_BAR; PG8_MMA(1, 0, At, B0); PG8_MMA(1, 1, At, B1); PG8_BAR; PG8_SCHED;
;         }
	ds_read_b128 v[192:195], v149 offset:49152
	ds_read_b128 v[196:199], v149 offset:50176
	ds_read_b128 v[204:207], v149 offset:51200
	ds_read_b128 v[208:211], v149 offset:52224
	ds_read_b128 v[212:215], v149 offset:53248
	ds_read_b128 v[216:219], v149 offset:54272
	ds_read_b128 v[220:223], v149 offset:55296
	ds_read_b128 v[224:227], v149 offset:56320
	s_mov_b32 m0, s51
	s_nop 0
	global_load_lds_dwordx4 v144, s[66:67]
	s_add_u32 s66, s30, 0x8080
	s_addc_u32 s67, s31, 0
	s_mov_b32 m0, s52
	s_nop 0
	global_load_lds_dwordx4 v144, s[66:67]
	s_add_u32 s66, s30, 0x10080
	s_addc_u32 s67, s31, 0
	s_mov_b32 m0, s55
	s_nop 0
	global_load_lds_dwordx4 v144, s[66:67]
	s_add_u32 s30, s30, 0x18080
	s_addc_u32 s31, s31, 0
	s_mov_b32 m0, s56
	s_nop 0
	global_load_lds_dwordx4 v144, s[30:31]
	s_add_u32 s10, s10, 0x20080
	s_mov_b32 m0, s53
	s_nop 0
	global_load_lds_dwordx4 v1, s[28:29]
	s_addc_u32 s11, s11, 0
	s_mov_b32 m0, s54
	s_nop 0
	global_load_lds_dwordx4 v1, s[10:11]
	s_waitcnt vmcnt(8)
	s_waitcnt lgkmcnt(0)
	s_barrier
	s_setprio 1
	s_waitcnt lgkmcnt(7)
	v_mfma_f32_16x16x32_bf16 v[94:97], v[130:133], v[192:195], v[94:97]
	v_mfma_f32_16x16x32_bf16 v[90:93], v[154:157], v[192:195], v[90:93]
	s_waitcnt lgkmcnt(5)
	v_mfma_f32_16x16x32_bf16 v[86:89], v[130:133], v[204:207], v[86:89]
	v_mfma_f32_16x16x32_bf16 v[82:85], v[154:157], v[204:207], v[82:85]
	s_waitcnt lgkmcnt(3)
	v_mfma_f32_16x16x32_bf16 v[78:81], v[130:133], v[212:215], v[78:81]
	v_mfma_f32_16x16x32_bf16 v[74:77], v[154:157], v[212:215], v[74:77]
	s_waitcnt lgkmcnt(1)
	v_mfma_f32_16x16x32_bf16 v[70:73], v[130:133], v[220:223], v[70:73]
	v_mfma_f32_16x16x32_bf16 v[66:69], v[154:157], v[220:223], v[66:69]
	v_mfma_f32_16x16x32_bf16 v[94:97], v[134:137], v[196:199], v[94:97]
	v_mfma_f32_16x16x32_bf16 v[90:93], v[158:161], v[196:199], v[90:93]
	v_mfma_f32_16x16x32_bf16 v[86:89], v[134:137], v[208:211], v[86:89]
	v_mfma_f32_16x16x32_bf16 v[82:85], v[158:161], v[208:211], v[82:85]
	v_mfma_f32_16x16x32_bf16 v[78:81], v[134:137], v[216:219], v[78:81]
	v_mfma_f32_16x16x32_bf16 v[74:77], v[158:161], v[216:219], v[74:77]
	s_waitcnt lgkmcnt(0)
	v_mfma_f32_16x16x32_bf16 v[70:73], v[134:137], v[224:227], v[70:73]
	v_mfma_f32_16x16x32_bf16 v[66:69], v[158:161], v[224:227], v[66:69]
	s_setprio 0
	s_setprio 1
	v_mfma_f32_16x16x32_bf16 v[30:33], v[168:171], v[192:195], v[30:33]
	v_mfma_f32_16x16x32_bf16 v[26:29], v[184:187], v[192:195], v[26:29]
	v_mfma_f32_16x16x32_bf16 v[22:25], v[168:171], v[204:207], v[22:25]
	v_mfma_f32_16x16x32_bf16 v[18:21], v[184:187], v[204:207], v[18:21]
	v_mfma_f32_16x16x32_bf16 v[14:17], v[168:171], v[212:215], v[14:17]
	v_mfma_f32_16x16x32_bf16 v[10:13], v[184:187], v[212:215], v[10:13]
	v_mfma_f32_16x16x32_bf16 v[6:9], v[168:171], v[220:223], v[6:9]
	v_mfma_f32_16x16x32_bf16 v[2:5], v[184:187], v[220:223], v[2:5]
	v_mfma_f32_16x16x32_bf16 v[30:33], v[172:175], v[196:199], v[30:33]
	v_mfma_f32_16x16x32_bf16 v[26:29], v[188:191], v[196:199], v[26:29]
	v_mfma_f32_16x16x32_bf16 v[22:25], v[172:175], v[208:211], v[22:25]
	v_mfma_f32_16x16x32_bf16 v[18:21], v[188:191], v[208:211], v[18:21]
	s_add_u32 s62, s62, 0x100
	s_addc_u32 s63, s63, 0
	s_add_u32 s6, s6, 0x100
	s_addc_u32 s7, s7, 0
	s_cmp_ge_i32 s64, s39
	s_mov_b32 s10, s64
	v_mfma_f32_16x16x32_bf16 v[14:17], v[172:175], v[216:219], v[14:17]
	v_mfma_f32_16x16x32_bf16 v[10:13], v[188:191], v[216:219], v[10:13]
	v_mfma_f32_16x16x32_bf16 v[6:9], v[172:175], v[224:227], v[6:9]
	v_mfma_f32_16x16x32_bf16 v[2:5], v[188:191], v[224:227], v[2:5]
	s_setprio 0
	s_barrier
	s_cbranch_scc0 .LBB0_769
	s_and_b64 vcc, exec, s[16:17]
	s_cbranch_vccz .LBB0_772

; #define PG8_STAGE(bufoff, gbase, X) do { _Pragma("unroll") for (int _i = 0; _i < 2; ++_i) { \
;         const char* gp_ = (const char*)(gbase) + (_i ? rs##X : (size_t)0); const unsigned la_ = (unsigned)(size_t)(lds + (bufoff) + ldsw + _i * 8192); \
;         asm volatile("s_mov_b32 m0, %2\n\ts_nop 0\n\tglobal_load_lds_dwordx4 %0, %1" :: "v"(voff##X), "s"(gp_), "s"(la_) : "memory", "m0"); } } while (0)
; #define PG8_LDA(dst, b, h) do { _Pragma("unroll") for (int m = 0; m < 4; ++m) _Pragma("unroll") for (int k = 0; k < 2; ++k) dst[m][k] = *(const LAS bf16x8*)(lds + PG8_SA(b, h) + aoff + m * 2048 + k * 1024); } while (0)
; #define PG8_LDB(dst, b, h) do { _Pragma("unroll") for (int n = 0; n < 2; ++n) _Pragma("unroll") for (int k = 0; k < 2; ++k) dst[n][k] = *(const LAS bf16x8*)(lds + PG8_SB(b, h) + boff + n * 2048 + k * 1024); } while (0)
; #define PG8_WAIT_V(n) asm volatile("s_waitcnt vmcnt(" #n ")" ::: "memory")
; #define PG8_WAIT_L(n) asm volatile("s_waitcnt lgkmcnt(" #n ")" ::: "memory")
; #define PG8_BAR __builtin_amdgcn_s_barrier()
; #define PG8_SCHED __builtin_amdgcn_sched_barrier(0)
; template <class Epi>
; __device__ __forceinline__ void gemm_phase(LAS unsigned char* lds, const Gemm g_in, const StaticOrder& S, const Epi& E) {
;     ...
;             const bool last = (t == nt - 2);
;             const char* a1 = cA + (size_t)(t + 1) * kstep;
;             const char* a2 = last ? nA : cA + (size_t)(t + 2) * kstep; const char* b2 = last ? nB : cB + (size_t)(t + 2) * kstep;
;             const char* a3 = a2 + kstep; const char* b3 = b2 + kstep;
;             PG8_LDB(B0, 0, 0); PG8_LDB(B1, 0, 1); PG8_SCHED; PG8_LDA(At, 0, 0); PG8_STAGE(PG8_SA(1, 1), a1 + hsA, A);
;             PG8_WAIT_V(8); PG8_WAIT_L(0); PG8_BAR; PG8_MMA(0, 0, At, B0); PG8_MMA(0, 1, At, B1); PG8_BAR; PG8_SCHED;
;             PG8_LDA(At, 0, 1); PG8_STAGE(PG8_SB(0, 0), b2, B); PG8_STAGE(PG8_SB(0, 1), b2 + hsB, B); PG8_STAGE(PG8_SA(0, 0), a2, A);
;             PG8_WAIT_V(8); PG8_WAIT_L(0); PG8_BAR; PG8_MMA(1, 0, At, B0); PG8_MMA(1, 1, At, B1); PG8_BAR; PG8_SCHED;
.LBB0_787:
	ds_read_b128 v[142:145], v137
	ds_read_b128 v[146:149], v137 offset:1024
	ds_read_b128 v[154:157], v137 offset:2048
	ds_read_b128 v[158:161], v137 offset:3072
	ds_read_b128 v[168:171], v138
	ds_read_b128 v[172:175], v138 offset:1024
	ds_read_b128 v[184:187], v138 offset:2048
	ds_read_b128 v[188:191], v138 offset:3072
	s_add_i32 s63, s26, 2
	s_add_u32 s28, s24, 0xfffa0080
	s_addc_u32 s27, s25, -1
	s_cmp_eq_u32 s55, s26
	s_cselect_b32 s26, s17, s28
	s_cselect_b32 s27, s15, s27
	s_cselect_b32 s30, s60, s61
	s_cselect_b32 s31, s59, s62
	s_add_u32 s28, s26, 0x80
	s_addc_u32 s29, s27, 0
	ds_read_b128 v[192:195], v139
	ds_read_b128 v[196:199], v139 offset:1024
	ds_read_b128 v[204:207], v139 offset:2048
	ds_read_b128 v[208:211], v139 offset:3072
	ds_read_b128 v[212:215], v139 offset:4096
	ds_read_b128 v[216:219], v139 offset:5120
	ds_read_b128 v[220:223], v139 offset:6144
	ds_read_b128 v[224:227], v139 offset:7168
	s_add_u32 s64, s24, 0xfffe0000
	s_addc_u32 s65, s25, -1
	s_mov_b32 m0, s56
	s_nop 0
	global_load_lds_dwordx4 v1, s[64:65]
	s_nop 0
	s_mov_b32 m0, s57
	s_nop 0
	global_load_lds_dwordx4 v1, s[24:25]
	s_waitcnt vmcnt(8)
	s_waitcnt lgkmcnt(0)
	s_barrier
	s_setprio 1
	s_waitcnt lgkmcnt(7)
	v_mfma_f32_16x16x32_bf16 v[126:129], v[142:145], v[192:195], v[126:129]
	v_mfma_f32_16x16x32_bf16 v[122:125], v[154:157], v[192:195], v[122:125]
	s_waitcnt lgkmcnt(5)
	v_mfma_f32_16x16x32_bf16 v[110:113], v[142:145], v[204:207], v[110:113]
	v_mfma_f32_16x16x32_bf16 v[106:109], v[154:157], v[204:207], v[106:109]
	s_waitcnt lgkmcnt(3)
	v_mfma_f32_16x16x32_bf16 v[94:97], v[142:145], v[212:215], v[94:97]
	v_mfma_f32_16x16x32_bf16 v[90:93], v[154:157], v[212:215], v[90:93]
	s_waitcnt lgkmcnt(1)
	v_mfma_f32_16x16x32_bf16 v[78:81], v[142:145], v[220:223], v[78:81]
	v_mfma_f32_16x16x32_bf16 v[74:77], v[154:157], v[220:223], v[74:77]
	v_mfma_f32_16x16x32_bf16 v[126:129], v[146:149], v[196:199], v[126:129]
	v_mfma_f32_16x16x32_bf16 v[122:125], v[158:161], v[196:199], v[122:125]
	v_mfma_f32_16x16x32_bf16 v[110:113], v[146:149], v[208:211], v[110:113]
	v_mfma_f32_16x16x32_bf16 v[106:109], v[158:161], v[208:211], v[106:109]
	v_mfma_f32_16x16x32_bf16 v[94:97], v[146:149], v[216:219], v[94:97]
	v_mfma_f32_16x16x32_bf16 v[90:93], v[158:161], v[216:219], v[90:93]
	s_waitcnt lgkmcnt(0)
	v_mfma_f32_16x16x32_bf16 v[78:81], v[146:149], v[224:227], v[78:81]
	v_mfma_f32_16x16x32_bf16 v[74:77], v[158:161], v[224:227], v[74:77]
	s_setprio 0
	s_setprio 1
	v_mfma_f32_16x16x32_bf16 v[118:121], v[168:171], v[192:195], v[118:121]
	v_mfma_f32_16x16x32_bf16 v[114:117], v[184:187], v[192:195], v[114:117]
	v_mfma_f32_16x16x32_bf16 v[102:105], v[168:171], v[204:207], v[102:105]
	v_mfma_f32_16x16x32_bf16 v[98:101], v[184:187], v[204:207], v[98:101]
	v_mfma_f32_16x16x32_bf16 v[86:89], v[168:171], v[212:215], v[86:89]
	v_mfma_f32_16x16x32_bf16 v[82:85], v[184:187], v[212:215], v[82:85]
	v_mfma_f32_16x16x32_bf16 v[70:73], v[168:171], v[220:223], v[70:73]
	v_mfma_f32_16x16x32_bf16 v[66:69], v[184:187], v[220:223], v[66:69]
	v_mfma_f32_16x16x32_bf16 v[118:121], v[172:175], v[196:199], v[118:121]
	v_mfma_f32_16x16x32_bf16 v[114:117], v[188:191], v[196:199], v[114:117]
	v_mfma_f32_16x16x32_bf16 v[102:105], v[172:175], v[208:211], v[102:105]
	v_mfma_f32_16x16x32_bf16 v[98:101], v[188:191], v[208:211], v[98:101]
	s_add_u32 s64, s30, 0x10000
	v_mfma_f32_16x16x32_bf16 v[86:89], v[172:175], v[216:219], v[86:89]
	v_mfma_f32_16x16x32_bf16 v[82:85], v[188:191], v[216:219], v[82:85]
	v_mfma_f32_16x16x32_bf16 v[70:73], v[172:175], v[224:227], v[70:73]
	v_mfma_f32_16x16x32_bf16 v[66:69], v[188:191], v[224:227], v[66:69]
	s_setprio 0
	s_barrier
	ds_read_b128 v[192:195], v139 offset:16384
	ds_read_b128 v[196:199], v139 offset:17408
	ds_read_b128 v[204:207], v139 offset:18432
	ds_read_b128 v[208:211], v139 offset:19456
	ds_read_b128 v[212:215], v139 offset:20480
	ds_read_b128 v[216:219], v139 offset:21504
	ds_read_b128 v[220:223], v139 offset:22528
	ds_read_b128 v[224:227], v139 offset:23552
	s_mov_b32 m0, s42
	s_nop 0
	global_load_lds_dwordx4 v134, s[30:31]
	s_addc_u32 s65, s31, 0
	s_mov_b32 m0, s43
	s_nop 0
	global_load_lds_dwordx4 v134, s[64:65]
	s_add_u32 s64, s30, 0x20000
	s_addc_u32 s65, s31, 0
	s_mov_b32 m0, s44
	s_nop 0
	global_load_lds_dwordx4 v134, s[64:65]
	s_add_u32 s64, s30, 0x30000
	s_addc_u32 s65, s31, 0
	s_mov_b32 m0, s45
	s_nop 0
	global_load_lds_dwordx4 v134, s[64:65]
	s_add_u32 s64, s26, 0x20000
	s_mov_b32 m0, s13
	s_nop 0
	global_load_lds_dwordx4 v1, s[26:27]
	s_addc_u32 s65, s27, 0
	s_mov_b32 m0, s46
	s_nop 0
	global_load_lds_dwordx4 v1, s[64:65]
	s_waitcnt vmcnt(8)
	s_waitcnt lgkmcnt(0)
	s_barrier
; #define PG8_STAGE(bufoff, gbase, X) do { _Pragma("unroll") for (int _i = 0; _i < 2; ++_i) { \
;         const char* gp_ = (const char*)(gbase) + (_i ? rs##X : (size_t)0); const unsigned la_ = (unsigned)(size_t)(lds + (bufoff) + ldsw + _i * 8192); \
;         asm volatile("s_mov_b32 m0, %2\n\ts_nop 0\n\tglobal_load_lds_dwordx4 %0, %1" :: "v"(voff##X), "s"(gp_), "s"(la_) : "memory", "m0"); } } while (0)
; #define PG8_LDA(dst, b, h) do { _Pragma("unroll") for (int m = 0; m < 4; ++m) _Pragma("unroll") for (int k = 0; k < 2; ++k) dst[m][k] = *(const LAS bf16x8*)(lds + PG8_SA(b, h) + aoff + m * 2048 + k * 1024); } while (0)
; #define PG8_LDB(dst, b, h) do { _Pragma("unroll") for (int n = 0; n < 2; ++n) _Pragma("unroll") for (int k = 0; k < 2; ++k) dst[n][k] = *(const LAS bf16x8*)(lds + PG8_SB(b, h) + boff + n * 2048 + k * 1024); } while (0)
; #define PG8_WAIT_V(n) asm volatile("s_waitcnt vmcnt(" #n ")" ::: "memory")
; #define PG8_WAIT_L(n) asm volatile("s_waitcnt lgkmcnt(" #n ")" ::: "memory")
; #define PG8_BAR __builtin_amdgcn_s_barrier()
; #define PG8_SCHED __builtin_amdgcn_sched_barrier(0)
; template <class Epi>
; __device__ __forceinline__ void gemm_phase(LAS unsigned char* lds, const Gemm g_in, const StaticOrder& S, const Epi& E) {
;     ...
;             PG8_LDA(At, 0, 1); PG8_STAGE(PG8_SB(0, 0), b2, B); PG8_STAGE(PG8_SB(0, 1), b2 + hsB, B); PG8_STAGE(PG8_SA(0, 0), a2, A);
;             PG8_WAIT_V(8); PG8_WAIT_L(0); PG8_BAR; PG8_MMA(1, 0, At, B0); PG8_MMA(1, 1, At, B1); PG8_BAR; PG8_SCHED;
;             PG8_LDB(B0, 1, 0); PG8_LDB(B1, 1, 1); PG8_SCHED; PG8_LDA(At, 1, 0); PG8_STAGE(PG8_SA(0, 1), a2 + hsA, A);
;             PG8_WAIT_V(8); PG8_WAIT_L(0); PG8_BAR; PG8_MMA(0, 0, At, B0); PG8_MMA(0, 1, At, B1); PG8_BAR; PG8_SCHED;
	s_setprio 1
	s_waitcnt lgkmcnt(7)
	v_mfma_f32_16x16x32_bf16 v[62:65], v[142:145], v[192:195], v[62:65]
	v_mfma_f32_16x16x32_bf16 v[58:61], v[154:157], v[192:195], v[58:61]
	s_waitcnt lgkmcnt(5)
	v_mfma_f32_16x16x32_bf16 v[46:49], v[142:145], v[204:207], v[46:49]
	v_mfma_f32_16x16x32_bf16 v[42:45], v[154:157], v[204:207], v[42:45]
	s_waitcnt lgkmcnt(3)
	v_mfma_f32_16x16x32_bf16 v[30:33], v[142:145], v[212:215], v[30:33]
	v_mfma_f32_16x16x32_bf16 v[26:29], v[154:157], v[212:215], v[26:29]
	s_waitcnt lgkmcnt(1)
	v_mfma_f32_16x16x32_bf16 v[14:17], v[142:145], v[220:223], v[14:17]
	v_mfma_f32_16x16x32_bf16 v[10:13], v[154:157], v[220:223], v[10:13]
	v_mfma_f32_16x16x32_bf16 v[62:65], v[146:149], v[196:199], v[62:65]
	v_mfma_f32_16x16x32_bf16 v[58:61], v[158:161], v[196:199], v[58:61]
	v_mfma_f32_16x16x32_bf16 v[46:49], v[146:149], v[208:211], v[46:49]
	v_mfma_f32_16x16x32_bf16 v[42:45], v[158:161], v[208:211], v[42:45]
	v_mfma_f32_16x16x32_bf16 v[30:33], v[146:149], v[216:219], v[30:33]
	v_mfma_f32_16x16x32_bf16 v[26:29], v[158:161], v[216:219], v[26:29]
	s_waitcnt lgkmcnt(0)
	v_mfma_f32_16x16x32_bf16 v[14:17], v[146:149], v[224:227], v[14:17]
	v_mfma_f32_16x16x32_bf16 v[10:13], v[158:161], v[224:227], v[10:13]
	s_setprio 0
	s_setprio 1
	v_mfma_f32_16x16x32_bf16 v[54:57], v[168:171], v[192:195], v[54:57]
	v_mfma_f32_16x16x32_bf16 v[50:53], v[184:187], v[192:195], v[50:53]
	v_mfma_f32_16x16x32_bf16 v[38:41], v[168:171], v[204:207], v[38:41]
	v_mfma_f32_16x16x32_bf16 v[34:37], v[184:187], v[204:207], v[34:37]
	v_mfma_f32_16x16x32_bf16 v[22:25], v[168:171], v[212:215], v[22:25]
	v_mfma_f32_16x16x32_bf16 v[18:21], v[184:187], v[212:215], v[18:21]
	v_mfma_f32_16x16x32_bf16 v[6:9], v[168:171], v[220:223], v[6:9]
	v_mfma_f32_16x16x32_bf16 v[2:5], v[184:187], v[220:223], v[2:5]
	v_mfma_f32_16x16x32_bf16 v[54:57], v[172:175], v[196:199], v[54:57]
	v_mfma_f32_16x16x32_bf16 v[50:53], v[188:191], v[196:199], v[50:53]
	v_mfma_f32_16x16x32_bf16 v[38:41], v[172:175], v[208:211], v[38:41]
	v_mfma_f32_16x16x32_bf16 v[34:37], v[188:191], v[208:211], v[34:37]
	v_mfma_f32_16x16x32_bf16 v[22:25], v[172:175], v[216:219], v[22:25]
	v_mfma_f32_16x16x32_bf16 v[18:21], v[188:191], v[216:219], v[18:21]
	v_mfma_f32_16x16x32_bf16 v[6:9], v[172:175], v[224:227], v[6:9]
	v_mfma_f32_16x16x32_bf16 v[2:5], v[188:191], v[224:227], v[2:5]
	s_setprio 0
	s_barrier
	ds_read_b128 v[142:145], v140
	ds_read_b128 v[146:149], v140 offset:1024
	ds_read_b128 v[154:157], v140 offset:2048
	ds_read_b128 v[158:161], v140 offset:3072
	ds_read_b128 v[168:171], v141
	ds_read_b128 v[172:175], v141 offset:1024
	ds_read_b128 v[184:187], v141 offset:2048
	ds_read_b128 v[188:191], v141 offset:3072
	ds_read_b128 v[192:195], v139 offset:32768
	ds_read_b128 v[196:199], v139 offset:33792
	ds_read_b128 v[204:207], v139 offset:34816
	ds_read_b128 v[208:211], v139 offset:35840
	ds_read_b128 v[212:215], v139 offset:36864
	ds_read_b128 v[216:219], v139 offset:37888
	ds_read_b128 v[220:223], v139 offset:38912
	ds_read_b128 v[224:227], v139 offset:39936
	s_add_u32 s64, s26, 0x40000
	s_addc_u32 s65, s27, 0
	s_mov_b32 m0, s47
	s_nop 0
	global_load_lds_dwordx4 v1, s[64:65]
	s_add_u32 s64, s26, 0x60000
	s_addc_u32 s65, s27, 0
	s_mov_b32 m0, s48
	s_nop 0
	global_load_lds_dwordx4 v1, s[64:65]
	s_waitcnt vmcnt(8)
	s_waitcnt lgkmcnt(0)
	s_barrier
	s_setprio 1
	s_waitcnt lgkmcnt(7)
	v_mfma_f32_16x16x32_bf16 v[126:129], v[142:145], v[192:195], v[126:129]
	v_mfma_f32_16x16x32_bf16 v[122:125], v[154:157], v[192:195], v[122:125]
	s_waitcnt lgkmcnt(5)
	v_mfma_f32_16x16x32_bf16 v[110:113], v[142:145], v[204:207], v[110:113]
	v_mfma_f32_16x16x32_bf16 v[106:109], v[154:157], v[204:207], v[106:109]
	s_waitcnt lgkmcnt(3)
	v_mfma_f32_16x16x32_bf16 v[94:97], v[142:145], v[212:215], v[94:97]
	v_mfma_f32_16x16x32_bf16 v[90:93], v[154:157], v[212:215], v[90:93]
	s_waitcnt lgkmcnt(1)
	v_mfma_f32_16x16x32_bf16 v[78:81], v[142:145], v[220:223], v[78:81]
	v_mfma_f32_16x16x32_bf16 v[74:77], v[154:157], v[220:223], v[74:77]
	v_mfma_f32_16x16x32_bf16 v[126:129], v[146:149], v[196:199], v[126:129]
	v_mfma_f32_16x16x32_bf16 v[122:125], v[158:161], v[196:199], v[122:125]
	v_mfma_f32_16x16x32_bf16 v[110:113], v[146:149], v[208:211], v[110:113]
	v_mfma_f32_16x16x32_bf16 v[106:109], v[158:161], v[208:211], v[106:109]
	v_mfma_f32_16x16x32_bf16 v[94:97], v[146:149], v[216:219], v[94:97]
	v_mfma_f32_16x16x32_bf16 v[90:93], v[158:161], v[216:219], v[90:93]
	s_waitcnt lgkmcnt(0)
	v_mfma_f32_16x16x32_bf16 v[78:81], v[146:149], v[224:227], v[78:81]
	v_mfma_f32_16x16x32_bf16 v[74:77], v[158:161], v[224:227], v[74:77]
	s_setprio 0
	s_setprio 1
	v_mfma_f32_16x16x32_bf16 v[118:121], v[168:171], v[192:195], v[118:121]
	v_mfma_f32_16x16x32_bf16 v[114:117], v[184:187], v[192:195], v[114:117]
	v_mfma_f32_16x16x32_bf16 v[102:105], v[168:171], v[204:207], v[102:105]
	v_mfma_f32_16x16x32_bf16 v[98:101], v[184:187], v[204:207], v[98:101]
	v_mfma_f32_16x16x32_bf16 v[86:89], v[168:171], v[212:215], v[86:89]
	v_mfma_f32_16x16x32_bf16 v[82:85], v[184:187], v[212:215], v[82:85]
	v_mfma_f32_16x16x32_bf16 v[70:73], v[168:171], v[220:223], v[70:73]
	v_mfma_f32_16x16x32_bf16 v[66:69], v[184:187], v[220:223], v[66:69]
	v_mfma_f32_16x16x32_bf16 v[118:121], v[172:175], v[196:199], v[118:121]
	v_mfma_f32_16x16x32_bf16 v[114:117], v[188:191], v[196:199], v[114:117]
	v_mfma_f32_16x16x32_bf16 v[102:105], v[172:175], v[208:211], v[102:105]
	v_mfma_f32_16x16x32_bf16 v[98:101], v[188:191], v[208:211], v[98:101]
	s_add_u32 s64, s30, 0x80
	s_addc_u32 s65, s31, 0
	v_mfma_f32_16x16x32_bf16 v[86:89], v[172:175], v[216:219], v[86:89]
	v_mfma_f32_16x16x32_bf16 v[82:85], v[188:191], v[216:219], v[82:85]
	v_mfma_f32_16x16x32_bf16 v[70:73], v[172:175], v[224:227], v[70:73]
	v_mfma_f32_16x16x32_bf16 v[66:69], v[188:191], v[224:227], v[66:69]
	s_setprio 0
	s_barrier
; #define PG8_STAGE(bufoff, gbase, X) do { _Pragma("unroll") for (int _i = 0; _i < 2; ++_i) { \
;         const char* gp_ = (const char*)(gbase) + (_i ? rs##X : (size_t)0); const unsigned la_ = (unsigned)(size_t)(lds + (bufoff) + ldsw + _i * 8192); \
;         asm volatile("s_mov_b32 m0, %2\n\ts_nop 0\n\tglobal_load_lds_dwordx4 %0, %1" :: "v"(voff##X), "s"(gp_), "s"(la_) : "memory", "m0"); } } while (0)
; #define PG8_LDA(dst, b, h) do { _Pragma("unroll") for (int m = 0; m < 4; ++m) _Pragma("unroll") for (int k = 0; k < 2; ++k) dst[m][k] = *(const LAS bf16x8*)(lds + PG8_SA(b, h) + aoff + m * 2048 + k * 1024); } while (0)
; #define PG8_WAIT_V(n) asm volatile("s_waitcnt vmcnt(" #n ")" ::: "memory")
; #define PG8_WAIT_L(n) asm volatile("s_waitcnt lgkmcnt(" #n ")" ::: "memory")
; #define PG8_BAR __builtin_amdgcn_s_barrier()
; #define PG8_SCHED __builtin_amdgcn_sched_barrier(0)
; template <class Epi>
; __device__ __forceinline__ void gemm_phase(LAS unsigned char* lds, const Gemm g_in, const StaticOrder& S, const Epi& E) {
;     ...
;             PG8_WAIT_V(8); PG8_WAIT_L(0); PG8_BAR; PG8_MMA(0, 0, At, B0); PG8_MMA(0, 1, At, B1); PG8_BAR; PG8_SCHED;
;             PG8_LDA(At, 1, 1); PG8_STAGE(PG8_SB(1, 0), b3, B); PG8_STAGE(PG8_SB(1, 1), b3 + hsB, B); PG8_STAGE(PG8_SA(1, 0), a3, A);
;             PG8_WAIT_V(8); PG8_WAIT_L(0); PG8_BAR; PG8_MMA(1, 0, At, B0); PG8_MMA(1, 1, At, B1); PG8_BAR; PG8_SCHED;
;         }
	ds_read_b128 v[192:195], v139 offset:49152
	ds_read_b128 v[196:199], v139 offset:50176
	ds_read_b128 v[204:207], v139 offset:51200
	ds_read_b128 v[208:211], v139 offset:52224
	ds_read_b128 v[212:215], v139 offset:53248
	ds_read_b128 v[216:219], v139 offset:54272
	ds_read_b128 v[220:223], v139 offset:55296
	ds_read_b128 v[224:227], v139 offset:56320
	s_mov_b32 m0, s49
	s_nop 0
	global_load_lds_dwordx4 v134, s[64:65]
	s_add_u32 s64, s30, 0x10080
	s_addc_u32 s65, s31, 0
	s_mov_b32 m0, s50
	s_nop 0
	global_load_lds_dwordx4 v134, s[64:65]
	s_add_u32 s64, s30, 0x20080
	s_addc_u32 s65, s31, 0
	s_mov_b32 m0, s53
	s_nop 0
	global_load_lds_dwordx4 v134, s[64:65]
	s_add_u32 s30, s30, 0x30080
	s_addc_u32 s31, s31, 0
	s_mov_b32 m0, s54
	s_nop 0
	global_load_lds_dwordx4 v134, s[30:31]
	s_add_u32 s26, s26, 0x20080
	s_mov_b32 m0, s51
	s_nop 0
	global_load_lds_dwordx4 v1, s[28:29]
	s_addc_u32 s27, s27, 0
	s_mov_b32 m0, s52
	s_nop 0
	global_load_lds_dwordx4 v1, s[26:27]
	s_waitcnt vmcnt(8)
	s_waitcnt lgkmcnt(0)
	s_barrier
	s_setprio 1
	s_waitcnt lgkmcnt(7)
	v_mfma_f32_16x16x32_bf16 v[62:65], v[142:145], v[192:195], v[62:65]
	v_mfma_f32_16x16x32_bf16 v[58:61], v[154:157], v[192:195], v[58:61]
	s_waitcnt lgkmcnt(5)
	v_mfma_f32_16x16x32_bf16 v[46:49], v[142:145], v[204:207], v[46:49]
	v_mfma_f32_16x16x32_bf16 v[42:45], v[154:157], v[204:207], v[42:45]
	s_waitcnt lgkmcnt(3)
	v_mfma_f32_16x16x32_bf16 v[30:33], v[142:145], v[212:215], v[30:33]
	v_mfma_f32_16x16x32_bf16 v[26:29], v[154:157], v[212:215], v[26:29]
	s_waitcnt lgkmcnt(1)
	v_mfma_f32_16x16x32_bf16 v[14:17], v[142:145], v[220:223], v[14:17]
	v_mfma_f32_16x16x32_bf16 v[10:13], v[154:157], v[220:223], v[10:13]
	v_mfma_f32_16x16x32_bf16 v[62:65], v[146:149], v[196:199], v[62:65]
	v_mfma_f32_16x16x32_bf16 v[58:61], v[158:161], v[196:199], v[58:61]
	v_mfma_f32_16x16x32_bf16 v[46:49], v[146:149], v[208:211], v[46:49]
	v_mfma_f32_16x16x32_bf16 v[42:45], v[158:161], v[208:211], v[42:45]
	v_mfma_f32_16x16x32_bf16 v[30:33], v[146:149], v[216:219], v[30:33]
	v_mfma_f32_16x16x32_bf16 v[26:29], v[158:161], v[216:219], v[26:29]
	s_waitcnt lgkmcnt(0)
	v_mfma_f32_16x16x32_bf16 v[14:17], v[146:149], v[224:227], v[14:17]
	v_mfma_f32_16x16x32_bf16 v[10:13], v[158:161], v[224:227], v[10:13]
	s_setprio 0
	s_setprio 1
	v_mfma_f32_16x16x32_bf16 v[54:57], v[168:171], v[192:195], v[54:57]
	v_mfma_f32_16x16x32_bf16 v[50:53], v[184:187], v[192:195], v[50:53]
	v_mfma_f32_16x16x32_bf16 v[38:41], v[168:171], v[204:207], v[38:41]
	v_mfma_f32_16x16x32_bf16 v[34:37], v[184:187], v[204:207], v[34:37]
	v_mfma_f32_16x16x32_bf16 v[22:25], v[168:171], v[212:215], v[22:25]
	v_mfma_f32_16x16x32_bf16 v[18:21], v[184:187], v[212:215], v[18:21]
	v_mfma_f32_16x16x32_bf16 v[6:9], v[168:171], v[220:223], v[6:9]
	v_mfma_f32_16x16x32_bf16 v[2:5], v[184:187], v[220:223], v[2:5]
	v_mfma_f32_16x16x32_bf16 v[54:57], v[172:175], v[196:199], v[54:57]
	v_mfma_f32_16x16x32_bf16 v[50:53], v[188:191], v[196:199], v[50:53]
	v_mfma_f32_16x16x32_bf16 v[38:41], v[172:175], v[208:211], v[38:41]
	v_mfma_f32_16x16x32_bf16 v[34:37], v[188:191], v[208:211], v[34:37]
	s_add_u32 s61, s61, 0x100
	s_addc_u32 s62, s62, 0
	s_add_u32 s24, s24, 0x100
	s_addc_u32 s25, s25, 0
	s_cmp_ge_i32 s63, s38
	s_mov_b32 s26, s63
	v_mfma_f32_16x16x32_bf16 v[22:25], v[172:175], v[216:219], v[22:25]
	v_mfma_f32_16x16x32_bf16 v[18:21], v[188:191], v[216:219], v[18:21]
	v_mfma_f32_16x16x32_bf16 v[6:9], v[172:175], v[224:227], v[6:9]
	v_mfma_f32_16x16x32_bf16 v[2:5], v[188:191], v[224:227], v[2:5]
	s_setprio 0
	s_barrier
	s_cbranch_scc0 .LBB0_787
	s_and_b64 vcc, exec, s[10:11]
	s_cbranch_vccz .LBB0_790

; #define PG8_STAGE(bufoff, gbase, X) do { _Pragma("unroll") for (int _i = 0; _i < 2; ++_i) { \
;         const char* gp_ = (const char*)(gbase) + (_i ? rs##X : (size_t)0); const unsigned la_ = (unsigned)(size_t)(lds + (bufoff) + ldsw + _i * 8192); \
;         asm volatile("s_mov_b32 m0, %2\n\ts_nop 0\n\tglobal_load_lds_dwordx4 %0, %1" :: "v"(voff##X), "s"(gp_), "s"(la_) : "memory", "m0"); } } while (0)
; #define PG8_LDA(dst, b, h) do { _Pragma("unroll") for (int m = 0; m < 4; ++m) _Pragma("unroll") for (int k = 0; k < 2; ++k) dst[m][k] = *(const LAS bf16x8*)(lds + PG8_SA(b, h) + aoff + m * 2048 + k * 1024); } while (0)
; #define PG8_LDB(dst, b, h) do { _Pragma("unroll") for (int n = 0; n < 2; ++n) _Pragma("unroll") for (int k = 0; k < 2; ++k) dst[n][k] = *(const LAS bf16x8*)(lds + PG8_SB(b, h) + boff + n * 2048 + k * 1024); } while (0)
; #define PG8_WAIT_V(n) asm volatile("s_waitcnt vmcnt(" #n ")" ::: "memory")
; #define PG8_WAIT_L(n) asm volatile("s_waitcnt lgkmcnt(" #n ")" ::: "memory")
; #define PG8_BAR __builtin_amdgcn_s_barrier()
; #define PG8_SCHED __builtin_amdgcn_sched_barrier(0)
; template <class Epi>
; __device__ __forceinline__ void gemm_phase(LAS unsigned char* lds, const Gemm g_in, const StaticOrder& S, const Epi& E) {
;     ...
;             const bool last = (t == nt - 2);
;             const char* a1 = cA + (size_t)(t + 1) * kstep;
;             const char* a2 = last ? nA : cA + (size_t)(t + 2) * kstep; const char* b2 = last ? nB : cB + (size_t)(t + 2) * kstep;
;             const char* a3 = a2 + kstep; const char* b3 = b2 + kstep;
;             PG8_LDB(B0, 0, 0); PG8_LDB(B1, 0, 1); PG8_SCHED; PG8_LDA(At, 0, 0); PG8_STAGE(PG8_SA(1, 1), a1 + hsA, A);
;             PG8_WAIT_V(8); PG8_WAIT_L(0); PG8_BAR; PG8_MMA(0, 0, At, B0); PG8_MMA(0, 1, At, B1); PG8_BAR; PG8_SCHED;
;             PG8_LDA(At, 0, 1); PG8_STAGE(PG8_SB(0, 0), b2, B); PG8_STAGE(PG8_SB(0, 1), b2 + hsB, B); PG8_STAGE(PG8_SA(0, 0), a2, A);
;             PG8_WAIT_V(8); PG8_WAIT_L(0); PG8_BAR; PG8_MMA(1, 0, At, B0); PG8_MMA(1, 1, At, B1); PG8_BAR; PG8_SCHED;
.LBB0_1254:
	ds_read_b128 v[130:133], v169
	ds_read_b128 v[134:137], v169 offset:1024
	ds_read_b128 v[138:141], v169 offset:2048
	ds_read_b128 v[142:145], v169 offset:3072
	ds_read_b128 v[146:149], v170
	ds_read_b128 v[154:157], v170 offset:1024
	ds_read_b128 v[158:161], v170 offset:2048
	ds_read_b128 v[162:165], v170 offset:3072
	s_add_i32 s62, s28, 2
	s_add_u32 s30, s26, 0xfff40080
	s_addc_u32 s29, s27, -1
	s_cmp_eq_u32 s55, s28
	s_cselect_b32 s28, s21, s30
	s_cselect_b32 s29, s19, s29
	s_cselect_b32 s34, s59, s60
	s_cselect_b32 s35, s58, s61
	s_add_u32 s30, s28, 0x80
	s_addc_u32 s31, s29, 0
	ds_read_b128 v[174:177], v171
	ds_read_b128 v[184:187], v171 offset:1024
	ds_read_b128 v[188:191], v171 offset:2048
	ds_read_b128 v[192:195], v171 offset:3072
	ds_read_b128 v[196:199], v171 offset:4096
	ds_read_b128 v[204:207], v171 offset:5120
	ds_read_b128 v[208:211], v171 offset:6144
	ds_read_b128 v[212:215], v171 offset:7168
	s_add_u32 s64, s26, 0xfffc0000
	s_addc_u32 s65, s27, -1
	s_mov_b32 m0, s56
	s_nop 0
	global_load_lds_dwordx4 v1, s[64:65]
	s_nop 0
	s_mov_b32 m0, s57
	s_nop 0
	global_load_lds_dwordx4 v1, s[26:27]
	s_waitcnt vmcnt(8)
	s_waitcnt lgkmcnt(0)
	s_barrier
	s_setprio 1
	s_waitcnt lgkmcnt(7)
	v_mfma_f32_16x16x32_bf16 v[126:129], v[130:133], v[174:177], v[126:129]
	v_mfma_f32_16x16x32_bf16 v[122:125], v[138:141], v[174:177], v[122:125]
	s_waitcnt lgkmcnt(5)
	v_mfma_f32_16x16x32_bf16 v[110:113], v[130:133], v[188:191], v[110:113]
	v_mfma_f32_16x16x32_bf16 v[106:109], v[138:141], v[188:191], v[106:109]
	s_waitcnt lgkmcnt(3)
	v_mfma_f32_16x16x32_bf16 v[94:97], v[130:133], v[196:199], v[94:97]
	v_mfma_f32_16x16x32_bf16 v[90:93], v[138:141], v[196:199], v[90:93]
	s_waitcnt lgkmcnt(1)
	v_mfma_f32_16x16x32_bf16 v[78:81], v[130:133], v[208:211], v[78:81]
	v_mfma_f32_16x16x32_bf16 v[74:77], v[138:141], v[208:211], v[74:77]
	v_mfma_f32_16x16x32_bf16 v[126:129], v[134:137], v[184:187], v[126:129]
	v_mfma_f32_16x16x32_bf16 v[122:125], v[142:145], v[184:187], v[122:125]
	v_mfma_f32_16x16x32_bf16 v[110:113], v[134:137], v[192:195], v[110:113]
	v_mfma_f32_16x16x32_bf16 v[106:109], v[142:145], v[192:195], v[106:109]
	v_mfma_f32_16x16x32_bf16 v[94:97], v[134:137], v[204:207], v[94:97]
	v_mfma_f32_16x16x32_bf16 v[90:93], v[142:145], v[204:207], v[90:93]
	s_waitcnt lgkmcnt(0)
	v_mfma_f32_16x16x32_bf16 v[78:81], v[134:137], v[212:215], v[78:81]
	v_mfma_f32_16x16x32_bf16 v[74:77], v[142:145], v[212:215], v[74:77]
	s_setprio 0
	s_setprio 1
	v_mfma_f32_16x16x32_bf16 v[118:121], v[146:149], v[174:177], v[118:121]
	v_mfma_f32_16x16x32_bf16 v[114:117], v[158:161], v[174:177], v[114:117]
	v_mfma_f32_16x16x32_bf16 v[102:105], v[146:149], v[188:191], v[102:105]
	v_mfma_f32_16x16x32_bf16 v[98:101], v[158:161], v[188:191], v[98:101]
	v_mfma_f32_16x16x32_bf16 v[86:89], v[146:149], v[196:199], v[86:89]
	v_mfma_f32_16x16x32_bf16 v[82:85], v[158:161], v[196:199], v[82:85]
	v_mfma_f32_16x16x32_bf16 v[70:73], v[146:149], v[208:211], v[70:73]
	v_mfma_f32_16x16x32_bf16 v[66:69], v[158:161], v[208:211], v[66:69]
	v_mfma_f32_16x16x32_bf16 v[118:121], v[154:157], v[184:187], v[118:121]
	v_mfma_f32_16x16x32_bf16 v[114:117], v[162:165], v[184:187], v[114:117]
	v_mfma_f32_16x16x32_bf16 v[102:105], v[154:157], v[192:195], v[102:105]
	v_mfma_f32_16x16x32_bf16 v[98:101], v[162:165], v[192:195], v[98:101]
	s_add_u32 s64, s34, 0x40000
	v_mfma_f32_16x16x32_bf16 v[86:89], v[154:157], v[204:207], v[86:89]
	v_mfma_f32_16x16x32_bf16 v[82:85], v[162:165], v[204:207], v[82:85]
	v_mfma_f32_16x16x32_bf16 v[70:73], v[154:157], v[212:215], v[70:73]
	v_mfma_f32_16x16x32_bf16 v[66:69], v[162:165], v[212:215], v[66:69]
	s_setprio 0
	s_barrier
	ds_read_b128 v[174:177], v171 offset:16384
	ds_read_b128 v[184:187], v171 offset:17408
	ds_read_b128 v[188:191], v171 offset:18432
	ds_read_b128 v[192:195], v171 offset:19456
	ds_read_b128 v[196:199], v171 offset:20480
	ds_read_b128 v[204:207], v171 offset:21504
	ds_read_b128 v[208:211], v171 offset:22528
	ds_read_b128 v[212:215], v171 offset:23552
	s_mov_b32 m0, s42
	s_nop 0
	global_load_lds_dwordx4 v166, s[34:35]
	s_addc_u32 s65, s35, 0
	s_mov_b32 m0, s43
	s_nop 0
	global_load_lds_dwordx4 v166, s[64:65]
	s_add_u32 s64, s34, 0x80000
	s_addc_u32 s65, s35, 0
	s_mov_b32 m0, s44
	s_nop 0
	global_load_lds_dwordx4 v166, s[64:65]
	s_add_u32 s64, s34, 0xc0000
	s_addc_u32 s65, s35, 0
	s_mov_b32 m0, s45
	s_nop 0
	global_load_lds_dwordx4 v166, s[64:65]
	s_add_u32 s64, s28, 0x40000
	s_mov_b32 m0, s41
	s_nop 0
	global_load_lds_dwordx4 v1, s[28:29]
	s_addc_u32 s65, s29, 0
	s_mov_b32 m0, s46
	s_nop 0
	global_load_lds_dwordx4 v1, s[64:65]
	s_waitcnt vmcnt(8)
	s_waitcnt lgkmcnt(0)
	s_barrier
; #define PG8_STAGE(bufoff, gbase, X) do { _Pragma("unroll") for (int _i = 0; _i < 2; ++_i) { \
;         const char* gp_ = (const char*)(gbase) + (_i ? rs##X : (size_t)0); const unsigned la_ = (unsigned)(size_t)(lds + (bufoff) + ldsw + _i * 8192); \
;         asm volatile("s_mov_b32 m0, %2\n\ts_nop 0\n\tglobal_load_lds_dwordx4 %0, %1" :: "v"(voff##X), "s"(gp_), "s"(la_) : "memory", "m0"); } } while (0)
; #define PG8_LDA(dst, b, h) do { _Pragma("unroll") for (int m = 0; m < 4; ++m) _Pragma("unroll") for (int k = 0; k < 2; ++k) dst[m][k] = *(const LAS bf16x8*)(lds + PG8_SA(b, h) + aoff + m * 2048 + k * 1024); } while (0)
; #define PG8_LDB(dst, b, h) do { _Pragma("unroll") for (int n = 0; n < 2; ++n) _Pragma("unroll") for (int k = 0; k < 2; ++k) dst[n][k] = *(const LAS bf16x8*)(lds + PG8_SB(b, h) + boff + n * 2048 + k * 1024); } while (0)
; #define PG8_WAIT_V(n) asm volatile("s_waitcnt vmcnt(" #n ")" ::: "memory")
; #define PG8_WAIT_L(n) asm volatile("s_waitcnt lgkmcnt(" #n ")" ::: "memory")
; #define PG8_BAR __builtin_amdgcn_s_barrier()
; #define PG8_SCHED __builtin_amdgcn_sched_barrier(0)
; template <class Epi>
; __device__ __forceinline__ void gemm_phase(LAS unsigned char* lds, const Gemm g_in, const StaticOrder& S, const Epi& E) {
;     ...
;             PG8_LDA(At, 0, 1); PG8_STAGE(PG8_SB(0, 0), b2, B); PG8_STAGE(PG8_SB(0, 1), b2 + hsB, B); PG8_STAGE(PG8_SA(0, 0), a2, A);
;             PG8_WAIT_V(8); PG8_WAIT_L(0); PG8_BAR; PG8_MMA(1, 0, At, B0); PG8_MMA(1, 1, At, B1); PG8_BAR; PG8_SCHED;
;             PG8_LDB(B0, 1, 0); PG8_LDB(B1, 1, 1); PG8_SCHED; PG8_LDA(At, 1, 0); PG8_STAGE(PG8_SA(0, 1), a2 + hsA, A);
;             PG8_WAIT_V(8); PG8_WAIT_L(0); PG8_BAR; PG8_MMA(0, 0, At, B0); PG8_MMA(0, 1, At, B1); PG8_BAR; PG8_SCHED;
	s_setprio 1
	s_waitcnt lgkmcnt(7)
	v_mfma_f32_16x16x32_bf16 v[62:65], v[130:133], v[174:177], v[62:65]
	v_mfma_f32_16x16x32_bf16 v[58:61], v[138:141], v[174:177], v[58:61]
	s_waitcnt lgkmcnt(5)
	v_mfma_f32_16x16x32_bf16 v[46:49], v[130:133], v[188:191], v[46:49]
	v_mfma_f32_16x16x32_bf16 v[42:45], v[138:141], v[188:191], v[42:45]
	s_waitcnt lgkmcnt(3)
	v_mfma_f32_16x16x32_bf16 v[30:33], v[130:133], v[196:199], v[30:33]
	v_mfma_f32_16x16x32_bf16 v[26:29], v[138:141], v[196:199], v[26:29]
	s_waitcnt lgkmcnt(1)
	v_mfma_f32_16x16x32_bf16 v[14:17], v[130:133], v[208:211], v[14:17]
	v_mfma_f32_16x16x32_bf16 v[10:13], v[138:141], v[208:211], v[10:13]
	v_mfma_f32_16x16x32_bf16 v[62:65], v[134:137], v[184:187], v[62:65]
	v_mfma_f32_16x16x32_bf16 v[58:61], v[142:145], v[184:187], v[58:61]
	v_mfma_f32_16x16x32_bf16 v[46:49], v[134:137], v[192:195], v[46:49]
	v_mfma_f32_16x16x32_bf16 v[42:45], v[142:145], v[192:195], v[42:45]
	v_mfma_f32_16x16x32_bf16 v[30:33], v[134:137], v[204:207], v[30:33]
	v_mfma_f32_16x16x32_bf16 v[26:29], v[142:145], v[204:207], v[26:29]
	s_waitcnt lgkmcnt(0)
	v_mfma_f32_16x16x32_bf16 v[14:17], v[134:137], v[212:215], v[14:17]
	v_mfma_f32_16x16x32_bf16 v[10:13], v[142:145], v[212:215], v[10:13]
	s_setprio 0
	s_setprio 1
	v_mfma_f32_16x16x32_bf16 v[54:57], v[146:149], v[174:177], v[54:57]
	v_mfma_f32_16x16x32_bf16 v[50:53], v[158:161], v[174:177], v[50:53]
	v_mfma_f32_16x16x32_bf16 v[38:41], v[146:149], v[188:191], v[38:41]
	v_mfma_f32_16x16x32_bf16 v[34:37], v[158:161], v[188:191], v[34:37]
	v_mfma_f32_16x16x32_bf16 v[22:25], v[146:149], v[196:199], v[22:25]
	v_mfma_f32_16x16x32_bf16 v[18:21], v[158:161], v[196:199], v[18:21]
	v_mfma_f32_16x16x32_bf16 v[6:9], v[146:149], v[208:211], v[6:9]
	v_mfma_f32_16x16x32_bf16 v[2:5], v[158:161], v[208:211], v[2:5]
	v_mfma_f32_16x16x32_bf16 v[54:57], v[154:157], v[184:187], v[54:57]
	v_mfma_f32_16x16x32_bf16 v[50:53], v[162:165], v[184:187], v[50:53]
	v_mfma_f32_16x16x32_bf16 v[38:41], v[154:157], v[192:195], v[38:41]
	v_mfma_f32_16x16x32_bf16 v[34:37], v[162:165], v[192:195], v[34:37]
	v_mfma_f32_16x16x32_bf16 v[22:25], v[154:157], v[204:207], v[22:25]
	v_mfma_f32_16x16x32_bf16 v[18:21], v[162:165], v[204:207], v[18:21]
	v_mfma_f32_16x16x32_bf16 v[6:9], v[154:157], v[212:215], v[6:9]
	v_mfma_f32_16x16x32_bf16 v[2:5], v[162:165], v[212:215], v[2:5]
	s_setprio 0
	s_barrier
	ds_read_b128 v[130:133], v172
	ds_read_b128 v[134:137], v172 offset:1024
	ds_read_b128 v[138:141], v172 offset:2048
	ds_read_b128 v[142:145], v172 offset:3072
	ds_read_b128 v[146:149], v173
	ds_read_b128 v[154:157], v173 offset:1024
	ds_read_b128 v[158:161], v173 offset:2048
	ds_read_b128 v[162:165], v173 offset:3072
	ds_read_b128 v[174:177], v171 offset:32768
	ds_read_b128 v[184:187], v171 offset:33792
	ds_read_b128 v[188:191], v171 offset:34816
	ds_read_b128 v[192:195], v171 offset:35840
	ds_read_b128 v[196:199], v171 offset:36864
	ds_read_b128 v[204:207], v171 offset:37888
	ds_read_b128 v[208:211], v171 offset:38912
	ds_read_b128 v[212:215], v171 offset:39936
	s_add_u32 s64, s28, 0x80000
	s_addc_u32 s65, s29, 0
	s_mov_b32 m0, s47
	s_nop 0
	global_load_lds_dwordx4 v1, s[64:65]
	s_add_u32 s64, s28, 0xc0000
	s_addc_u32 s65, s29, 0
	s_mov_b32 m0, s48
	s_nop 0
	global_load_lds_dwordx4 v1, s[64:65]
	s_waitcnt vmcnt(8)
	s_waitcnt lgkmcnt(0)
	s_barrier
	s_setprio 1
	s_waitcnt lgkmcnt(7)
	v_mfma_f32_16x16x32_bf16 v[126:129], v[130:133], v[174:177], v[126:129]
	v_mfma_f32_16x16x32_bf16 v[122:125], v[138:141], v[174:177], v[122:125]
	s_waitcnt lgkmcnt(5)
	v_mfma_f32_16x16x32_bf16 v[110:113], v[130:133], v[188:191], v[110:113]
	v_mfma_f32_16x16x32_bf16 v[106:109], v[138:141], v[188:191], v[106:109]
	s_waitcnt lgkmcnt(3)
	v_mfma_f32_16x16x32_bf16 v[94:97], v[130:133], v[196:199], v[94:97]
	v_mfma_f32_16x16x32_bf16 v[90:93], v[138:141], v[196:199], v[90:93]
	s_waitcnt lgkmcnt(1)
	v_mfma_f32_16x16x32_bf16 v[78:81], v[130:133], v[208:211], v[78:81]
	v_mfma_f32_16x16x32_bf16 v[74:77], v[138:141], v[208:211], v[74:77]
	v_mfma_f32_16x16x32_bf16 v[126:129], v[134:137], v[184:187], v[126:129]
	v_mfma_f32_16x16x32_bf16 v[122:125], v[142:145], v[184:187], v[122:125]
	v_mfma_f32_16x16x32_bf16 v[110:113], v[134:137], v[192:195], v[110:113]
	v_mfma_f32_16x16x32_bf16 v[106:109], v[142:145], v[192:195], v[106:109]
	v_mfma_f32_16x16x32_bf16 v[94:97], v[134:137], v[204:207], v[94:97]
	v_mfma_f32_16x16x32_bf16 v[90:93], v[142:145], v[204:207], v[90:93]
	s_waitcnt lgkmcnt(0)
	v_mfma_f32_16x16x32_bf16 v[78:81], v[134:137], v[212:215], v[78:81]
	v_mfma_f32_16x16x32_bf16 v[74:77], v[142:145], v[212:215], v[74:77]
	s_setprio 0
	s_setprio 1
	v_mfma_f32_16x16x32_bf16 v[118:121], v[146:149], v[174:177], v[118:121]
	v_mfma_f32_16x16x32_bf16 v[114:117], v[158:161], v[174:177], v[114:117]
	v_mfma_f32_16x16x32_bf16 v[102:105], v[146:149], v[188:191], v[102:105]
	v_mfma_f32_16x16x32_bf16 v[98:101], v[158:161], v[188:191], v[98:101]
	v_mfma_f32_16x16x32_bf16 v[86:89], v[146:149], v[196:199], v[86:89]
	v_mfma_f32_16x16x32_bf16 v[82:85], v[158:161], v[196:199], v[82:85]
	v_mfma_f32_16x16x32_bf16 v[70:73], v[146:149], v[208:211], v[70:73]
	v_mfma_f32_16x16x32_bf16 v[66:69], v[158:161], v[208:211], v[66:69]
	v_mfma_f32_16x16x32_bf16 v[118:121], v[154:157], v[184:187], v[118:121]
	v_mfma_f32_16x16x32_bf16 v[114:117], v[162:165], v[184:187], v[114:117]
	v_mfma_f32_16x16x32_bf16 v[102:105], v[154:157], v[192:195], v[102:105]
	v_mfma_f32_16x16x32_bf16 v[98:101], v[162:165], v[192:195], v[98:101]
	s_add_u32 s64, s34, 0x80
	s_addc_u32 s65, s35, 0
	v_mfma_f32_16x16x32_bf16 v[86:89], v[154:157], v[204:207], v[86:89]
	v_mfma_f32_16x16x32_bf16 v[82:85], v[162:165], v[204:207], v[82:85]
	v_mfma_f32_16x16x32_bf16 v[70:73], v[154:157], v[212:215], v[70:73]
	v_mfma_f32_16x16x32_bf16 v[66:69], v[162:165], v[212:215], v[66:69]
	s_setprio 0
	s_barrier
; #define PG8_STAGE(bufoff, gbase, X) do { _Pragma("unroll") for (int _i = 0; _i < 2; ++_i) { \
;         const char* gp_ = (const char*)(gbase) + (_i ? rs##X : (size_t)0); const unsigned la_ = (unsigned)(size_t)(lds + (bufoff) + ldsw + _i * 8192); \
;         asm volatile("s_mov_b32 m0, %2\n\ts_nop 0\n\tglobal_load_lds_dwordx4 %0, %1" :: "v"(voff##X), "s"(gp_), "s"(la_) : "memory", "m0"); } } while (0)
; #define PG8_LDA(dst, b, h) do { _Pragma("unroll") for (int m = 0; m < 4; ++m) _Pragma("unroll") for (int k = 0; k < 2; ++k) dst[m][k] = *(const LAS bf16x8*)(lds + PG8_SA(b, h) + aoff + m * 2048 + k * 1024); } while (0)
; #define PG8_WAIT_V(n) asm volatile("s_waitcnt vmcnt(" #n ")" ::: "memory")
; #define PG8_WAIT_L(n) asm volatile("s_waitcnt lgkmcnt(" #n ")" ::: "memory")
; #define PG8_BAR __builtin_amdgcn_s_barrier()
; #define PG8_SCHED __builtin_amdgcn_sched_barrier(0)
; template <class Epi>
; __device__ __forceinline__ void gemm_phase(LAS unsigned char* lds, const Gemm g_in, const StaticOrder& S, const Epi& E) {
;     ...
;             PG8_WAIT_V(8); PG8_WAIT_L(0); PG8_BAR; PG8_MMA(0, 0, At, B0); PG8_MMA(0, 1, At, B1); PG8_BAR; PG8_SCHED;
;             PG8_LDA(At, 1, 1); PG8_STAGE(PG8_SB(1, 0), b3, B); PG8_STAGE(PG8_SB(1, 1), b3 + hsB, B); PG8_STAGE(PG8_SA(1, 0), a3, A);
;             PG8_WAIT_V(8); PG8_WAIT_L(0); PG8_BAR; PG8_MMA(1, 0, At, B0); PG8_MMA(1, 1, At, B1); PG8_BAR; PG8_SCHED;
;         }
	ds_read_b128 v[174:177], v171 offset:49152
	ds_read_b128 v[184:187], v171 offset:50176
	ds_read_b128 v[188:191], v171 offset:51200
	ds_read_b128 v[192:195], v171 offset:52224
	ds_read_b128 v[196:199], v171 offset:53248
	ds_read_b128 v[204:207], v171 offset:54272
	ds_read_b128 v[208:211], v171 offset:55296
	ds_read_b128 v[212:215], v171 offset:56320
	s_mov_b32 m0, s49
	s_nop 0
	global_load_lds_dwordx4 v166, s[64:65]
	s_add_u32 s64, s34, 0x40080
	s_addc_u32 s65, s35, 0
	s_mov_b32 m0, s50
	s_nop 0
	global_load_lds_dwordx4 v166, s[64:65]
	s_add_u32 s64, s34, 0x80080
	s_addc_u32 s65, s35, 0
	s_mov_b32 m0, s53
	s_nop 0
	global_load_lds_dwordx4 v166, s[64:65]
	s_add_u32 s34, s34, 0xc0080
	s_addc_u32 s35, s35, 0
	s_mov_b32 m0, s54
	s_nop 0
	global_load_lds_dwordx4 v166, s[34:35]
	s_add_u32 s28, s28, 0x40080
	s_mov_b32 m0, s51
	s_nop 0
	global_load_lds_dwordx4 v1, s[30:31]
	s_addc_u32 s29, s29, 0
	s_mov_b32 m0, s52
	s_nop 0
	global_load_lds_dwordx4 v1, s[28:29]
	s_waitcnt vmcnt(8)
	s_waitcnt lgkmcnt(0)
	s_barrier
	s_setprio 1
	s_waitcnt lgkmcnt(7)
	v_mfma_f32_16x16x32_bf16 v[62:65], v[130:133], v[174:177], v[62:65]
	v_mfma_f32_16x16x32_bf16 v[58:61], v[138:141], v[174:177], v[58:61]
	s_waitcnt lgkmcnt(5)
	v_mfma_f32_16x16x32_bf16 v[46:49], v[130:133], v[188:191], v[46:49]
	v_mfma_f32_16x16x32_bf16 v[42:45], v[138:141], v[188:191], v[42:45]
	s_waitcnt lgkmcnt(3)
	v_mfma_f32_16x16x32_bf16 v[30:33], v[130:133], v[196:199], v[30:33]
	v_mfma_f32_16x16x32_bf16 v[26:29], v[138:141], v[196:199], v[26:29]
	s_waitcnt lgkmcnt(1)
	v_mfma_f32_16x16x32_bf16 v[14:17], v[130:133], v[208:211], v[14:17]
	v_mfma_f32_16x16x32_bf16 v[10:13], v[138:141], v[208:211], v[10:13]
	v_mfma_f32_16x16x32_bf16 v[62:65], v[134:137], v[184:187], v[62:65]
	v_mfma_f32_16x16x32_bf16 v[58:61], v[142:145], v[184:187], v[58:61]
	v_mfma_f32_16x16x32_bf16 v[46:49], v[134:137], v[192:195], v[46:49]
	v_mfma_f32_16x16x32_bf16 v[42:45], v[142:145], v[192:195], v[42:45]
	v_mfma_f32_16x16x32_bf16 v[30:33], v[134:137], v[204:207], v[30:33]
	v_mfma_f32_16x16x32_bf16 v[26:29], v[142:145], v[204:207], v[26:29]
	s_waitcnt lgkmcnt(0)
	v_mfma_f32_16x16x32_bf16 v[14:17], v[134:137], v[212:215], v[14:17]
	v_mfma_f32_16x16x32_bf16 v[10:13], v[142:145], v[212:215], v[10:13]
	s_setprio 0
	s_setprio 1
	v_mfma_f32_16x16x32_bf16 v[54:57], v[146:149], v[174:177], v[54:57]
	v_mfma_f32_16x16x32_bf16 v[50:53], v[158:161], v[174:177], v[50:53]
	v_mfma_f32_16x16x32_bf16 v[38:41], v[146:149], v[188:191], v[38:41]
	v_mfma_f32_16x16x32_bf16 v[34:37], v[158:161], v[188:191], v[34:37]
	v_mfma_f32_16x16x32_bf16 v[22:25], v[146:149], v[196:199], v[22:25]
	v_mfma_f32_16x16x32_bf16 v[18:21], v[158:161], v[196:199], v[18:21]
	v_mfma_f32_16x16x32_bf16 v[6:9], v[146:149], v[208:211], v[6:9]
	v_mfma_f32_16x16x32_bf16 v[2:5], v[158:161], v[208:211], v[2:5]
	v_mfma_f32_16x16x32_bf16 v[54:57], v[154:157], v[184:187], v[54:57]
	v_mfma_f32_16x16x32_bf16 v[50:53], v[162:165], v[184:187], v[50:53]
	v_mfma_f32_16x16x32_bf16 v[38:41], v[154:157], v[192:195], v[38:41]
	v_mfma_f32_16x16x32_bf16 v[34:37], v[162:165], v[192:195], v[34:37]
	s_add_u32 s60, s60, 0x100
	s_addc_u32 s61, s61, 0
	s_add_u32 s26, s26, 0x100
	s_addc_u32 s27, s27, 0
	s_cmp_ge_i32 s62, s38
	s_mov_b32 s28, s62
	v_mfma_f32_16x16x32_bf16 v[22:25], v[154:157], v[204:207], v[22:25]
	v_mfma_f32_16x16x32_bf16 v[18:21], v[162:165], v[204:207], v[18:21]
	v_mfma_f32_16x16x32_bf16 v[6:9], v[154:157], v[212:215], v[6:9]
	v_mfma_f32_16x16x32_bf16 v[2:5], v[162:165], v[212:215], v[2:5]
	s_setprio 0
	s_barrier
	s_cbranch_scc0 .LBB0_1254
	s_and_b64 vcc, exec, s[16:17]
	s_cbranch_vccz .LBB0_1257

; #define PG8_STAGE(bufoff, gbase, X) do { _Pragma("unroll") for (int _i = 0; _i < 2; ++_i) { \
;         const char* gp_ = (const char*)(gbase) + (_i ? rs##X : (size_t)0); const unsigned la_ = (unsigned)(size_t)(lds + (bufoff) + ldsw + _i * 8192); \
;         asm volatile("s_mov_b32 m0, %2\n\ts_nop 0\n\tglobal_load_lds_dwordx4 %0, %1" :: "v"(voff##X), "s"(gp_), "s"(la_) : "memory", "m0"); } } while (0)
; #define PG8_LDA(dst, b, h) do { _Pragma("unroll") for (int m = 0; m < 4; ++m) _Pragma("unroll") for (int k = 0; k < 2; ++k) dst[m][k] = *(const LAS bf16x8*)(lds + PG8_SA(b, h) + aoff + m * 2048 + k * 1024); } while (0)
; #define PG8_LDB(dst, b, h) do { _Pragma("unroll") for (int n = 0; n < 2; ++n) _Pragma("unroll") for (int k = 0; k < 2; ++k) dst[n][k] = *(const LAS bf16x8*)(lds + PG8_SB(b, h) + boff + n * 2048 + k * 1024); } while (0)
; #define PG8_WAIT_V(n) asm volatile("s_waitcnt vmcnt(" #n ")" ::: "memory")
; #define PG8_WAIT_L(n) asm volatile("s_waitcnt lgkmcnt(" #n ")" ::: "memory")
; #define PG8_BAR __builtin_amdgcn_s_barrier()
; #define PG8_SCHED __builtin_amdgcn_sched_barrier(0)
; template <class Epi>
; __device__ __forceinline__ void gemm_phase(LAS unsigned char* lds, const Gemm g_in, const StaticOrder& S, const Epi& E) {
;     ...
;             const bool last = (t == nt - 2);
;             const char* a1 = cA + (size_t)(t + 1) * kstep;
;             const char* a2 = last ? nA : cA + (size_t)(t + 2) * kstep; const char* b2 = last ? nB : cB + (size_t)(t + 2) * kstep;
;             const char* a3 = a2 + kstep; const char* b3 = b2 + kstep;
;             PG8_LDB(B0, 0, 0); PG8_LDB(B1, 0, 1); PG8_SCHED; PG8_LDA(At, 0, 0); PG8_STAGE(PG8_SA(1, 1), a1 + hsA, A);
;             PG8_WAIT_V(8); PG8_WAIT_L(0); PG8_BAR; PG8_MMA(0, 0, At, B0); PG8_MMA(0, 1, At, B1); PG8_BAR; PG8_SCHED;
;             PG8_LDA(At, 0, 1); PG8_STAGE(PG8_SB(0, 0), b2, B); PG8_STAGE(PG8_SB(0, 1), b2 + hsB, B); PG8_STAGE(PG8_SA(0, 0), a2, A);
;             PG8_WAIT_V(8); PG8_WAIT_L(0); PG8_BAR; PG8_MMA(1, 0, At, B0); PG8_MMA(1, 1, At, B1); PG8_BAR; PG8_SCHED;
.LBB0_1285:
	ds_read_b128 v[130:133], v205
	ds_read_b128 v[134:137], v205 offset:1024
	ds_read_b128 v[138:141], v205 offset:2048
	ds_read_b128 v[142:145], v205 offset:3072
	ds_read_b128 v[146:149], v206
	ds_read_b128 v[150:153], v206 offset:1024
	ds_read_b128 v[154:157], v206 offset:2048
	ds_read_b128 v[158:161], v206 offset:3072
	s_add_i32 s66, s34, 2
	s_add_u32 s36, s30, 0xfff40080
	s_addc_u32 s35, s31, -1
	s_cmp_eq_u32 s58, s34
	s_cselect_b32 s34, s25, s36
	s_cselect_b32 s35, s23, s35
	s_cselect_b32 s38, s63, s64
	s_cselect_b32 s39, s62, s65
	s_add_u32 s36, s34, 0x80
	s_addc_u32 s37, s35, 0
	ds_read_b128 v[162:165], v207
	ds_read_b128 v[166:169], v207 offset:1024
	ds_read_b128 v[170:173], v207 offset:2048
	ds_read_b128 v[174:177], v207 offset:3072
	ds_read_b128 v[188:191], v207 offset:4096
	ds_read_b128 v[192:195], v207 offset:5120
	ds_read_b128 v[196:199], v207 offset:6144
	ds_read_b128 v[212:215], v207 offset:7168
	s_add_u32 s68, s30, 0xfffc0000
	s_addc_u32 s69, s31, -1
	s_mov_b32 m0, s59
	s_nop 0
	global_load_lds_dwordx4 v1, s[68:69]
	s_nop 0
	s_mov_b32 m0, s60
	s_nop 0
	global_load_lds_dwordx4 v1, s[30:31]
	s_waitcnt vmcnt(8)
	s_waitcnt lgkmcnt(0)
	s_barrier
	s_setprio 1
	s_waitcnt lgkmcnt(7)
	v_mfma_f32_16x16x32_bf16 v[126:129], v[130:133], v[162:165], v[126:129]
	v_mfma_f32_16x16x32_bf16 v[122:125], v[138:141], v[162:165], v[122:125]
	s_waitcnt lgkmcnt(5)
	v_mfma_f32_16x16x32_bf16 v[110:113], v[130:133], v[170:173], v[110:113]
	v_mfma_f32_16x16x32_bf16 v[106:109], v[138:141], v[170:173], v[106:109]
	s_waitcnt lgkmcnt(3)
	v_mfma_f32_16x16x32_bf16 v[94:97], v[130:133], v[188:191], v[94:97]
	v_mfma_f32_16x16x32_bf16 v[90:93], v[138:141], v[188:191], v[90:93]
	s_waitcnt lgkmcnt(1)
	v_mfma_f32_16x16x32_bf16 v[78:81], v[130:133], v[196:199], v[78:81]
	v_mfma_f32_16x16x32_bf16 v[74:77], v[138:141], v[196:199], v[74:77]
	v_mfma_f32_16x16x32_bf16 v[126:129], v[134:137], v[166:169], v[126:129]
	v_mfma_f32_16x16x32_bf16 v[122:125], v[142:145], v[166:169], v[122:125]
	v_mfma_f32_16x16x32_bf16 v[110:113], v[134:137], v[174:177], v[110:113]
	v_mfma_f32_16x16x32_bf16 v[106:109], v[142:145], v[174:177], v[106:109]
	v_mfma_f32_16x16x32_bf16 v[94:97], v[134:137], v[192:195], v[94:97]
	v_mfma_f32_16x16x32_bf16 v[90:93], v[142:145], v[192:195], v[90:93]
	s_waitcnt lgkmcnt(0)
	v_mfma_f32_16x16x32_bf16 v[78:81], v[134:137], v[212:215], v[78:81]
	v_mfma_f32_16x16x32_bf16 v[74:77], v[142:145], v[212:215], v[74:77]
	s_setprio 0
	s_setprio 1
	v_mfma_f32_16x16x32_bf16 v[118:121], v[146:149], v[162:165], v[118:121]
	v_mfma_f32_16x16x32_bf16 v[114:117], v[154:157], v[162:165], v[114:117]
	v_mfma_f32_16x16x32_bf16 v[102:105], v[146:149], v[170:173], v[102:105]
	v_mfma_f32_16x16x32_bf16 v[98:101], v[154:157], v[170:173], v[98:101]
	v_mfma_f32_16x16x32_bf16 v[86:89], v[146:149], v[188:191], v[86:89]
	v_mfma_f32_16x16x32_bf16 v[82:85], v[154:157], v[188:191], v[82:85]
	v_mfma_f32_16x16x32_bf16 v[70:73], v[146:149], v[196:199], v[70:73]
	v_mfma_f32_16x16x32_bf16 v[66:69], v[154:157], v[196:199], v[66:69]
	v_mfma_f32_16x16x32_bf16 v[118:121], v[150:153], v[166:169], v[118:121]
	v_mfma_f32_16x16x32_bf16 v[114:117], v[158:161], v[166:169], v[114:117]
	v_mfma_f32_16x16x32_bf16 v[102:105], v[150:153], v[174:177], v[102:105]
	v_mfma_f32_16x16x32_bf16 v[98:101], v[158:161], v[174:177], v[98:101]
	s_add_u32 s68, s38, 0x40000
	v_mfma_f32_16x16x32_bf16 v[86:89], v[150:153], v[192:195], v[86:89]
	v_mfma_f32_16x16x32_bf16 v[82:85], v[158:161], v[192:195], v[82:85]
	v_mfma_f32_16x16x32_bf16 v[70:73], v[150:153], v[212:215], v[70:73]
	v_mfma_f32_16x16x32_bf16 v[66:69], v[158:161], v[212:215], v[66:69]
	s_setprio 0
	s_barrier
	ds_read_b128 v[162:165], v207 offset:16384
	ds_read_b128 v[166:169], v207 offset:17408
	ds_read_b128 v[170:173], v207 offset:18432
	ds_read_b128 v[174:177], v207 offset:19456
	ds_read_b128 v[188:191], v207 offset:20480
	ds_read_b128 v[192:195], v207 offset:21504
	ds_read_b128 v[196:199], v207 offset:22528
	ds_read_b128 v[212:215], v207 offset:23552
	s_mov_b32 m0, s45
	s_nop 0
	global_load_lds_dwordx4 v179, s[38:39]
	s_addc_u32 s69, s39, 0
	s_mov_b32 m0, s46
	s_nop 0
	global_load_lds_dwordx4 v179, s[68:69]
	s_add_u32 s68, s38, 0x80000
	s_addc_u32 s69, s39, 0
	s_mov_b32 m0, s47
	s_nop 0
	global_load_lds_dwordx4 v179, s[68:69]
	s_add_u32 s68, s38, 0xc0000
	s_addc_u32 s69, s39, 0
	s_mov_b32 m0, s48
	s_nop 0
	global_load_lds_dwordx4 v179, s[68:69]
	s_add_u32 s68, s34, 0x40000
	s_mov_b32 m0, s44
	s_nop 0
	global_load_lds_dwordx4 v1, s[34:35]
	s_addc_u32 s69, s35, 0
	s_mov_b32 m0, s49
	s_nop 0
	global_load_lds_dwordx4 v1, s[68:69]
	s_waitcnt vmcnt(8)
	s_waitcnt lgkmcnt(0)
	s_barrier
; #define PG8_STAGE(bufoff, gbase, X) do { _Pragma("unroll") for (int _i = 0; _i < 2; ++_i) { \
;         const char* gp_ = (const char*)(gbase) + (_i ? rs##X : (size_t)0); const unsigned la_ = (unsigned)(size_t)(lds + (bufoff) + ldsw + _i * 8192); \
;         asm volatile("s_mov_b32 m0, %2\n\ts_nop 0\n\tglobal_load_lds_dwordx4 %0, %1" :: "v"(voff##X), "s"(gp_), "s"(la_) : "memory", "m0"); } } while (0)
; #define PG8_LDA(dst, b, h) do { _Pragma("unroll") for (int m = 0; m < 4; ++m) _Pragma("unroll") for (int k = 0; k < 2; ++k) dst[m][k] = *(const LAS bf16x8*)(lds + PG8_SA(b, h) + aoff + m * 2048 + k * 1024); } while (0)
; #define PG8_LDB(dst, b, h) do { _Pragma("unroll") for (int n = 0; n < 2; ++n) _Pragma("unroll") for (int k = 0; k < 2; ++k) dst[n][k] = *(const LAS bf16x8*)(lds + PG8_SB(b, h) + boff + n * 2048 + k * 1024); } while (0)
; #define PG8_WAIT_V(n) asm volatile("s_waitcnt vmcnt(" #n ")" ::: "memory")
; #define PG8_WAIT_L(n) asm volatile("s_waitcnt lgkmcnt(" #n ")" ::: "memory")
; #define PG8_BAR __builtin_amdgcn_s_barrier()
; #define PG8_SCHED __builtin_amdgcn_sched_barrier(0)
; template <class Epi>
; __device__ __forceinline__ void gemm_phase(LAS unsigned char* lds, const Gemm g_in, const StaticOrder& S, const Epi& E) {
;     ...
;             PG8_LDA(At, 0, 1); PG8_STAGE(PG8_SB(0, 0), b2, B); PG8_STAGE(PG8_SB(0, 1), b2 + hsB, B); PG8_STAGE(PG8_SA(0, 0), a2, A);
;             PG8_WAIT_V(8); PG8_WAIT_L(0); PG8_BAR; PG8_MMA(1, 0, At, B0); PG8_MMA(1, 1, At, B1); PG8_BAR; PG8_SCHED;
;             PG8_LDB(B0, 1, 0); PG8_LDB(B1, 1, 1); PG8_SCHED; PG8_LDA(At, 1, 0); PG8_STAGE(PG8_SA(0, 1), a2 + hsA, A);
;             PG8_WAIT_V(8); PG8_WAIT_L(0); PG8_BAR; PG8_MMA(0, 0, At, B0); PG8_MMA(0, 1, At, B1); PG8_BAR; PG8_SCHED;
	s_setprio 1
	s_waitcnt lgkmcnt(7)
	v_mfma_f32_16x16x32_bf16 v[62:65], v[130:133], v[162:165], v[62:65]
	v_mfma_f32_16x16x32_bf16 v[58:61], v[138:141], v[162:165], v[58:61]
	s_waitcnt lgkmcnt(5)
	v_mfma_f32_16x16x32_bf16 v[46:49], v[130:133], v[170:173], v[46:49]
	v_mfma_f32_16x16x32_bf16 v[42:45], v[138:141], v[170:173], v[42:45]
	s_waitcnt lgkmcnt(3)
	v_mfma_f32_16x16x32_bf16 v[30:33], v[130:133], v[188:191], v[30:33]
	v_mfma_f32_16x16x32_bf16 v[26:29], v[138:141], v[188:191], v[26:29]
	s_waitcnt lgkmcnt(1)
	v_mfma_f32_16x16x32_bf16 v[14:17], v[130:133], v[196:199], v[14:17]
	v_mfma_f32_16x16x32_bf16 v[10:13], v[138:141], v[196:199], v[10:13]
	v_mfma_f32_16x16x32_bf16 v[62:65], v[134:137], v[166:169], v[62:65]
	v_mfma_f32_16x16x32_bf16 v[58:61], v[142:145], v[166:169], v[58:61]
	v_mfma_f32_16x16x32_bf16 v[46:49], v[134:137], v[174:177], v[46:49]
	v_mfma_f32_16x16x32_bf16 v[42:45], v[142:145], v[174:177], v[42:45]
	v_mfma_f32_16x16x32_bf16 v[30:33], v[134:137], v[192:195], v[30:33]
	v_mfma_f32_16x16x32_bf16 v[26:29], v[142:145], v[192:195], v[26:29]
	s_waitcnt lgkmcnt(0)
	v_mfma_f32_16x16x32_bf16 v[14:17], v[134:137], v[212:215], v[14:17]
	v_mfma_f32_16x16x32_bf16 v[10:13], v[142:145], v[212:215], v[10:13]
	s_setprio 0
	s_setprio 1
	v_mfma_f32_16x16x32_bf16 v[54:57], v[146:149], v[162:165], v[54:57]
	v_mfma_f32_16x16x32_bf16 v[50:53], v[154:157], v[162:165], v[50:53]
	v_mfma_f32_16x16x32_bf16 v[38:41], v[146:149], v[170:173], v[38:41]
	v_mfma_f32_16x16x32_bf16 v[34:37], v[154:157], v[170:173], v[34:37]
	v_mfma_f32_16x16x32_bf16 v[22:25], v[146:149], v[188:191], v[22:25]
	v_mfma_f32_16x16x32_bf16 v[18:21], v[154:157], v[188:191], v[18:21]
	v_mfma_f32_16x16x32_bf16 v[6:9], v[146:149], v[196:199], v[6:9]
	v_mfma_f32_16x16x32_bf16 v[2:5], v[154:157], v[196:199], v[2:5]
	v_mfma_f32_16x16x32_bf16 v[54:57], v[150:153], v[166:169], v[54:57]
	v_mfma_f32_16x16x32_bf16 v[50:53], v[158:161], v[166:169], v[50:53]
	v_mfma_f32_16x16x32_bf16 v[38:41], v[150:153], v[174:177], v[38:41]
	v_mfma_f32_16x16x32_bf16 v[34:37], v[158:161], v[174:177], v[34:37]
	v_mfma_f32_16x16x32_bf16 v[22:25], v[150:153], v[192:195], v[22:25]
	v_mfma_f32_16x16x32_bf16 v[18:21], v[158:161], v[192:195], v[18:21]
	v_mfma_f32_16x16x32_bf16 v[6:9], v[150:153], v[212:215], v[6:9]
	v_mfma_f32_16x16x32_bf16 v[2:5], v[158:161], v[212:215], v[2:5]
	s_setprio 0
	s_barrier
	ds_read_b128 v[130:133], v208
	ds_read_b128 v[134:137], v208 offset:1024
	ds_read_b128 v[138:141], v208 offset:2048
	ds_read_b128 v[142:145], v208 offset:3072
	ds_read_b128 v[146:149], v209
	ds_read_b128 v[150:153], v209 offset:1024
	ds_read_b128 v[154:157], v209 offset:2048
	ds_read_b128 v[158:161], v209 offset:3072
	ds_read_b128 v[162:165], v207 offset:32768
	ds_read_b128 v[166:169], v207 offset:33792
	ds_read_b128 v[170:173], v207 offset:34816
	ds_read_b128 v[174:177], v207 offset:35840
	ds_read_b128 v[188:191], v207 offset:36864
	ds_read_b128 v[192:195], v207 offset:37888
	ds_read_b128 v[196:199], v207 offset:38912
	ds_read_b128 v[212:215], v207 offset:39936
	s_add_u32 s68, s34, 0x80000
	s_addc_u32 s69, s35, 0
	s_mov_b32 m0, s50
	s_nop 0
	global_load_lds_dwordx4 v1, s[68:69]
	s_add_u32 s68, s34, 0xc0000
	s_addc_u32 s69, s35, 0
	s_mov_b32 m0, s51
	s_nop 0
	global_load_lds_dwordx4 v1, s[68:69]
	s_waitcnt vmcnt(8)
	s_waitcnt lgkmcnt(0)
	s_barrier
	s_setprio 1
	s_waitcnt lgkmcnt(7)
	v_mfma_f32_16x16x32_bf16 v[126:129], v[130:133], v[162:165], v[126:129]
	v_mfma_f32_16x16x32_bf16 v[122:125], v[138:141], v[162:165], v[122:125]
	s_waitcnt lgkmcnt(5)
	v_mfma_f32_16x16x32_bf16 v[110:113], v[130:133], v[170:173], v[110:113]
	v_mfma_f32_16x16x32_bf16 v[106:109], v[138:141], v[170:173], v[106:109]
	s_waitcnt lgkmcnt(3)
	v_mfma_f32_16x16x32_bf16 v[94:97], v[130:133], v[188:191], v[94:97]
	v_mfma_f32_16x16x32_bf16 v[90:93], v[138:141], v[188:191], v[90:93]
	s_waitcnt lgkmcnt(1)
	v_mfma_f32_16x16x32_bf16 v[78:81], v[130:133], v[196:199], v[78:81]
	v_mfma_f32_16x16x32_bf16 v[74:77], v[138:141], v[196:199], v[74:77]
	v_mfma_f32_16x16x32_bf16 v[126:129], v[134:137], v[166:169], v[126:129]
	v_mfma_f32_16x16x32_bf16 v[122:125], v[142:145], v[166:169], v[122:125]
	v_mfma_f32_16x16x32_bf16 v[110:113], v[134:137], v[174:177], v[110:113]
	v_mfma_f32_16x16x32_bf16 v[106:109], v[142:145], v[174:177], v[106:109]
	v_mfma_f32_16x16x32_bf16 v[94:97], v[134:137], v[192:195], v[94:97]
	v_mfma_f32_16x16x32_bf16 v[90:93], v[142:145], v[192:195], v[90:93]
	s_waitcnt lgkmcnt(0)
	v_mfma_f32_16x16x32_bf16 v[78:81], v[134:137], v[212:215], v[78:81]
	v_mfma_f32_16x16x32_bf16 v[74:77], v[142:145], v[212:215], v[74:77]
	s_setprio 0
	s_setprio 1
	v_mfma_f32_16x16x32_bf16 v[118:121], v[146:149], v[162:165], v[118:121]
	v_mfma_f32_16x16x32_bf16 v[114:117], v[154:157], v[162:165], v[114:117]
	v_mfma_f32_16x16x32_bf16 v[102:105], v[146:149], v[170:173], v[102:105]
	v_mfma_f32_16x16x32_bf16 v[98:101], v[154:157], v[170:173], v[98:101]
	v_mfma_f32_16x16x32_bf16 v[86:89], v[146:149], v[188:191], v[86:89]
	v_mfma_f32_16x16x32_bf16 v[82:85], v[154:157], v[188:191], v[82:85]
	v_mfma_f32_16x16x32_bf16 v[70:73], v[146:149], v[196:199], v[70:73]
	v_mfma_f32_16x16x32_bf16 v[66:69], v[154:157], v[196:199], v[66:69]
	v_mfma_f32_16x16x32_bf16 v[118:121], v[150:153], v[166:169], v[118:121]
	v_mfma_f32_16x16x32_bf16 v[114:117], v[158:161], v[166:169], v[114:117]
	v_mfma_f32_16x16x32_bf16 v[102:105], v[150:153], v[174:177], v[102:105]
	v_mfma_f32_16x16x32_bf16 v[98:101], v[158:161], v[174:177], v[98:101]
	s_add_u32 s68, s38, 0x80
	s_addc_u32 s69, s39, 0
	v_mfma_f32_16x16x32_bf16 v[86:89], v[150:153], v[192:195], v[86:89]
	v_mfma_f32_16x16x32_bf16 v[82:85], v[158:161], v[192:195], v[82:85]
	v_mfma_f32_16x16x32_bf16 v[70:73], v[150:153], v[212:215], v[70:73]
	v_mfma_f32_16x16x32_bf16 v[66:69], v[158:161], v[212:215], v[66:69]
	s_setprio 0
	s_barrier
; #define PG8_STAGE(bufoff, gbase, X) do { _Pragma("unroll") for (int _i = 0; _i < 2; ++_i) { \
;         const char* gp_ = (const char*)(gbase) + (_i ? rs##X : (size_t)0); const unsigned la_ = (unsigned)(size_t)(lds + (bufoff) + ldsw + _i * 8192); \
;         asm volatile("s_mov_b32 m0, %2\n\ts_nop 0\n\tglobal_load_lds_dwordx4 %0, %1" :: "v"(voff##X), "s"(gp_), "s"(la_) : "memory", "m0"); } } while (0)
; #define PG8_LDA(dst, b, h) do { _Pragma("unroll") for (int m = 0; m < 4; ++m) _Pragma("unroll") for (int k = 0; k < 2; ++k) dst[m][k] = *(const LAS bf16x8*)(lds + PG8_SA(b, h) + aoff + m * 2048 + k * 1024); } while (0)
; #define PG8_WAIT_V(n) asm volatile("s_waitcnt vmcnt(" #n ")" ::: "memory")
; #define PG8_WAIT_L(n) asm volatile("s_waitcnt lgkmcnt(" #n ")" ::: "memory")
; #define PG8_BAR __builtin_amdgcn_s_barrier()
; #define PG8_SCHED __builtin_amdgcn_sched_barrier(0)
; template <class Epi>
; __device__ __forceinline__ void gemm_phase(LAS unsigned char* lds, const Gemm g_in, const StaticOrder& S, const Epi& E) {
;     ...
;             PG8_WAIT_V(8); PG8_WAIT_L(0); PG8_BAR; PG8_MMA(0, 0, At, B0); PG8_MMA(0, 1, At, B1); PG8_BAR; PG8_SCHED;
;             PG8_LDA(At, 1, 1); PG8_STAGE(PG8_SB(1, 0), b3, B); PG8_STAGE(PG8_SB(1, 1), b3 + hsB, B); PG8_STAGE(PG8_SA(1, 0), a3, A);
;             PG8_WAIT_V(8); PG8_WAIT_L(0); PG8_BAR; PG8_MMA(1, 0, At, B0); PG8_MMA(1, 1, At, B1); PG8_BAR; PG8_SCHED;
;         }
	ds_read_b128 v[162:165], v207 offset:49152
	ds_read_b128 v[166:169], v207 offset:50176
	ds_read_b128 v[170:173], v207 offset:51200
	ds_read_b128 v[174:177], v207 offset:52224
	ds_read_b128 v[188:191], v207 offset:53248
	ds_read_b128 v[192:195], v207 offset:54272
	ds_read_b128 v[196:199], v207 offset:55296
	ds_read_b128 v[212:215], v207 offset:56320
	s_mov_b32 m0, s52
	s_nop 0
	global_load_lds_dwordx4 v179, s[68:69]
	s_add_u32 s68, s38, 0x40080
	s_addc_u32 s69, s39, 0
	s_mov_b32 m0, s53
	s_nop 0
	global_load_lds_dwordx4 v179, s[68:69]
	s_add_u32 s68, s38, 0x80080
	s_addc_u32 s69, s39, 0
	s_mov_b32 m0, s56
	s_nop 0
	global_load_lds_dwordx4 v179, s[68:69]
	s_add_u32 s38, s38, 0xc0080
	s_addc_u32 s39, s39, 0
	s_mov_b32 m0, s57
	s_nop 0
	global_load_lds_dwordx4 v179, s[38:39]
	s_add_u32 s34, s34, 0x40080
	s_mov_b32 m0, s54
	s_nop 0
	global_load_lds_dwordx4 v1, s[36:37]
	s_addc_u32 s35, s35, 0
	s_mov_b32 m0, s55
	s_nop 0
	global_load_lds_dwordx4 v1, s[34:35]
	s_waitcnt vmcnt(8)
	s_waitcnt lgkmcnt(0)
	s_barrier
	s_setprio 1
	s_waitcnt lgkmcnt(7)
	v_mfma_f32_16x16x32_bf16 v[62:65], v[130:133], v[162:165], v[62:65]
	v_mfma_f32_16x16x32_bf16 v[58:61], v[138:141], v[162:165], v[58:61]
	s_waitcnt lgkmcnt(5)
	v_mfma_f32_16x16x32_bf16 v[46:49], v[130:133], v[170:173], v[46:49]
	v_mfma_f32_16x16x32_bf16 v[42:45], v[138:141], v[170:173], v[42:45]
	s_waitcnt lgkmcnt(3)
	v_mfma_f32_16x16x32_bf16 v[30:33], v[130:133], v[188:191], v[30:33]
	v_mfma_f32_16x16x32_bf16 v[26:29], v[138:141], v[188:191], v[26:29]
	s_waitcnt lgkmcnt(1)
	v_mfma_f32_16x16x32_bf16 v[14:17], v[130:133], v[196:199], v[14:17]
	v_mfma_f32_16x16x32_bf16 v[10:13], v[138:141], v[196:199], v[10:13]
	v_mfma_f32_16x16x32_bf16 v[62:65], v[134:137], v[166:169], v[62:65]
	v_mfma_f32_16x16x32_bf16 v[58:61], v[142:145], v[166:169], v[58:61]
	v_mfma_f32_16x16x32_bf16 v[46:49], v[134:137], v[174:177], v[46:49]
	v_mfma_f32_16x16x32_bf16 v[42:45], v[142:145], v[174:177], v[42:45]
	v_mfma_f32_16x16x32_bf16 v[30:33], v[134:137], v[192:195], v[30:33]
	v_mfma_f32_16x16x32_bf16 v[26:29], v[142:145], v[192:195], v[26:29]
	s_waitcnt lgkmcnt(0)
	v_mfma_f32_16x16x32_bf16 v[14:17], v[134:137], v[212:215], v[14:17]
	v_mfma_f32_16x16x32_bf16 v[10:13], v[142:145], v[212:215], v[10:13]
	s_setprio 0
	s_setprio 1
	v_mfma_f32_16x16x32_bf16 v[54:57], v[146:149], v[162:165], v[54:57]
	v_mfma_f32_16x16x32_bf16 v[50:53], v[154:157], v[162:165], v[50:53]
	v_mfma_f32_16x16x32_bf16 v[38:41], v[146:149], v[170:173], v[38:41]
	v_mfma_f32_16x16x32_bf16 v[34:37], v[154:157], v[170:173], v[34:37]
	v_mfma_f32_16x16x32_bf16 v[22:25], v[146:149], v[188:191], v[22:25]
	v_mfma_f32_16x16x32_bf16 v[18:21], v[154:157], v[188:191], v[18:21]
	v_mfma_f32_16x16x32_bf16 v[6:9], v[146:149], v[196:199], v[6:9]
	v_mfma_f32_16x16x32_bf16 v[2:5], v[154:157], v[196:199], v[2:5]
	v_mfma_f32_16x16x32_bf16 v[54:57], v[150:153], v[166:169], v[54:57]
	v_mfma_f32_16x16x32_bf16 v[50:53], v[158:161], v[166:169], v[50:53]
	v_mfma_f32_16x16x32_bf16 v[38:41], v[150:153], v[174:177], v[38:41]
	v_mfma_f32_16x16x32_bf16 v[34:37], v[158:161], v[174:177], v[34:37]
	s_add_u32 s64, s64, 0x100
	s_addc_u32 s65, s65, 0
	s_add_u32 s30, s30, 0x100
	s_addc_u32 s31, s31, 0
	s_cmp_ge_i32 s66, s41
	s_mov_b32 s34, s66
	v_mfma_f32_16x16x32_bf16 v[22:25], v[150:153], v[192:195], v[22:25]
	v_mfma_f32_16x16x32_bf16 v[18:21], v[158:161], v[192:195], v[18:21]
	v_mfma_f32_16x16x32_bf16 v[6:9], v[150:153], v[212:215], v[6:9]
	v_mfma_f32_16x16x32_bf16 v[2:5], v[158:161], v[212:215], v[2:5]
	s_setprio 0
	s_barrier
	s_cbranch_scc0 .LBB0_1285
	s_and_b64 vcc, exec, s[16:17]
	s_cbranch_vccz .LBB0_1288

; #define PG8_STAGE(bufoff, gbase, X) do { _Pragma("unroll") for (int _i = 0; _i < 2; ++_i) { \
;         const char* gp_ = (const char*)(gbase) + (_i ? rs##X : (size_t)0); const unsigned la_ = (unsigned)(size_t)(lds + (bufoff) + ldsw + _i * 8192); \
;         asm volatile("s_mov_b32 m0, %2\n\ts_nop 0\n\tglobal_load_lds_dwordx4 %0, %1" :: "v"(voff##X), "s"(gp_), "s"(la_) : "memory", "m0"); } } while (0)
; #define PG8_LDA(dst, b, h) do { _Pragma("unroll") for (int m = 0; m < 4; ++m) _Pragma("unroll") for (int k = 0; k < 2; ++k) dst[m][k] = *(const LAS bf16x8*)(lds + PG8_SA(b, h) + aoff + m * 2048 + k * 1024); } while (0)
; #define PG8_LDB(dst, b, h) do { _Pragma("unroll") for (int n = 0; n < 2; ++n) _Pragma("unroll") for (int k = 0; k < 2; ++k) dst[n][k] = *(const LAS bf16x8*)(lds + PG8_SB(b, h) + boff + n * 2048 + k * 1024); } while (0)
; #define PG8_WAIT_V(n) asm volatile("s_waitcnt vmcnt(" #n ")" ::: "memory")
; #define PG8_WAIT_L(n) asm volatile("s_waitcnt lgkmcnt(" #n ")" ::: "memory")
; #define PG8_BAR __builtin_amdgcn_s_barrier()
; #define PG8_SCHED __builtin_amdgcn_sched_barrier(0)
; template <class Epi>
; __device__ __forceinline__ void gemm_phase(LAS unsigned char* lds, const Gemm g_in, const StaticOrder& S, const Epi& E) {
;     ...
;             const bool last = (t == nt - 2);
;             const char* a1 = cA + (size_t)(t + 1) * kstep;
;             const char* a2 = last ? nA : cA + (size_t)(t + 2) * kstep; const char* b2 = last ? nB : cB + (size_t)(t + 2) * kstep;
;             const char* a3 = a2 + kstep; const char* b3 = b2 + kstep;
;             PG8_LDB(B0, 0, 0); PG8_LDB(B1, 0, 1); PG8_SCHED; PG8_LDA(At, 0, 0); PG8_STAGE(PG8_SA(1, 1), a1 + hsA, A);
;             PG8_WAIT_V(8); PG8_WAIT_L(0); PG8_BAR; PG8_MMA(0, 0, At, B0); PG8_MMA(0, 1, At, B1); PG8_BAR; PG8_SCHED;
;             PG8_LDA(At, 0, 1); PG8_STAGE(PG8_SB(0, 0), b2, B); PG8_STAGE(PG8_SB(0, 1), b2 + hsB, B); PG8_STAGE(PG8_SA(0, 0), a2, A);
;             PG8_WAIT_V(8); PG8_WAIT_L(0); PG8_BAR; PG8_MMA(1, 0, At, B0); PG8_MMA(1, 1, At, B1); PG8_BAR; PG8_SCHED;
.LBB0_1368:
	v_add_u32_e32 v147, 0x10000, v145
	ds_read_b128 v[134:137], v147
	ds_read_b128 v[138:141], v147 offset:1024
	ds_read_b128 v[148:151], v147 offset:2048
	ds_read_b128 v[152:155], v147 offset:3072
	v_add_u32_e32 v147, 0x14000, v145
	ds_read_b128 v[156:159], v147
	ds_read_b128 v[160:163], v147 offset:1024
	ds_read_b128 v[164:167], v147 offset:2048
	ds_read_b128 v[168:171], v147 offset:3072
	s_add_i32 s70, s40, 2
	s_add_u32 s42, s38, 0xfff40080
	s_addc_u32 s41, s39, -1
	s_cmp_eq_u32 s63, s40
	s_cselect_b32 s40, s31, s42
	s_cselect_b32 s41, s29, s41
	s_cselect_b32 s44, s67, s68
	s_cselect_b32 s45, s66, s69
	s_add_u32 s42, s40, 0x80
	s_addc_u32 s43, s41, 0
	ds_read_b128 v[172:175], v146
	ds_read_b128 v[184:187], v146 offset:1024
	ds_read_b128 v[188:191], v146 offset:2048
	ds_read_b128 v[192:195], v146 offset:3072
	ds_read_b128 v[196:199], v146 offset:4096
	ds_read_b128 v[204:207], v146 offset:5120
	ds_read_b128 v[208:211], v146 offset:6144
	ds_read_b128 v[212:215], v146 offset:7168
	s_add_u32 s72, s38, 0xfffc0000
	s_addc_u32 s73, s39, -1
	s_mov_b32 m0, s64
	s_nop 0
	global_load_lds_dwordx4 v1, s[72:73]
	s_nop 0
	s_mov_b32 m0, s65
	s_nop 0
	global_load_lds_dwordx4 v1, s[38:39]
	s_waitcnt vmcnt(8)
	s_waitcnt lgkmcnt(0)
	s_barrier
	s_setprio 1
	s_waitcnt lgkmcnt(7)
	v_mfma_i32_16x16x64_i8 v[126:129], v[134:137], v[172:175], v[126:129]
	v_mfma_i32_16x16x64_i8 v[122:125], v[148:151], v[172:175], v[122:125]
	s_waitcnt lgkmcnt(5)
	v_mfma_i32_16x16x64_i8 v[118:121], v[134:137], v[188:191], v[118:121]
	v_mfma_i32_16x16x64_i8 v[110:113], v[148:151], v[188:191], v[110:113]
	s_waitcnt lgkmcnt(3)
	v_mfma_i32_16x16x64_i8 v[102:105], v[134:137], v[196:199], v[102:105]
	v_mfma_i32_16x16x64_i8 v[94:97], v[148:151], v[196:199], v[94:97]
	s_waitcnt lgkmcnt(1)
	v_mfma_i32_16x16x64_i8 v[86:89], v[134:137], v[208:211], v[86:89]
	v_mfma_i32_16x16x64_i8 v[78:81], v[148:151], v[208:211], v[78:81]
	v_mfma_i32_16x16x64_i8 v[126:129], v[138:141], v[184:187], v[126:129]
	v_mfma_i32_16x16x64_i8 v[122:125], v[152:155], v[184:187], v[122:125]
	v_mfma_i32_16x16x64_i8 v[118:121], v[138:141], v[192:195], v[118:121]
	v_mfma_i32_16x16x64_i8 v[110:113], v[152:155], v[192:195], v[110:113]
	v_mfma_i32_16x16x64_i8 v[102:105], v[138:141], v[204:207], v[102:105]
	v_mfma_i32_16x16x64_i8 v[94:97], v[152:155], v[204:207], v[94:97]
	s_waitcnt lgkmcnt(0)
	v_mfma_i32_16x16x64_i8 v[86:89], v[138:141], v[212:215], v[86:89]
	v_mfma_i32_16x16x64_i8 v[78:81], v[152:155], v[212:215], v[78:81]
	s_setprio 0
	s_setprio 1
	v_mfma_i32_16x16x64_i8 v[114:117], v[156:159], v[172:175], v[114:117]
	v_mfma_i32_16x16x64_i8 v[106:109], v[164:167], v[172:175], v[106:109]
	v_mfma_i32_16x16x64_i8 v[98:101], v[156:159], v[188:191], v[98:101]
	v_mfma_i32_16x16x64_i8 v[90:93], v[164:167], v[188:191], v[90:93]
	v_mfma_i32_16x16x64_i8 v[82:85], v[156:159], v[196:199], v[82:85]
	v_mfma_i32_16x16x64_i8 v[74:77], v[164:167], v[196:199], v[74:77]
	v_mfma_i32_16x16x64_i8 v[70:73], v[156:159], v[208:211], v[70:73]
	v_mfma_i32_16x16x64_i8 v[66:69], v[164:167], v[208:211], v[66:69]
	v_mfma_i32_16x16x64_i8 v[114:117], v[160:163], v[184:187], v[114:117]
	v_mfma_i32_16x16x64_i8 v[106:109], v[168:171], v[184:187], v[106:109]
	v_mfma_i32_16x16x64_i8 v[98:101], v[160:163], v[192:195], v[98:101]
	v_mfma_i32_16x16x64_i8 v[90:93], v[168:171], v[192:195], v[90:93]
	s_add_u32 s72, s44, 0x40000
	v_mfma_i32_16x16x64_i8 v[82:85], v[160:163], v[204:207], v[82:85]
	v_mfma_i32_16x16x64_i8 v[74:77], v[168:171], v[204:207], v[74:77]
	v_mfma_i32_16x16x64_i8 v[70:73], v[160:163], v[212:215], v[70:73]
	v_mfma_i32_16x16x64_i8 v[66:69], v[168:171], v[212:215], v[66:69]
	s_setprio 0
	s_barrier
	ds_read_b128 v[172:175], v146 offset:16384
	ds_read_b128 v[184:187], v146 offset:17408
	ds_read_b128 v[188:191], v146 offset:18432
	ds_read_b128 v[192:195], v146 offset:19456
	ds_read_b128 v[196:199], v146 offset:20480
	ds_read_b128 v[204:207], v146 offset:21504
	ds_read_b128 v[208:211], v146 offset:22528
	ds_read_b128 v[212:215], v146 offset:23552
	s_mov_b32 m0, s50
	s_nop 0
	global_load_lds_dwordx4 v142, s[44:45]
	s_addc_u32 s73, s45, 0
	s_mov_b32 m0, s51
	s_nop 0
	global_load_lds_dwordx4 v142, s[72:73]
	s_add_u32 s72, s44, 0x80000
	s_addc_u32 s73, s45, 0
	s_mov_b32 m0, s52
	s_nop 0
	global_load_lds_dwordx4 v142, s[72:73]
	s_add_u32 s72, s44, 0xc0000
	s_addc_u32 s73, s45, 0
	s_mov_b32 m0, s53
	s_nop 0
	global_load_lds_dwordx4 v142, s[72:73]
	s_add_u32 s72, s40, 0x40000
	s_mov_b32 m0, s49
	s_nop 0
	global_load_lds_dwordx4 v1, s[40:41]
	s_addc_u32 s73, s41, 0
	s_mov_b32 m0, s54
	s_nop 0
	global_load_lds_dwordx4 v1, s[72:73]
	s_waitcnt vmcnt(8)
	s_waitcnt lgkmcnt(0)
	s_barrier
; #define PG8_STAGE(bufoff, gbase, X) do { _Pragma("unroll") for (int _i = 0; _i < 2; ++_i) { \
;         const char* gp_ = (const char*)(gbase) + (_i ? rs##X : (size_t)0); const unsigned la_ = (unsigned)(size_t)(lds + (bufoff) + ldsw + _i * 8192); \
;         asm volatile("s_mov_b32 m0, %2\n\ts_nop 0\n\tglobal_load_lds_dwordx4 %0, %1" :: "v"(voff##X), "s"(gp_), "s"(la_) : "memory", "m0"); } } while (0)
; #define PG8_LDA(dst, b, h) do { _Pragma("unroll") for (int m = 0; m < 4; ++m) _Pragma("unroll") for (int k = 0; k < 2; ++k) dst[m][k] = *(const LAS bf16x8*)(lds + PG8_SA(b, h) + aoff + m * 2048 + k * 1024); } while (0)
; #define PG8_LDB(dst, b, h) do { _Pragma("unroll") for (int n = 0; n < 2; ++n) _Pragma("unroll") for (int k = 0; k < 2; ++k) dst[n][k] = *(const LAS bf16x8*)(lds + PG8_SB(b, h) + boff + n * 2048 + k * 1024); } while (0)
; #define PG8_WAIT_V(n) asm volatile("s_waitcnt vmcnt(" #n ")" ::: "memory")
; #define PG8_WAIT_L(n) asm volatile("s_waitcnt lgkmcnt(" #n ")" ::: "memory")
; #define PG8_BAR __builtin_amdgcn_s_barrier()
; #define PG8_SCHED __builtin_amdgcn_sched_barrier(0)
; template <class Epi>
; __device__ __forceinline__ void gemm_phase(LAS unsigned char* lds, const Gemm g_in, const StaticOrder& S, const Epi& E) {
;     ...
;             PG8_LDA(At, 0, 1); PG8_STAGE(PG8_SB(0, 0), b2, B); PG8_STAGE(PG8_SB(0, 1), b2 + hsB, B); PG8_STAGE(PG8_SA(0, 0), a2, A);
;             PG8_WAIT_V(8); PG8_WAIT_L(0); PG8_BAR; PG8_MMA(1, 0, At, B0); PG8_MMA(1, 1, At, B1); PG8_BAR; PG8_SCHED;
;             PG8_LDB(B0, 1, 0); PG8_LDB(B1, 1, 1); PG8_SCHED; PG8_LDA(At, 1, 0); PG8_STAGE(PG8_SA(0, 1), a2 + hsA, A);
;             PG8_WAIT_V(8); PG8_WAIT_L(0); PG8_BAR; PG8_MMA(0, 0, At, B0); PG8_MMA(0, 1, At, B1); PG8_BAR; PG8_SCHED;
	s_setprio 1
	s_waitcnt lgkmcnt(7)
	v_mfma_i32_16x16x64_i8 v[62:65], v[134:137], v[172:175], v[62:65]
	v_mfma_i32_16x16x64_i8 v[58:61], v[148:151], v[172:175], v[58:61]
	s_waitcnt lgkmcnt(5)
	v_mfma_i32_16x16x64_i8 v[54:57], v[134:137], v[188:191], v[54:57]
	v_mfma_i32_16x16x64_i8 v[46:49], v[148:151], v[188:191], v[46:49]
	s_waitcnt lgkmcnt(3)
	v_mfma_i32_16x16x64_i8 v[38:41], v[134:137], v[196:199], v[38:41]
	v_mfma_i32_16x16x64_i8 v[30:33], v[148:151], v[196:199], v[30:33]
	s_waitcnt lgkmcnt(1)
	v_mfma_i32_16x16x64_i8 v[22:25], v[134:137], v[208:211], v[22:25]
	v_mfma_i32_16x16x64_i8 v[14:17], v[148:151], v[208:211], v[14:17]
	v_mfma_i32_16x16x64_i8 v[62:65], v[138:141], v[184:187], v[62:65]
	v_mfma_i32_16x16x64_i8 v[58:61], v[152:155], v[184:187], v[58:61]
	v_mfma_i32_16x16x64_i8 v[54:57], v[138:141], v[192:195], v[54:57]
	v_mfma_i32_16x16x64_i8 v[46:49], v[152:155], v[192:195], v[46:49]
	v_mfma_i32_16x16x64_i8 v[38:41], v[138:141], v[204:207], v[38:41]
	v_mfma_i32_16x16x64_i8 v[30:33], v[152:155], v[204:207], v[30:33]
	s_waitcnt lgkmcnt(0)
	v_mfma_i32_16x16x64_i8 v[22:25], v[138:141], v[212:215], v[22:25]
	v_mfma_i32_16x16x64_i8 v[14:17], v[152:155], v[212:215], v[14:17]
	s_setprio 0
	s_setprio 1
	v_mfma_i32_16x16x64_i8 v[50:53], v[156:159], v[172:175], v[50:53]
	v_mfma_i32_16x16x64_i8 v[42:45], v[164:167], v[172:175], v[42:45]
	v_mfma_i32_16x16x64_i8 v[34:37], v[156:159], v[188:191], v[34:37]
	v_mfma_i32_16x16x64_i8 v[26:29], v[164:167], v[188:191], v[26:29]
	v_mfma_i32_16x16x64_i8 v[18:21], v[156:159], v[196:199], v[18:21]
	v_mfma_i32_16x16x64_i8 v[10:13], v[164:167], v[196:199], v[10:13]
	v_mfma_i32_16x16x64_i8 v[6:9], v[156:159], v[208:211], v[6:9]
	v_mfma_i32_16x16x64_i8 v[2:5], v[164:167], v[208:211], v[2:5]
	v_mfma_i32_16x16x64_i8 v[50:53], v[160:163], v[184:187], v[50:53]
	v_mfma_i32_16x16x64_i8 v[42:45], v[168:171], v[184:187], v[42:45]
	v_mfma_i32_16x16x64_i8 v[34:37], v[160:163], v[192:195], v[34:37]
	v_mfma_i32_16x16x64_i8 v[26:29], v[168:171], v[192:195], v[26:29]
	v_mfma_i32_16x16x64_i8 v[18:21], v[160:163], v[204:207], v[18:21]
	v_mfma_i32_16x16x64_i8 v[10:13], v[168:171], v[204:207], v[10:13]
	v_mfma_i32_16x16x64_i8 v[6:9], v[160:163], v[212:215], v[6:9]
	v_mfma_i32_16x16x64_i8 v[2:5], v[168:171], v[212:215], v[2:5]
	s_setprio 0
	s_barrier
	v_add_u32_e32 v147, 0x18000, v145
	ds_read_b128 v[134:137], v147
	ds_read_b128 v[138:141], v147 offset:1024
	ds_read_b128 v[148:151], v147 offset:2048
	ds_read_b128 v[152:155], v147 offset:3072
	v_add_u32_e32 v147, 0x1c000, v145
	ds_read_b128 v[156:159], v147
	ds_read_b128 v[160:163], v147 offset:1024
	ds_read_b128 v[164:167], v147 offset:2048
	ds_read_b128 v[168:171], v147 offset:3072
	ds_read_b128 v[172:175], v146 offset:32768
	ds_read_b128 v[184:187], v146 offset:33792
	ds_read_b128 v[188:191], v146 offset:34816
	ds_read_b128 v[192:195], v146 offset:35840
	ds_read_b128 v[196:199], v146 offset:36864
	ds_read_b128 v[204:207], v146 offset:37888
	ds_read_b128 v[208:211], v146 offset:38912
	ds_read_b128 v[212:215], v146 offset:39936
	s_add_u32 s72, s40, 0x80000
	s_addc_u32 s73, s41, 0
	s_mov_b32 m0, s55
	s_nop 0
	global_load_lds_dwordx4 v1, s[72:73]
	s_add_u32 s72, s40, 0xc0000
	s_addc_u32 s73, s41, 0
	s_mov_b32 m0, s56
	s_nop 0
	global_load_lds_dwordx4 v1, s[72:73]
	s_waitcnt vmcnt(8)
	s_waitcnt lgkmcnt(0)
	s_barrier
	s_setprio 1
	s_waitcnt lgkmcnt(7)
	v_mfma_i32_16x16x64_i8 v[126:129], v[134:137], v[172:175], v[126:129]
	v_mfma_i32_16x16x64_i8 v[122:125], v[148:151], v[172:175], v[122:125]
	s_waitcnt lgkmcnt(5)
	v_mfma_i32_16x16x64_i8 v[118:121], v[134:137], v[188:191], v[118:121]
	v_mfma_i32_16x16x64_i8 v[110:113], v[148:151], v[188:191], v[110:113]
	s_waitcnt lgkmcnt(3)
	v_mfma_i32_16x16x64_i8 v[102:105], v[134:137], v[196:199], v[102:105]
	v_mfma_i32_16x16x64_i8 v[94:97], v[148:151], v[196:199], v[94:97]
	s_waitcnt lgkmcnt(1)
	v_mfma_i32_16x16x64_i8 v[86:89], v[134:137], v[208:211], v[86:89]
	v_mfma_i32_16x16x64_i8 v[78:81], v[148:151], v[208:211], v[78:81]
	v_mfma_i32_16x16x64_i8 v[126:129], v[138:141], v[184:187], v[126:129]
	v_mfma_i32_16x16x64_i8 v[122:125], v[152:155], v[184:187], v[122:125]
	v_mfma_i32_16x16x64_i8 v[118:121], v[138:141], v[192:195], v[118:121]
	v_mfma_i32_16x16x64_i8 v[110:113], v[152:155], v[192:195], v[110:113]
	v_mfma_i32_16x16x64_i8 v[102:105], v[138:141], v[204:207], v[102:105]
	v_mfma_i32_16x16x64_i8 v[94:97], v[152:155], v[204:207], v[94:97]
	s_waitcnt lgkmcnt(0)
	v_mfma_i32_16x16x64_i8 v[86:89], v[138:141], v[212:215], v[86:89]
	v_mfma_i32_16x16x64_i8 v[78:81], v[152:155], v[212:215], v[78:81]
	s_setprio 0
	s_setprio 1
	v_mfma_i32_16x16x64_i8 v[114:117], v[156:159], v[172:175], v[114:117]
	v_mfma_i32_16x16x64_i8 v[106:109], v[164:167], v[172:175], v[106:109]
	v_mfma_i32_16x16x64_i8 v[98:101], v[156:159], v[188:191], v[98:101]
	v_mfma_i32_16x16x64_i8 v[90:93], v[164:167], v[188:191], v[90:93]
	v_mfma_i32_16x16x64_i8 v[82:85], v[156:159], v[196:199], v[82:85]
	v_mfma_i32_16x16x64_i8 v[74:77], v[164:167], v[196:199], v[74:77]
	v_mfma_i32_16x16x64_i8 v[70:73], v[156:159], v[208:211], v[70:73]
	v_mfma_i32_16x16x64_i8 v[66:69], v[164:167], v[208:211], v[66:69]
	v_mfma_i32_16x16x64_i8 v[114:117], v[160:163], v[184:187], v[114:117]
	v_mfma_i32_16x16x64_i8 v[106:109], v[168:171], v[184:187], v[106:109]
	v_mfma_i32_16x16x64_i8 v[98:101], v[160:163], v[192:195], v[98:101]
	v_mfma_i32_16x16x64_i8 v[90:93], v[168:171], v[192:195], v[90:93]
	s_add_u32 s72, s44, 0x80
	s_addc_u32 s73, s45, 0
	v_mfma_i32_16x16x64_i8 v[82:85], v[160:163], v[204:207], v[82:85]
	v_mfma_i32_16x16x64_i8 v[74:77], v[168:171], v[204:207], v[74:77]
	v_mfma_i32_16x16x64_i8 v[70:73], v[160:163], v[212:215], v[70:73]
	v_mfma_i32_16x16x64_i8 v[66:69], v[168:171], v[212:215], v[66:69]
	s_setprio 0
	s_barrier
; #define PG8_STAGE(bufoff, gbase, X) do { _Pragma("unroll") for (int _i = 0; _i < 2; ++_i) { \
;         const char* gp_ = (const char*)(gbase) + (_i ? rs##X : (size_t)0); const unsigned la_ = (unsigned)(size_t)(lds + (bufoff) + ldsw + _i * 8192); \
;         asm volatile("s_mov_b32 m0, %2\n\ts_nop 0\n\tglobal_load_lds_dwordx4 %0, %1" :: "v"(voff##X), "s"(gp_), "s"(la_) : "memory", "m0"); } } while (0)
; #define PG8_LDA(dst, b, h) do { _Pragma("unroll") for (int m = 0; m < 4; ++m) _Pragma("unroll") for (int k = 0; k < 2; ++k) dst[m][k] = *(const LAS bf16x8*)(lds + PG8_SA(b, h) + aoff + m * 2048 + k * 1024); } while (0)
; #define PG8_WAIT_V(n) asm volatile("s_waitcnt vmcnt(" #n ")" ::: "memory")
; #define PG8_WAIT_L(n) asm volatile("s_waitcnt lgkmcnt(" #n ")" ::: "memory")
; #define PG8_BAR __builtin_amdgcn_s_barrier()
; #define PG8_SCHED __builtin_amdgcn_sched_barrier(0)
; template <class Epi>
; __device__ __forceinline__ void gemm_phase(LAS unsigned char* lds, const Gemm g_in, const StaticOrder& S, const Epi& E) {
;     ...
;             PG8_WAIT_V(8); PG8_WAIT_L(0); PG8_BAR; PG8_MMA(0, 0, At, B0); PG8_MMA(0, 1, At, B1); PG8_BAR; PG8_SCHED;
;             PG8_LDA(At, 1, 1); PG8_STAGE(PG8_SB(1, 0), b3, B); PG8_STAGE(PG8_SB(1, 1), b3 + hsB, B); PG8_STAGE(PG8_SA(1, 0), a3, A);
;             PG8_WAIT_V(8); PG8_WAIT_L(0); PG8_BAR; PG8_MMA(1, 0, At, B0); PG8_MMA(1, 1, At, B1); PG8_BAR; PG8_SCHED;
;         }
;     __device__ __forceinline__ void operator()(const f32x4 (&acc)[2][2][4][2], const Unit& u, int wr, int wc, int fr, int fq) const {
;     ...
;                     for (int bj = 0; bj < 2; ++bj) { f32x4 a0 = acc[ai][bj][m][0], a1 = acc[ai][bj][m][1];
;                         if (IN == 2) { a0 = __builtin_convertvector(__builtin_bit_cast(i32x4, a0), f32x4); a1 = __builtin_convertvector(__builtin_bit_cast(i32x4, a1), f32x4); }
	ds_read_b128 v[172:175], v146 offset:49152
	ds_read_b128 v[184:187], v146 offset:50176
	ds_read_b128 v[188:191], v146 offset:51200
	ds_read_b128 v[192:195], v146 offset:52224
	ds_read_b128 v[196:199], v146 offset:53248
	ds_read_b128 v[204:207], v146 offset:54272
	ds_read_b128 v[208:211], v146 offset:55296
	ds_read_b128 v[212:215], v146 offset:56320
	s_mov_b32 m0, s57
	s_nop 0
	global_load_lds_dwordx4 v142, s[72:73]
	s_add_u32 s72, s44, 0x40080
	s_addc_u32 s73, s45, 0
	s_mov_b32 m0, s58
	s_nop 0
	global_load_lds_dwordx4 v142, s[72:73]
	s_add_u32 s72, s44, 0x80080
	s_addc_u32 s73, s45, 0
	s_mov_b32 m0, s61
	s_nop 0
	global_load_lds_dwordx4 v142, s[72:73]
	s_add_u32 s44, s44, 0xc0080
	s_addc_u32 s45, s45, 0
	s_mov_b32 m0, s62
	s_nop 0
	global_load_lds_dwordx4 v142, s[44:45]
	s_add_u32 s40, s40, 0x40080
	s_mov_b32 m0, s59
	s_nop 0
	global_load_lds_dwordx4 v1, s[42:43]
	s_addc_u32 s41, s41, 0
	s_mov_b32 m0, s60
	s_nop 0
	global_load_lds_dwordx4 v1, s[40:41]
	s_waitcnt vmcnt(8)
	s_waitcnt lgkmcnt(0)
	s_barrier
	s_setprio 1
	s_waitcnt lgkmcnt(7)
	v_mfma_i32_16x16x64_i8 v[62:65], v[134:137], v[172:175], v[62:65]
	v_mfma_i32_16x16x64_i8 v[58:61], v[148:151], v[172:175], v[58:61]
	s_waitcnt lgkmcnt(5)
	v_mfma_i32_16x16x64_i8 v[54:57], v[134:137], v[188:191], v[54:57]
	v_mfma_i32_16x16x64_i8 v[46:49], v[148:151], v[188:191], v[46:49]
	s_waitcnt lgkmcnt(3)
	v_mfma_i32_16x16x64_i8 v[38:41], v[134:137], v[196:199], v[38:41]
	v_mfma_i32_16x16x64_i8 v[30:33], v[148:151], v[196:199], v[30:33]
	s_waitcnt lgkmcnt(1)
	v_mfma_i32_16x16x64_i8 v[22:25], v[134:137], v[208:211], v[22:25]
	v_mfma_i32_16x16x64_i8 v[14:17], v[148:151], v[208:211], v[14:17]
	v_mfma_i32_16x16x64_i8 v[62:65], v[138:141], v[184:187], v[62:65]
	v_mfma_i32_16x16x64_i8 v[58:61], v[152:155], v[184:187], v[58:61]
	v_mfma_i32_16x16x64_i8 v[54:57], v[138:141], v[192:195], v[54:57]
	v_mfma_i32_16x16x64_i8 v[46:49], v[152:155], v[192:195], v[46:49]
	v_mfma_i32_16x16x64_i8 v[38:41], v[138:141], v[204:207], v[38:41]
	v_mfma_i32_16x16x64_i8 v[30:33], v[152:155], v[204:207], v[30:33]
	s_waitcnt lgkmcnt(0)
	v_mfma_i32_16x16x64_i8 v[22:25], v[138:141], v[212:215], v[22:25]
	v_mfma_i32_16x16x64_i8 v[14:17], v[152:155], v[212:215], v[14:17]
	s_setprio 0
	s_setprio 1
	v_mfma_i32_16x16x64_i8 v[50:53], v[156:159], v[172:175], v[50:53]
	v_mfma_i32_16x16x64_i8 v[42:45], v[164:167], v[172:175], v[42:45]
	v_mfma_i32_16x16x64_i8 v[34:37], v[156:159], v[188:191], v[34:37]
	v_mfma_i32_16x16x64_i8 v[26:29], v[164:167], v[188:191], v[26:29]
	v_mfma_i32_16x16x64_i8 v[18:21], v[156:159], v[196:199], v[18:21]
	v_mfma_i32_16x16x64_i8 v[10:13], v[164:167], v[196:199], v[10:13]
	v_mfma_i32_16x16x64_i8 v[6:9], v[156:159], v[208:211], v[6:9]
	v_mfma_i32_16x16x64_i8 v[2:5], v[164:167], v[208:211], v[2:5]
	v_mfma_i32_16x16x64_i8 v[50:53], v[160:163], v[184:187], v[50:53]
	v_mfma_i32_16x16x64_i8 v[42:45], v[168:171], v[184:187], v[42:45]
	v_mfma_i32_16x16x64_i8 v[34:37], v[160:163], v[192:195], v[34:37]
	v_mfma_i32_16x16x64_i8 v[26:29], v[168:171], v[192:195], v[26:29]
	s_add_u32 s68, s68, 0x100
	s_addc_u32 s69, s69, 0
	s_add_u32 s38, s38, 0x100
	s_addc_u32 s39, s39, 0
	s_cmp_ge_i32 s70, s46
	s_mov_b32 s40, s70
	v_mfma_i32_16x16x64_i8 v[18:21], v[160:163], v[204:207], v[18:21]
	v_mfma_i32_16x16x64_i8 v[10:13], v[168:171], v[204:207], v[10:13]
	v_mfma_i32_16x16x64_i8 v[6:9], v[160:163], v[212:215], v[6:9]
	v_mfma_i32_16x16x64_i8 v[2:5], v[168:171], v[212:215], v[2:5]
	s_setprio 0
	s_barrier
	s_cbranch_scc0 .LBB0_1368
	v_cvt_f32_i32_e32 v127, v127
	v_cvt_f32_i32_e32 v126, v126
	v_cvt_f32_i32_e32 v129, v129
	v_cvt_f32_i32_e32 v128, v128
	v_cvt_f32_i32_e32 v135, v123
	v_cvt_f32_i32_e32 v125, v125
	v_cvt_f32_i32_e32 v124, v124
	v_cvt_f32_i32_e32 v134, v122
	v_cvt_f32_i32_e32 v115, v115
	v_cvt_f32_i32_e32 v114, v114
	v_cvt_f32_i32_e32 v117, v117
	v_cvt_f32_i32_e32 v116, v116
	v_cvt_f32_i32_e32 v107, v107
	v_cvt_f32_i32_e32 v109, v109
	v_cvt_f32_i32_e32 v108, v108
	v_cvt_f32_i32_e32 v106, v106
	v_pk_mul_f32 v[122:123], v[128:129], s[16:17] op_sel_hi:[1,0]
	v_pk_mul_f32 v[128:129], v[126:127], s[16:17] op_sel_hi:[1,0]
	v_pk_mul_f32 v[126:127], v[124:125], s[16:17] op_sel_hi:[1,0]
	v_pk_mul_f32 v[124:125], v[134:135], s[16:17] op_sel_hi:[1,0]
	v_pk_mul_f32 v[140:141], v[116:117], s[16:17] op_sel_hi:[1,0]
	v_pk_mul_f32 v[138:139], v[114:115], s[16:17] op_sel_hi:[1,0]
	v_pk_mul_f32 v[136:137], v[108:109], s[16:17] op_sel_hi:[1,0]
	v_pk_mul_f32 v[134:135], v[106:107], s[16:17] op_sel_hi:[1,0]
	v_cvt_f32_i32_e32 v107, v119
	v_cvt_f32_i32_e32 v106, v118
	v_cvt_f32_i32_e32 v109, v121
	v_cvt_f32_i32_e32 v108, v120
	v_cvt_f32_i32_e32 v115, v111
	v_cvt_f32_i32_e32 v117, v113
	v_cvt_f32_i32_e32 v116, v112
	v_cvt_f32_i32_e32 v114, v110
	v_cvt_f32_i32_e32 v99, v99
	v_cvt_f32_i32_e32 v98, v98
	v_cvt_f32_i32_e32 v101, v101
	v_cvt_f32_i32_e32 v100, v100
	v_cvt_f32_i32_e32 v91, v91
	v_cvt_f32_i32_e32 v93, v93
	v_cvt_f32_i32_e32 v92, v92
	v_cvt_f32_i32_e32 v90, v90
	v_pk_mul_f32 v[112:113], v[108:109], s[16:17] op_sel_hi:[1,0]
	v_pk_mul_f32 v[110:111], v[106:107], s[16:17] op_sel_hi:[1,0]
	v_pk_mul_f32 v[108:109], v[116:117], s[16:17] op_sel_hi:[1,0]
	v_pk_mul_f32 v[106:107], v[114:115], s[16:17] op_sel_hi:[1,0]
	v_pk_mul_f32 v[120:121], v[100:101], s[16:17] op_sel_hi:[1,0]
	v_pk_mul_f32 v[118:119], v[98:99], s[16:17] op_sel_hi:[1,0]
	v_pk_mul_f32 v[116:117], v[92:93], s[16:17] op_sel_hi:[1,0]
	v_pk_mul_f32 v[114:115], v[90:91], s[16:17] op_sel_hi:[1,0]
	v_cvt_f32_i32_e32 v91, v103
	v_cvt_f32_i32_e32 v90, v102
; #define PG8_BAR __builtin_amdgcn_s_barrier()
; template <class Epi>
; __device__ __forceinline__ void gemm_phase(LAS unsigned char* lds, const Gemm g_in, const StaticOrder& S, const Epi& E) {
;     ...
;         if (wr == 0) PG8_BAR;
;     __device__ __forceinline__ void operator()(const f32x4 (&acc)[2][2][4][2], const Unit& u, int wr, int wc, int fr, int fq) const {
;     ...
;                     for (int bj = 0; bj < 2; ++bj) { f32x4 a0 = acc[ai][bj][m][0], a1 = acc[ai][bj][m][1];
;                         if (IN == 2) { a0 = __builtin_convertvector(__builtin_bit_cast(i32x4, a0), f32x4); a1 = __builtin_convertvector(__builtin_bit_cast(i32x4, a1), f32x4); }
;                         const f32x4 v0 = bv[m][bj][0] * ALPHA + a0 * scale, v1 = bv[m][bj][1] * ALPHA + a1 * scale;
	v_cvt_f32_i32_e32 v93, v105
	v_cvt_f32_i32_e32 v92, v104
	v_cvt_f32_i32_e32 v99, v95
	v_cvt_f32_i32_e32 v101, v97
	v_cvt_f32_i32_e32 v100, v96
	v_cvt_f32_i32_e32 v98, v94
	v_cvt_f32_i32_e32 v83, v83
	v_cvt_f32_i32_e32 v82, v82
	v_cvt_f32_i32_e32 v85, v85
	v_cvt_f32_i32_e32 v84, v84
	v_cvt_f32_i32_e32 v75, v75
	v_cvt_f32_i32_e32 v77, v77
	v_cvt_f32_i32_e32 v76, v76
	v_cvt_f32_i32_e32 v74, v74
	v_pk_mul_f32 v[96:97], v[92:93], s[16:17] op_sel_hi:[1,0]
	v_pk_mul_f32 v[94:95], v[90:91], s[16:17] op_sel_hi:[1,0]
	v_pk_mul_f32 v[92:93], v[100:101], s[16:17] op_sel_hi:[1,0]
	v_pk_mul_f32 v[90:91], v[98:99], s[16:17] op_sel_hi:[1,0]
	v_pk_mul_f32 v[104:105], v[84:85], s[16:17] op_sel_hi:[1,0]
	v_pk_mul_f32 v[102:103], v[82:83], s[16:17] op_sel_hi:[1,0]
	v_pk_mul_f32 v[100:101], v[76:77], s[16:17] op_sel_hi:[1,0]
	v_pk_mul_f32 v[98:99], v[74:75], s[16:17] op_sel_hi:[1,0]
	v_cvt_f32_i32_e32 v75, v87
	v_cvt_f32_i32_e32 v74, v86
	v_cvt_f32_i32_e32 v77, v89
	v_cvt_f32_i32_e32 v76, v88
	v_cvt_f32_i32_e32 v83, v79
	v_cvt_f32_i32_e32 v85, v81
	v_cvt_f32_i32_e32 v84, v80
	v_cvt_f32_i32_e32 v82, v78
	v_cvt_f32_i32_e32 v71, v71
	v_cvt_f32_i32_e32 v70, v70
	v_cvt_f32_i32_e32 v73, v73
	v_cvt_f32_i32_e32 v72, v72
	v_cvt_f32_i32_e32 v67, v67
	v_cvt_f32_i32_e32 v69, v69
	v_cvt_f32_i32_e32 v68, v68
	v_cvt_f32_i32_e32 v66, v66
	v_cvt_f32_i32_e32 v51, v51
	v_cvt_f32_i32_e32 v50, v50
	v_cvt_f32_i32_e32 v53, v53
	v_cvt_f32_i32_e32 v52, v52
	v_cvt_f32_i32_e32 v43, v43
	v_cvt_f32_i32_e32 v45, v45
	v_cvt_f32_i32_e32 v44, v44
	v_cvt_f32_i32_e32 v42, v42
	v_pk_mul_f32 v[80:81], v[76:77], s[16:17] op_sel_hi:[1,0]
	v_pk_mul_f32 v[78:79], v[74:75], s[16:17] op_sel_hi:[1,0]
	v_pk_mul_f32 v[76:77], v[84:85], s[16:17] op_sel_hi:[1,0]
	v_pk_mul_f32 v[74:75], v[82:83], s[16:17] op_sel_hi:[1,0]
	v_pk_mul_f32 v[88:89], v[72:73], s[16:17] op_sel_hi:[1,0]
	v_pk_mul_f32 v[86:87], v[70:71], s[16:17] op_sel_hi:[1,0]
	v_pk_mul_f32 v[84:85], v[68:69], s[16:17] op_sel_hi:[1,0]
	v_pk_mul_f32 v[82:83], v[66:67], s[16:17] op_sel_hi:[1,0]
	v_pk_mul_f32 v[72:73], v[52:53], s[16:17] op_sel_hi:[1,0]
	v_pk_mul_f32 v[70:71], v[50:51], s[16:17] op_sel_hi:[1,0]
	v_pk_mul_f32 v[68:69], v[44:45], s[16:17] op_sel_hi:[1,0]
	v_pk_mul_f32 v[66:67], v[42:43], s[16:17] op_sel_hi:[1,0]
	v_cvt_f32_i32_e32 v43, v55
	v_cvt_f32_i32_e32 v42, v54
	v_cvt_f32_i32_e32 v45, v57
	v_cvt_f32_i32_e32 v44, v56
	v_cvt_f32_i32_e32 v51, v47
	v_cvt_f32_i32_e32 v53, v49
	v_cvt_f32_i32_e32 v52, v48
	v_cvt_f32_i32_e32 v50, v46
	v_cvt_f32_i32_e32 v35, v35
	v_cvt_f32_i32_e32 v34, v34
	v_cvt_f32_i32_e32 v37, v37
	v_cvt_f32_i32_e32 v36, v36
	v_cvt_f32_i32_e32 v27, v27
	v_cvt_f32_i32_e32 v29, v29
	v_cvt_f32_i32_e32 v28, v28
	v_cvt_f32_i32_e32 v26, v26
	v_pk_mul_f32 v[48:49], v[44:45], s[16:17] op_sel_hi:[1,0]
	v_pk_mul_f32 v[46:47], v[42:43], s[16:17] op_sel_hi:[1,0]
	v_pk_mul_f32 v[44:45], v[52:53], s[16:17] op_sel_hi:[1,0]
	v_pk_mul_f32 v[42:43], v[50:51], s[16:17] op_sel_hi:[1,0]
	v_pk_mul_f32 v[56:57], v[36:37], s[16:17] op_sel_hi:[1,0]
	v_pk_mul_f32 v[54:55], v[34:35], s[16:17] op_sel_hi:[1,0]
	v_pk_mul_f32 v[52:53], v[28:29], s[16:17] op_sel_hi:[1,0]
	v_pk_mul_f32 v[50:51], v[26:27], s[16:17] op_sel_hi:[1,0]
	v_cvt_f32_i32_e32 v27, v39
	v_cvt_f32_i32_e32 v26, v38
	v_cvt_f32_i32_e32 v29, v41
	v_cvt_f32_i32_e32 v28, v40
	v_cvt_f32_i32_e32 v35, v31
	v_cvt_f32_i32_e32 v37, v33
	v_cvt_f32_i32_e32 v36, v32
	v_cvt_f32_i32_e32 v34, v30
	v_cvt_f32_i32_e32 v19, v19
	v_cvt_f32_i32_e32 v18, v18
	v_cvt_f32_i32_e32 v21, v21
	v_cvt_f32_i32_e32 v20, v20
	v_cvt_f32_i32_e32 v11, v11
	v_cvt_f32_i32_e32 v13, v13
	v_cvt_f32_i32_e32 v12, v12
	v_cvt_f32_i32_e32 v10, v10
	v_cvt_f32_i32_e32 v63, v63
	v_cvt_f32_i32_e32 v62, v62
	v_cvt_f32_i32_e32 v65, v65
	v_cvt_f32_i32_e32 v64, v64
	v_cvt_f32_i32_e32 v59, v59
	v_cvt_f32_i32_e32 v61, v61
	v_cvt_f32_i32_e32 v60, v60
	v_cvt_f32_i32_e32 v58, v58
	v_pk_mul_f32 v[32:33], v[28:29], s[16:17] op_sel_hi:[1,0]
	v_pk_mul_f32 v[30:31], v[26:27], s[16:17] op_sel_hi:[1,0]
	v_pk_mul_f32 v[28:29], v[36:37], s[16:17] op_sel_hi:[1,0]
	v_pk_mul_f32 v[26:27], v[34:35], s[16:17] op_sel_hi:[1,0]
	v_pk_mul_f32 v[36:37], v[20:21], s[16:17] op_sel_hi:[1,0]
	v_pk_mul_f32 v[34:35], v[18:19], s[16:17] op_sel_hi:[1,0]
	v_pk_mul_f32 v[20:21], v[12:13], s[16:17] op_sel_hi:[1,0]
	v_pk_mul_f32 v[18:19], v[10:11], s[16:17] op_sel_hi:[1,0]
	v_cvt_f32_i32_e32 v11, v23
	v_cvt_f32_i32_e32 v10, v22
	v_cvt_f32_i32_e32 v13, v25
	v_cvt_f32_i32_e32 v12, v24
	v_cvt_f32_i32_e32 v23, v15
	v_cvt_f32_i32_e32 v25, v17
	v_cvt_f32_i32_e32 v24, v16
	v_cvt_f32_i32_e32 v22, v14
	v_cvt_f32_i32_e32 v7, v7
	v_cvt_f32_i32_e32 v6, v6
	v_cvt_f32_i32_e32 v9, v9
	v_cvt_f32_i32_e32 v8, v8
	v_cvt_f32_i32_e32 v3, v3
	v_cvt_f32_i32_e32 v5, v5
	v_cvt_f32_i32_e32 v4, v4
	v_cvt_f32_i32_e32 v2, v2
	v_pk_mul_f32 v[64:65], v[64:65], s[16:17] op_sel_hi:[1,0]
	v_pk_mul_f32 v[62:63], v[62:63], s[16:17] op_sel_hi:[1,0]
	v_pk_mul_f32 v[60:61], v[60:61], s[16:17] op_sel_hi:[1,0]
	v_pk_mul_f32 v[58:59], v[58:59], s[16:17] op_sel_hi:[1,0]
	v_pk_mul_f32 v[16:17], v[12:13], s[16:17] op_sel_hi:[1,0]
	v_pk_mul_f32 v[14:15], v[10:11], s[16:17] op_sel_hi:[1,0]
	v_pk_mul_f32 v[12:13], v[24:25], s[16:17] op_sel_hi:[1,0]
	v_pk_mul_f32 v[10:11], v[22:23], s[16:17] op_sel_hi:[1,0]
	v_pk_mul_f32 v[8:9], v[8:9], s[16:17] op_sel_hi:[1,0]
	v_pk_mul_f32 v[6:7], v[6:7], s[16:17] op_sel_hi:[1,0]
	v_pk_mul_f32 v[4:5], v[4:5], s[16:17] op_sel_hi:[1,0]
	v_pk_mul_f32 v[2:3], v[2:3], s[16:17] op_sel_hi:[1,0]
	s_and_b64 vcc, exec, s[14:15]
	s_cbranch_vccz .LBB0_1371

; #define PG8_STAGE(bufoff, gbase, X) do { _Pragma("unroll") for (int _i = 0; _i < 2; ++_i) { \
;         const char* gp_ = (const char*)(gbase) + (_i ? rs##X : (size_t)0); const unsigned la_ = (unsigned)(size_t)(lds + (bufoff) + ldsw + _i * 8192); \
;         asm volatile("s_mov_b32 m0, %2\n\ts_nop 0\n\tglobal_load_lds_dwordx4 %0, %1" :: "v"(voff##X), "s"(gp_), "s"(la_) : "memory", "m0"); } } while (0)
; #define PG8_LDA(dst, b, h) do { _Pragma("unroll") for (int m = 0; m < 4; ++m) _Pragma("unroll") for (int k = 0; k < 2; ++k) dst[m][k] = *(const LAS bf16x8*)(lds + PG8_SA(b, h) + aoff + m * 2048 + k * 1024); } while (0)
; #define PG8_LDB(dst, b, h) do { _Pragma("unroll") for (int n = 0; n < 2; ++n) _Pragma("unroll") for (int k = 0; k < 2; ++k) dst[n][k] = *(const LAS bf16x8*)(lds + PG8_SB(b, h) + boff + n * 2048 + k * 1024); } while (0)
; #define PG8_WAIT_V(n) asm volatile("s_waitcnt vmcnt(" #n ")" ::: "memory")
; #define PG8_WAIT_L(n) asm volatile("s_waitcnt lgkmcnt(" #n ")" ::: "memory")
; #define PG8_BAR __builtin_amdgcn_s_barrier()
; #define PG8_SCHED __builtin_amdgcn_sched_barrier(0)
; template <class Epi>
; __device__ __forceinline__ void gemm_phase(LAS unsigned char* lds, const Gemm g_in, const StaticOrder& S, const Epi& E) {
;     ...
;             const bool last = (t == nt - 2);
;             const char* a1 = cA + (size_t)(t + 1) * kstep;
;             const char* a2 = last ? nA : cA + (size_t)(t + 2) * kstep; const char* b2 = last ? nB : cB + (size_t)(t + 2) * kstep;
;             const char* a3 = a2 + kstep; const char* b3 = b2 + kstep;
;             PG8_LDB(B0, 0, 0); PG8_LDB(B1, 0, 1); PG8_SCHED; PG8_LDA(At, 0, 0); PG8_STAGE(PG8_SA(1, 1), a1 + hsA, A);
;             PG8_WAIT_V(8); PG8_WAIT_L(0); PG8_BAR; PG8_MMA(0, 0, At, B0); PG8_MMA(0, 1, At, B1); PG8_BAR; PG8_SCHED;
;             PG8_LDA(At, 0, 1); PG8_STAGE(PG8_SB(0, 0), b2, B); PG8_STAGE(PG8_SB(0, 1), b2 + hsB, B); PG8_STAGE(PG8_SA(0, 0), a2, A);
;             PG8_WAIT_V(8); PG8_WAIT_L(0); PG8_BAR; PG8_MMA(1, 0, At, B0); PG8_MMA(1, 1, At, B1); PG8_BAR; PG8_SCHED;
.LBB0_1510:
	v_add_u32_e32 v139, 0x10000, v137
	ds_read_b128 v[140:143], v139
	ds_read_b128 v[144:147], v139 offset:1024
	ds_read_b128 v[148:151], v139 offset:2048
	ds_read_b128 v[152:155], v139 offset:3072
	v_add_u32_e32 v139, 0x14000, v137
	ds_read_b128 v[156:159], v139
	ds_read_b128 v[160:163], v139 offset:1024
	ds_read_b128 v[164:167], v139 offset:2048
	ds_read_b128 v[168:171], v139 offset:3072
	s_add_i32 s64, s28, 2
	s_add_u32 s30, s26, 0xfff40080
	s_addc_u32 s29, s27, -1
	s_cmp_eq_u32 s56, s28
	s_cselect_b32 s28, s21, s30
	s_cselect_b32 s29, s19, s29
	s_cselect_b32 s34, s61, s62
	s_cselect_b32 s35, s60, s63
	s_add_u32 s30, s28, 0x80
	s_addc_u32 s31, s29, 0
	ds_read_b128 v[172:175], v138
	ds_read_b128 v[182:185], v138 offset:1024
	ds_read_b128 v[186:189], v138 offset:2048
	ds_read_b128 v[190:193], v138 offset:3072
	ds_read_b128 v[194:197], v138 offset:4096
	ds_read_b128 v[198:201], v138 offset:5120
	ds_read_b128 v[204:207], v138 offset:6144
	ds_read_b128 v[208:211], v138 offset:7168
	s_add_u32 s66, s26, 0xfffc0000
	s_addc_u32 s67, s27, -1
	s_mov_b32 m0, s57
	s_nop 0
	global_load_lds_dwordx4 v1, s[66:67]
	s_nop 0
	s_mov_b32 m0, s58
	s_nop 0
	global_load_lds_dwordx4 v1, s[26:27]
	s_waitcnt vmcnt(8)
	s_waitcnt lgkmcnt(0)
	s_barrier
	s_setprio 1
	s_waitcnt lgkmcnt(7)
	v_mfma_i32_16x16x64_i8 v[126:129], v[140:143], v[172:175], v[126:129]
	v_mfma_i32_16x16x64_i8 v[118:121], v[148:151], v[172:175], v[118:121]
	s_waitcnt lgkmcnt(5)
	v_mfma_i32_16x16x64_i8 v[110:113], v[140:143], v[186:189], v[110:113]
	v_mfma_i32_16x16x64_i8 v[102:105], v[148:151], v[186:189], v[102:105]
	s_waitcnt lgkmcnt(3)
	v_mfma_i32_16x16x64_i8 v[94:97], v[140:143], v[194:197], v[94:97]
	v_mfma_i32_16x16x64_i8 v[86:89], v[148:151], v[194:197], v[86:89]
	s_waitcnt lgkmcnt(1)
	v_mfma_i32_16x16x64_i8 v[78:81], v[140:143], v[204:207], v[78:81]
	v_mfma_i32_16x16x64_i8 v[70:73], v[148:151], v[204:207], v[70:73]
	v_mfma_i32_16x16x64_i8 v[126:129], v[144:147], v[182:185], v[126:129]
	v_mfma_i32_16x16x64_i8 v[118:121], v[152:155], v[182:185], v[118:121]
	v_mfma_i32_16x16x64_i8 v[110:113], v[144:147], v[190:193], v[110:113]
	v_mfma_i32_16x16x64_i8 v[102:105], v[152:155], v[190:193], v[102:105]
	v_mfma_i32_16x16x64_i8 v[94:97], v[144:147], v[198:201], v[94:97]
	v_mfma_i32_16x16x64_i8 v[86:89], v[152:155], v[198:201], v[86:89]
	s_waitcnt lgkmcnt(0)
	v_mfma_i32_16x16x64_i8 v[78:81], v[144:147], v[208:211], v[78:81]
	v_mfma_i32_16x16x64_i8 v[70:73], v[152:155], v[208:211], v[70:73]
	s_setprio 0
	s_setprio 1
	v_mfma_i32_16x16x64_i8 v[122:125], v[156:159], v[172:175], v[122:125]
	v_mfma_i32_16x16x64_i8 v[114:117], v[164:167], v[172:175], v[114:117]
	v_mfma_i32_16x16x64_i8 v[106:109], v[156:159], v[186:189], v[106:109]
	v_mfma_i32_16x16x64_i8 v[98:101], v[164:167], v[186:189], v[98:101]
	v_mfma_i32_16x16x64_i8 v[90:93], v[156:159], v[194:197], v[90:93]
	v_mfma_i32_16x16x64_i8 v[82:85], v[164:167], v[194:197], v[82:85]
	v_mfma_i32_16x16x64_i8 v[74:77], v[156:159], v[204:207], v[74:77]
	v_mfma_i32_16x16x64_i8 v[66:69], v[164:167], v[204:207], v[66:69]
	v_mfma_i32_16x16x64_i8 v[122:125], v[160:163], v[182:185], v[122:125]
	v_mfma_i32_16x16x64_i8 v[114:117], v[168:171], v[182:185], v[114:117]
	v_mfma_i32_16x16x64_i8 v[106:109], v[160:163], v[190:193], v[106:109]
	v_mfma_i32_16x16x64_i8 v[98:101], v[168:171], v[190:193], v[98:101]
	s_add_u32 s66, s34, 0x40000
	v_mfma_i32_16x16x64_i8 v[90:93], v[160:163], v[198:201], v[90:93]
	v_mfma_i32_16x16x64_i8 v[82:85], v[168:171], v[198:201], v[82:85]
	v_mfma_i32_16x16x64_i8 v[74:77], v[160:163], v[208:211], v[74:77]
	v_mfma_i32_16x16x64_i8 v[66:69], v[168:171], v[208:211], v[66:69]
	s_setprio 0
	s_barrier
	ds_read_b128 v[172:175], v138 offset:16384
	ds_read_b128 v[182:185], v138 offset:17408
	ds_read_b128 v[186:189], v138 offset:18432
	ds_read_b128 v[190:193], v138 offset:19456
	ds_read_b128 v[194:197], v138 offset:20480
	ds_read_b128 v[198:201], v138 offset:21504
	ds_read_b128 v[204:207], v138 offset:22528
	ds_read_b128 v[208:211], v138 offset:23552
	s_mov_b32 m0, s41
	s_nop 0
	global_load_lds_dwordx4 v134, s[34:35]
	s_addc_u32 s67, s35, 0
	s_mov_b32 m0, s42
	s_nop 0
	global_load_lds_dwordx4 v134, s[66:67]
	s_add_u32 s66, s34, 0x80000
	s_addc_u32 s67, s35, 0
	s_mov_b32 m0, s43
	s_nop 0
	global_load_lds_dwordx4 v134, s[66:67]
	s_add_u32 s66, s34, 0xc0000
	s_addc_u32 s67, s35, 0
	s_mov_b32 m0, s44
	s_nop 0
	global_load_lds_dwordx4 v134, s[66:67]
	s_add_u32 s66, s28, 0x40000
	s_mov_b32 m0, s40
	s_nop 0
	global_load_lds_dwordx4 v1, s[28:29]
	s_addc_u32 s67, s29, 0
	s_mov_b32 m0, s45
	s_nop 0
	global_load_lds_dwordx4 v1, s[66:67]
	s_waitcnt vmcnt(8)
	s_waitcnt lgkmcnt(0)
	s_barrier
; #define PG8_STAGE(bufoff, gbase, X) do { _Pragma("unroll") for (int _i = 0; _i < 2; ++_i) { \
;         const char* gp_ = (const char*)(gbase) + (_i ? rs##X : (size_t)0); const unsigned la_ = (unsigned)(size_t)(lds + (bufoff) + ldsw + _i * 8192); \
;         asm volatile("s_mov_b32 m0, %2\n\ts_nop 0\n\tglobal_load_lds_dwordx4 %0, %1" :: "v"(voff##X), "s"(gp_), "s"(la_) : "memory", "m0"); } } while (0)
; #define PG8_LDA(dst, b, h) do { _Pragma("unroll") for (int m = 0; m < 4; ++m) _Pragma("unroll") for (int k = 0; k < 2; ++k) dst[m][k] = *(const LAS bf16x8*)(lds + PG8_SA(b, h) + aoff + m * 2048 + k * 1024); } while (0)
; #define PG8_LDB(dst, b, h) do { _Pragma("unroll") for (int n = 0; n < 2; ++n) _Pragma("unroll") for (int k = 0; k < 2; ++k) dst[n][k] = *(const LAS bf16x8*)(lds + PG8_SB(b, h) + boff + n * 2048 + k * 1024); } while (0)
; #define PG8_WAIT_V(n) asm volatile("s_waitcnt vmcnt(" #n ")" ::: "memory")
; #define PG8_WAIT_L(n) asm volatile("s_waitcnt lgkmcnt(" #n ")" ::: "memory")
; #define PG8_BAR __builtin_amdgcn_s_barrier()
; #define PG8_SCHED __builtin_amdgcn_sched_barrier(0)
; template <class Epi>
; __device__ __forceinline__ void gemm_phase(LAS unsigned char* lds, const Gemm g_in, const StaticOrder& S, const Epi& E) {
;     ...
;             PG8_LDA(At, 0, 1); PG8_STAGE(PG8_SB(0, 0), b2, B); PG8_STAGE(PG8_SB(0, 1), b2 + hsB, B); PG8_STAGE(PG8_SA(0, 0), a2, A);
;             PG8_WAIT_V(8); PG8_WAIT_L(0); PG8_BAR; PG8_MMA(1, 0, At, B0); PG8_MMA(1, 1, At, B1); PG8_BAR; PG8_SCHED;
;             PG8_LDB(B0, 1, 0); PG8_LDB(B1, 1, 1); PG8_SCHED; PG8_LDA(At, 1, 0); PG8_STAGE(PG8_SA(0, 1), a2 + hsA, A);
;             PG8_WAIT_V(8); PG8_WAIT_L(0); PG8_BAR; PG8_MMA(0, 0, At, B0); PG8_MMA(0, 1, At, B1); PG8_BAR; PG8_SCHED;
	s_setprio 1
	s_waitcnt lgkmcnt(7)
	v_mfma_i32_16x16x64_i8 v[62:65], v[140:143], v[172:175], v[62:65]
	v_mfma_i32_16x16x64_i8 v[54:57], v[148:151], v[172:175], v[54:57]
	s_waitcnt lgkmcnt(5)
	v_mfma_i32_16x16x64_i8 v[46:49], v[140:143], v[186:189], v[46:49]
	v_mfma_i32_16x16x64_i8 v[38:41], v[148:151], v[186:189], v[38:41]
	s_waitcnt lgkmcnt(3)
	v_mfma_i32_16x16x64_i8 v[30:33], v[140:143], v[194:197], v[30:33]
	v_mfma_i32_16x16x64_i8 v[22:25], v[148:151], v[194:197], v[22:25]
	s_waitcnt lgkmcnt(1)
	v_mfma_i32_16x16x64_i8 v[14:17], v[140:143], v[204:207], v[14:17]
	v_mfma_i32_16x16x64_i8 v[6:9], v[148:151], v[204:207], v[6:9]
	v_mfma_i32_16x16x64_i8 v[62:65], v[144:147], v[182:185], v[62:65]
	v_mfma_i32_16x16x64_i8 v[54:57], v[152:155], v[182:185], v[54:57]
	v_mfma_i32_16x16x64_i8 v[46:49], v[144:147], v[190:193], v[46:49]
	v_mfma_i32_16x16x64_i8 v[38:41], v[152:155], v[190:193], v[38:41]
	v_mfma_i32_16x16x64_i8 v[30:33], v[144:147], v[198:201], v[30:33]
	v_mfma_i32_16x16x64_i8 v[22:25], v[152:155], v[198:201], v[22:25]
	s_waitcnt lgkmcnt(0)
	v_mfma_i32_16x16x64_i8 v[14:17], v[144:147], v[208:211], v[14:17]
	v_mfma_i32_16x16x64_i8 v[6:9], v[152:155], v[208:211], v[6:9]
	s_setprio 0
	s_setprio 1
	v_mfma_i32_16x16x64_i8 v[58:61], v[156:159], v[172:175], v[58:61]
	v_mfma_i32_16x16x64_i8 v[50:53], v[164:167], v[172:175], v[50:53]
	v_mfma_i32_16x16x64_i8 v[42:45], v[156:159], v[186:189], v[42:45]
	v_mfma_i32_16x16x64_i8 v[34:37], v[164:167], v[186:189], v[34:37]
	v_mfma_i32_16x16x64_i8 v[26:29], v[156:159], v[194:197], v[26:29]
	v_mfma_i32_16x16x64_i8 v[18:21], v[164:167], v[194:197], v[18:21]
	v_mfma_i32_16x16x64_i8 v[10:13], v[156:159], v[204:207], v[10:13]
	v_mfma_i32_16x16x64_i8 v[2:5], v[164:167], v[204:207], v[2:5]
	v_mfma_i32_16x16x64_i8 v[58:61], v[160:163], v[182:185], v[58:61]
	v_mfma_i32_16x16x64_i8 v[50:53], v[168:171], v[182:185], v[50:53]
	v_mfma_i32_16x16x64_i8 v[42:45], v[160:163], v[190:193], v[42:45]
	v_mfma_i32_16x16x64_i8 v[34:37], v[168:171], v[190:193], v[34:37]
	v_mfma_i32_16x16x64_i8 v[26:29], v[160:163], v[198:201], v[26:29]
	v_mfma_i32_16x16x64_i8 v[18:21], v[168:171], v[198:201], v[18:21]
	v_mfma_i32_16x16x64_i8 v[10:13], v[160:163], v[208:211], v[10:13]
	v_mfma_i32_16x16x64_i8 v[2:5], v[168:171], v[208:211], v[2:5]
	s_setprio 0
	s_barrier
	v_add_u32_e32 v139, 0x18000, v137
	ds_read_b128 v[140:143], v139
	ds_read_b128 v[144:147], v139 offset:1024
	ds_read_b128 v[148:151], v139 offset:2048
	ds_read_b128 v[152:155], v139 offset:3072
	v_add_u32_e32 v139, 0x1c000, v137
	ds_read_b128 v[156:159], v139
	ds_read_b128 v[160:163], v139 offset:1024
	ds_read_b128 v[164:167], v139 offset:2048
	ds_read_b128 v[168:171], v139 offset:3072
	ds_read_b128 v[172:175], v138 offset:32768
	ds_read_b128 v[182:185], v138 offset:33792
	ds_read_b128 v[186:189], v138 offset:34816
	ds_read_b128 v[190:193], v138 offset:35840
	ds_read_b128 v[194:197], v138 offset:36864
	ds_read_b128 v[198:201], v138 offset:37888
	ds_read_b128 v[204:207], v138 offset:38912
	ds_read_b128 v[208:211], v138 offset:39936
	s_add_u32 s66, s28, 0x80000
	s_addc_u32 s67, s29, 0
	s_mov_b32 m0, s46
	s_nop 0
	global_load_lds_dwordx4 v1, s[66:67]
	s_add_u32 s66, s28, 0xc0000
	s_addc_u32 s67, s29, 0
	s_mov_b32 m0, s47
	s_nop 0
	global_load_lds_dwordx4 v1, s[66:67]
	s_waitcnt vmcnt(8)
	s_waitcnt lgkmcnt(0)
	s_barrier
	s_setprio 1
	s_waitcnt lgkmcnt(7)
	v_mfma_i32_16x16x64_i8 v[126:129], v[140:143], v[172:175], v[126:129]
	v_mfma_i32_16x16x64_i8 v[118:121], v[148:151], v[172:175], v[118:121]
	s_waitcnt lgkmcnt(5)
	v_mfma_i32_16x16x64_i8 v[110:113], v[140:143], v[186:189], v[110:113]
	v_mfma_i32_16x16x64_i8 v[102:105], v[148:151], v[186:189], v[102:105]
	s_waitcnt lgkmcnt(3)
	v_mfma_i32_16x16x64_i8 v[94:97], v[140:143], v[194:197], v[94:97]
	v_mfma_i32_16x16x64_i8 v[86:89], v[148:151], v[194:197], v[86:89]
	s_waitcnt lgkmcnt(1)
	v_mfma_i32_16x16x64_i8 v[78:81], v[140:143], v[204:207], v[78:81]
	v_mfma_i32_16x16x64_i8 v[70:73], v[148:151], v[204:207], v[70:73]
	v_mfma_i32_16x16x64_i8 v[126:129], v[144:147], v[182:185], v[126:129]
	v_mfma_i32_16x16x64_i8 v[118:121], v[152:155], v[182:185], v[118:121]
	v_mfma_i32_16x16x64_i8 v[110:113], v[144:147], v[190:193], v[110:113]
	v_mfma_i32_16x16x64_i8 v[102:105], v[152:155], v[190:193], v[102:105]
	v_mfma_i32_16x16x64_i8 v[94:97], v[144:147], v[198:201], v[94:97]
	v_mfma_i32_16x16x64_i8 v[86:89], v[152:155], v[198:201], v[86:89]
	s_waitcnt lgkmcnt(0)
	v_mfma_i32_16x16x64_i8 v[78:81], v[144:147], v[208:211], v[78:81]
	v_mfma_i32_16x16x64_i8 v[70:73], v[152:155], v[208:211], v[70:73]
	s_setprio 0
	s_setprio 1
	v_mfma_i32_16x16x64_i8 v[122:125], v[156:159], v[172:175], v[122:125]
	v_mfma_i32_16x16x64_i8 v[114:117], v[164:167], v[172:175], v[114:117]
	v_mfma_i32_16x16x64_i8 v[106:109], v[156:159], v[186:189], v[106:109]
	v_mfma_i32_16x16x64_i8 v[98:101], v[164:167], v[186:189], v[98:101]
	v_mfma_i32_16x16x64_i8 v[90:93], v[156:159], v[194:197], v[90:93]
	v_mfma_i32_16x16x64_i8 v[82:85], v[164:167], v[194:197], v[82:85]
	v_mfma_i32_16x16x64_i8 v[74:77], v[156:159], v[204:207], v[74:77]
	v_mfma_i32_16x16x64_i8 v[66:69], v[164:167], v[204:207], v[66:69]
	v_mfma_i32_16x16x64_i8 v[122:125], v[160:163], v[182:185], v[122:125]
	v_mfma_i32_16x16x64_i8 v[114:117], v[168:171], v[182:185], v[114:117]
	v_mfma_i32_16x16x64_i8 v[106:109], v[160:163], v[190:193], v[106:109]
	v_mfma_i32_16x16x64_i8 v[98:101], v[168:171], v[190:193], v[98:101]
	s_add_u32 s66, s34, 0x80
	s_addc_u32 s67, s35, 0
	v_mfma_i32_16x16x64_i8 v[90:93], v[160:163], v[198:201], v[90:93]
	v_mfma_i32_16x16x64_i8 v[82:85], v[168:171], v[198:201], v[82:85]
	v_mfma_i32_16x16x64_i8 v[74:77], v[160:163], v[208:211], v[74:77]
	v_mfma_i32_16x16x64_i8 v[66:69], v[168:171], v[208:211], v[66:69]
	s_setprio 0
	s_barrier
; #define PG8_STAGE(bufoff, gbase, X) do { _Pragma("unroll") for (int _i = 0; _i < 2; ++_i) { \
;         const char* gp_ = (const char*)(gbase) + (_i ? rs##X : (size_t)0); const unsigned la_ = (unsigned)(size_t)(lds + (bufoff) + ldsw + _i * 8192); \
;         asm volatile("s_mov_b32 m0, %2\n\ts_nop 0\n\tglobal_load_lds_dwordx4 %0, %1" :: "v"(voff##X), "s"(gp_), "s"(la_) : "memory", "m0"); } } while (0)
; #define PG8_LDA(dst, b, h) do { _Pragma("unroll") for (int m = 0; m < 4; ++m) _Pragma("unroll") for (int k = 0; k < 2; ++k) dst[m][k] = *(const LAS bf16x8*)(lds + PG8_SA(b, h) + aoff + m * 2048 + k * 1024); } while (0)
; #define PG8_WAIT_V(n) asm volatile("s_waitcnt vmcnt(" #n ")" ::: "memory")
; #define PG8_WAIT_L(n) asm volatile("s_waitcnt lgkmcnt(" #n ")" ::: "memory")
; #define PG8_BAR __builtin_amdgcn_s_barrier()
; #define PG8_SCHED __builtin_amdgcn_sched_barrier(0)
; template <class Epi>
; __device__ __forceinline__ void gemm_phase(LAS unsigned char* lds, const Gemm g_in, const StaticOrder& S, const Epi& E) {
;     ...
;             PG8_WAIT_V(8); PG8_WAIT_L(0); PG8_BAR; PG8_MMA(0, 0, At, B0); PG8_MMA(0, 1, At, B1); PG8_BAR; PG8_SCHED;
;             PG8_LDA(At, 1, 1); PG8_STAGE(PG8_SB(1, 0), b3, B); PG8_STAGE(PG8_SB(1, 1), b3 + hsB, B); PG8_STAGE(PG8_SA(1, 0), a3, A);
;             PG8_WAIT_V(8); PG8_WAIT_L(0); PG8_BAR; PG8_MMA(1, 0, At, B0); PG8_MMA(1, 1, At, B1); PG8_BAR; PG8_SCHED;
;         }
	ds_read_b128 v[172:175], v138 offset:49152
	ds_read_b128 v[182:185], v138 offset:50176
	ds_read_b128 v[186:189], v138 offset:51200
	ds_read_b128 v[190:193], v138 offset:52224
	ds_read_b128 v[194:197], v138 offset:53248
	ds_read_b128 v[198:201], v138 offset:54272
	ds_read_b128 v[204:207], v138 offset:55296
	ds_read_b128 v[208:211], v138 offset:56320
	s_mov_b32 m0, s50
	s_nop 0
	global_load_lds_dwordx4 v134, s[66:67]
	s_add_u32 s66, s34, 0x40080
	s_addc_u32 s67, s35, 0
	s_mov_b32 m0, s51
	s_nop 0
	global_load_lds_dwordx4 v134, s[66:67]
	s_add_u32 s66, s34, 0x80080
	s_addc_u32 s67, s35, 0
	s_mov_b32 m0, s54
	s_nop 0
	global_load_lds_dwordx4 v134, s[66:67]
	s_add_u32 s34, s34, 0xc0080
	s_addc_u32 s35, s35, 0
	s_mov_b32 m0, s55
	s_nop 0
	global_load_lds_dwordx4 v134, s[34:35]
	s_add_u32 s28, s28, 0x40080
	s_mov_b32 m0, s52
	s_nop 0
	global_load_lds_dwordx4 v1, s[30:31]
	s_addc_u32 s29, s29, 0
	s_mov_b32 m0, s53
	s_nop 0
	global_load_lds_dwordx4 v1, s[28:29]
	s_waitcnt vmcnt(8)
	s_waitcnt lgkmcnt(0)
	s_barrier
	s_setprio 1
	s_waitcnt lgkmcnt(7)
	v_mfma_i32_16x16x64_i8 v[62:65], v[140:143], v[172:175], v[62:65]
	v_mfma_i32_16x16x64_i8 v[54:57], v[148:151], v[172:175], v[54:57]
	s_waitcnt lgkmcnt(5)
	v_mfma_i32_16x16x64_i8 v[46:49], v[140:143], v[186:189], v[46:49]
	v_mfma_i32_16x16x64_i8 v[38:41], v[148:151], v[186:189], v[38:41]
	s_waitcnt lgkmcnt(3)
	v_mfma_i32_16x16x64_i8 v[30:33], v[140:143], v[194:197], v[30:33]
	v_mfma_i32_16x16x64_i8 v[22:25], v[148:151], v[194:197], v[22:25]
	s_waitcnt lgkmcnt(1)
	v_mfma_i32_16x16x64_i8 v[14:17], v[140:143], v[204:207], v[14:17]
	v_mfma_i32_16x16x64_i8 v[6:9], v[148:151], v[204:207], v[6:9]
	v_mfma_i32_16x16x64_i8 v[62:65], v[144:147], v[182:185], v[62:65]
	v_mfma_i32_16x16x64_i8 v[54:57], v[152:155], v[182:185], v[54:57]
	v_mfma_i32_16x16x64_i8 v[46:49], v[144:147], v[190:193], v[46:49]
	v_mfma_i32_16x16x64_i8 v[38:41], v[152:155], v[190:193], v[38:41]
	v_mfma_i32_16x16x64_i8 v[30:33], v[144:147], v[198:201], v[30:33]
	v_mfma_i32_16x16x64_i8 v[22:25], v[152:155], v[198:201], v[22:25]
	s_waitcnt lgkmcnt(0)
	v_mfma_i32_16x16x64_i8 v[14:17], v[144:147], v[208:211], v[14:17]
	v_mfma_i32_16x16x64_i8 v[6:9], v[152:155], v[208:211], v[6:9]
	s_setprio 0
	s_setprio 1
	v_mfma_i32_16x16x64_i8 v[58:61], v[156:159], v[172:175], v[58:61]
	v_mfma_i32_16x16x64_i8 v[50:53], v[164:167], v[172:175], v[50:53]
	v_mfma_i32_16x16x64_i8 v[42:45], v[156:159], v[186:189], v[42:45]
	v_mfma_i32_16x16x64_i8 v[34:37], v[164:167], v[186:189], v[34:37]
	v_mfma_i32_16x16x64_i8 v[26:29], v[156:159], v[194:197], v[26:29]
	v_mfma_i32_16x16x64_i8 v[18:21], v[164:167], v[194:197], v[18:21]
	v_mfma_i32_16x16x64_i8 v[10:13], v[156:159], v[204:207], v[10:13]
	v_mfma_i32_16x16x64_i8 v[2:5], v[164:167], v[204:207], v[2:5]
	v_mfma_i32_16x16x64_i8 v[58:61], v[160:163], v[182:185], v[58:61]
	v_mfma_i32_16x16x64_i8 v[50:53], v[168:171], v[182:185], v[50:53]
	v_mfma_i32_16x16x64_i8 v[42:45], v[160:163], v[190:193], v[42:45]
	v_mfma_i32_16x16x64_i8 v[34:37], v[168:171], v[190:193], v[34:37]
	s_add_u32 s62, s62, 0x100
	s_addc_u32 s63, s63, 0
	s_add_u32 s26, s26, 0x100
	s_addc_u32 s27, s27, 0
	s_cmp_ge_i32 s64, s37
	s_mov_b32 s28, s64
	v_mfma_i32_16x16x64_i8 v[26:29], v[160:163], v[198:201], v[26:29]
	v_mfma_i32_16x16x64_i8 v[18:21], v[168:171], v[198:201], v[18:21]
	v_mfma_i32_16x16x64_i8 v[10:13], v[160:163], v[208:211], v[10:13]
	v_mfma_i32_16x16x64_i8 v[2:5], v[168:171], v[208:211], v[2:5]
	s_setprio 0
	s_barrier
	s_cbranch_scc0 .LBB0_1510
	s_and_b64 vcc, exec, s[14:15]
	s_cbranch_vccz .LBB0_1513
